# v77: A/B - mid-segment s_setprio 0/1 flip pairs deleted in the GEMM MFMA segments (48 pairs)
# speedup vs baseline: 1.0023x; 1.0023x over previous
.LBB0_179:
	s_ashr_i32 s47, s46, 31
	s_lshl_b64 s[48:49], s[46:47], 19
	s_add_u32 s48, s26, s48
	s_addc_u32 s49, s27, s49
	s_and_b64 s[50:51], s[44:45], exec
	s_cselect_b32 s47, s49, s63
	s_cselect_b32 s82, s48, s62
	s_ashr_i32 s21, s20, 31
	s_lshl_b64 s[50:51], s[20:21], 19
	s_add_u32 s50, s59, s50
	s_addc_u32 s51, s66, s51
	s_and_b64 s[84:85], s[44:45], exec
	s_cselect_b32 s21, s51, s61
	s_cselect_b32 s83, s50, s60
	s_add_u32 s89, s60, 0x100
	s_addc_u32 s84, s61, 0
	s_add_u32 s60, s62, 0x40080
	s_addc_u32 s61, s63, 0
	s_mov_b32 s85, -2
	s_add_u32 s62, s60, 0xfffc0080
	s_addc_u32 s63, s61, -1
	s_cmp_eq_u32 s85, 12
	s_cselect_b32 vcc_hi, s47, s63
	s_cselect_b32 vcc_lo, s82, s62
	s_cselect_b32 s63, s21, s84
	s_cselect_b32 s62, s83, s89
	v_lshl_add_u64 v[142:143], s[60:61], 0, v[136:137]
	s_add_i32 m0, s68, 0xc000
	global_load_lds_dwordx4 v[142:143], off
	v_lshl_add_u64 v[142:143], s[60:61], 0, v[134:135]
	s_add_i32 m0, s68, 0xe000
	s_nop 0
	global_load_lds_dwordx4 v[142:143], off
	s_waitcnt vmcnt(8)
	s_waitcnt lgkmcnt(0)
	s_barrier
	s_setprio 1
	s_waitcnt lgkmcnt(0)
	v_mfma_f32_16x16x32_bf16 v[124:127], v[138:141], v[210:213], 0
	v_mfma_f32_16x16x32_bf16 v[116:119], v[176:179], v[210:213], 0
	v_mfma_f32_16x16x32_bf16 v[108:111], v[138:141], v[218:221], 0
	v_mfma_f32_16x16x32_bf16 v[100:103], v[176:179], v[218:221], 0
	v_mfma_f32_16x16x32_bf16 v[92:95], v[138:141], v[228:231], 0
	v_mfma_f32_16x16x32_bf16 v[84:87], v[176:179], v[228:231], 0
	v_mfma_f32_16x16x32_bf16 v[76:79], v[138:141], v[236:239], 0
	v_mfma_f32_16x16x32_bf16 v[68:71], v[176:179], v[236:239], 0
	v_mfma_f32_16x16x32_bf16 v[124:127], v[172:175], v[214:217], v[124:127]
	v_mfma_f32_16x16x32_bf16 v[116:119], v[180:183], v[214:217], v[116:119]
	v_mfma_f32_16x16x32_bf16 v[108:111], v[172:175], v[224:227], v[108:111]
	v_mfma_f32_16x16x32_bf16 v[100:103], v[180:183], v[224:227], v[100:103]
	v_mfma_f32_16x16x32_bf16 v[92:95], v[172:175], v[232:235], v[92:95]
	v_mfma_f32_16x16x32_bf16 v[84:87], v[180:183], v[232:235], v[84:87]
	v_mfma_f32_16x16x32_bf16 v[76:79], v[172:175], v[240:243], v[76:79]
	v_mfma_f32_16x16x32_bf16 v[68:71], v[180:183], v[240:243], v[68:71]
	v_mfma_f32_16x16x32_bf16 v[120:123], v[184:187], v[210:213], 0
	v_mfma_f32_16x16x32_bf16 v[112:115], v[192:195], v[210:213], 0
	v_mfma_f32_16x16x32_bf16 v[104:107], v[184:187], v[218:221], 0
	v_mfma_f32_16x16x32_bf16 v[96:99], v[192:195], v[218:221], 0
	v_mfma_f32_16x16x32_bf16 v[88:91], v[184:187], v[228:231], 0
	v_mfma_f32_16x16x32_bf16 v[80:83], v[192:195], v[228:231], 0
	v_mfma_f32_16x16x32_bf16 v[72:75], v[184:187], v[236:239], 0
	v_mfma_f32_16x16x32_bf16 v[64:67], v[192:195], v[236:239], 0
	v_mfma_f32_16x16x32_bf16 v[120:123], v[188:191], v[214:217], v[120:123]
	v_mfma_f32_16x16x32_bf16 v[112:115], v[196:199], v[214:217], v[112:115]
	v_mfma_f32_16x16x32_bf16 v[104:107], v[188:191], v[224:227], v[104:107]
	v_mfma_f32_16x16x32_bf16 v[96:99], v[196:199], v[224:227], v[96:99]
	v_mfma_f32_16x16x32_bf16 v[88:91], v[188:191], v[232:235], v[88:91]
	v_mfma_f32_16x16x32_bf16 v[80:83], v[196:199], v[232:235], v[80:83]
	v_mfma_f32_16x16x32_bf16 v[72:75], v[188:191], v[240:243], v[72:75]
	v_mfma_f32_16x16x32_bf16 v[64:67], v[196:199], v[240:243], v[64:67]
	s_setprio 0
	s_barrier
	s_add_i32 s86, s86, s67
	v_lshl_add_u64 v[142:143], s[62:63], 0, v[152:153]
	s_mov_b32 m0, s86
	ds_read_b128 v[210:213], v148 offset:16384
	ds_read_b128 v[214:217], v148 offset:17408
	ds_read_b128 v[218:221], v148 offset:18432
	ds_read_b128 v[224:227], v148 offset:19456
	ds_read_b128 v[228:231], v148 offset:20480
	ds_read_b128 v[232:235], v148 offset:21504
	ds_read_b128 v[236:239], v148 offset:22528
	ds_read_b128 v[240:243], v148 offset:23552
	global_load_lds_dwordx4 v[142:143], off
	s_add_i32 m0, s86, 0x2000
	s_add_u32 s86, s62, 0x40000
	v_lshl_add_u64 v[150:151], s[62:63], 0, v[128:129]
	s_addc_u32 s87, s63, 0
	s_add_i32 s92, s92, s67
	global_load_lds_dwordx4 v[150:151], off
	v_lshl_add_u64 v[244:245], s[86:87], 0, v[152:153]
	s_mov_b32 m0, s92
	v_lshl_add_u64 v[246:247], vcc, 0, v[130:131]
	global_load_lds_dwordx4 v[244:245], off
	v_lshl_add_u64 v[244:245], s[86:87], 0, v[128:129]
	s_add_i32 m0, s92, 0x2000
	s_nop 0
	global_load_lds_dwordx4 v[244:245], off
	v_lshl_add_u64 v[244:245], vcc, 0, v[132:133]
	s_mov_b32 m0, s68
	s_nop 0
	global_load_lds_dwordx4 v[244:245], off
	s_mov_b32 m0, s69
	s_nop 0
	global_load_lds_dwordx4 v[246:247], off
	s_waitcnt vmcnt(8)
	s_waitcnt lgkmcnt(0)
	s_barrier
	s_setprio 1
	s_waitcnt lgkmcnt(0)
	v_mfma_f32_16x16x32_bf16 v[60:63], v[138:141], v[210:213], 0
	v_mfma_f32_16x16x32_bf16 v[52:55], v[176:179], v[210:213], 0
	v_mfma_f32_16x16x32_bf16 v[44:47], v[138:141], v[218:221], 0
	v_mfma_f32_16x16x32_bf16 v[36:39], v[176:179], v[218:221], 0
	v_mfma_f32_16x16x32_bf16 v[28:31], v[138:141], v[228:231], 0
	v_mfma_f32_16x16x32_bf16 v[20:23], v[176:179], v[228:231], 0
	v_mfma_f32_16x16x32_bf16 v[12:15], v[138:141], v[236:239], 0
	v_mfma_f32_16x16x32_bf16 v[4:7], v[176:179], v[236:239], 0
	v_mfma_f32_16x16x32_bf16 v[60:63], v[172:175], v[214:217], v[60:63]
	v_mfma_f32_16x16x32_bf16 v[52:55], v[180:183], v[214:217], v[52:55]
	v_mfma_f32_16x16x32_bf16 v[44:47], v[172:175], v[224:227], v[44:47]
	v_mfma_f32_16x16x32_bf16 v[36:39], v[180:183], v[224:227], v[36:39]
	v_mfma_f32_16x16x32_bf16 v[28:31], v[172:175], v[232:235], v[28:31]
	v_mfma_f32_16x16x32_bf16 v[20:23], v[180:183], v[232:235], v[20:23]
	v_mfma_f32_16x16x32_bf16 v[12:15], v[172:175], v[240:243], v[12:15]
	v_mfma_f32_16x16x32_bf16 v[4:7], v[180:183], v[240:243], v[4:7]
	v_mfma_f32_16x16x32_bf16 v[56:59], v[184:187], v[210:213], 0
	v_mfma_f32_16x16x32_bf16 v[48:51], v[192:195], v[210:213], 0
	v_mfma_f32_16x16x32_bf16 v[40:43], v[184:187], v[218:221], 0
	v_mfma_f32_16x16x32_bf16 v[32:35], v[192:195], v[218:221], 0
	v_mfma_f32_16x16x32_bf16 v[24:27], v[184:187], v[228:231], 0
	v_mfma_f32_16x16x32_bf16 v[16:19], v[192:195], v[228:231], 0
	v_mfma_f32_16x16x32_bf16 v[8:11], v[184:187], v[236:239], 0
	v_mfma_f32_16x16x32_bf16 v[0:3], v[192:195], v[236:239], 0
	v_mfma_f32_16x16x32_bf16 v[56:59], v[188:191], v[214:217], v[56:59]
	v_mfma_f32_16x16x32_bf16 v[48:51], v[196:199], v[214:217], v[48:51]
	v_mfma_f32_16x16x32_bf16 v[40:43], v[188:191], v[224:227], v[40:43]
	v_mfma_f32_16x16x32_bf16 v[32:35], v[196:199], v[224:227], v[32:35]
	v_mfma_f32_16x16x32_bf16 v[24:27], v[188:191], v[232:235], v[24:27]
	v_mfma_f32_16x16x32_bf16 v[16:19], v[196:199], v[232:235], v[16:19]
	v_mfma_f32_16x16x32_bf16 v[8:11], v[188:191], v[240:243], v[8:11]
	v_mfma_f32_16x16x32_bf16 v[0:3], v[196:199], v[240:243], v[0:3]
	s_setprio 0
	s_barrier
	s_add_i32 s92, 0, 0x18000
	v_add_u32_e32 v149, s92, v145
	s_add_i32 s93, 0, 0x1c000
	ds_read_b128 v[138:141], v149
	ds_read_b128 v[172:175], v149 offset:1024
	ds_read_b128 v[176:179], v149 offset:2048
	ds_read_b128 v[180:183], v149 offset:3072
	v_add_u32_e32 v149, s93, v145
	ds_read_b128 v[184:187], v149
	ds_read_b128 v[188:191], v149 offset:1024
	ds_read_b128 v[192:195], v149 offset:2048
	ds_read_b128 v[196:199], v149 offset:3072
	s_add_u32 s86, vcc_lo, 0x40000
	s_addc_u32 s87, vcc_hi, 0
	s_mov_b32 m0, s74
	v_lshl_add_u64 v[248:249], s[86:87], 0, v[132:133]
	ds_read_b128 v[210:213], v148 offset:32768
	ds_read_b128 v[214:217], v148 offset:33792
	ds_read_b128 v[218:221], v148 offset:34816
	ds_read_b128 v[224:227], v148 offset:35840
	ds_read_b128 v[228:231], v148 offset:36864
	ds_read_b128 v[232:235], v148 offset:37888
	ds_read_b128 v[236:239], v148 offset:38912
	ds_read_b128 v[240:243], v148 offset:39936
	global_load_lds_dwordx4 v[248:249], off
	v_lshl_add_u64 v[248:249], s[86:87], 0, v[130:131]
	s_mov_b32 m0, s75
	s_nop 0
	global_load_lds_dwordx4 v[248:249], off
	s_waitcnt vmcnt(8)
	s_waitcnt lgkmcnt(0)
	s_barrier
	s_setprio 1
	s_waitcnt lgkmcnt(0)
	v_mfma_f32_16x16x32_bf16 v[124:127], v[138:141], v[210:213], v[124:127]
	v_mfma_f32_16x16x32_bf16 v[116:119], v[176:179], v[210:213], v[116:119]
	v_mfma_f32_16x16x32_bf16 v[108:111], v[138:141], v[218:221], v[108:111]
	v_mfma_f32_16x16x32_bf16 v[100:103], v[176:179], v[218:221], v[100:103]
	v_mfma_f32_16x16x32_bf16 v[92:95], v[138:141], v[228:231], v[92:95]
	v_mfma_f32_16x16x32_bf16 v[84:87], v[176:179], v[228:231], v[84:87]
	v_mfma_f32_16x16x32_bf16 v[76:79], v[138:141], v[236:239], v[76:79]
	v_mfma_f32_16x16x32_bf16 v[68:71], v[176:179], v[236:239], v[68:71]
	v_mfma_f32_16x16x32_bf16 v[124:127], v[172:175], v[214:217], v[124:127]
	v_mfma_f32_16x16x32_bf16 v[116:119], v[180:183], v[214:217], v[116:119]
	v_mfma_f32_16x16x32_bf16 v[108:111], v[172:175], v[224:227], v[108:111]
	v_mfma_f32_16x16x32_bf16 v[100:103], v[180:183], v[224:227], v[100:103]
	v_mfma_f32_16x16x32_bf16 v[92:95], v[172:175], v[232:235], v[92:95]
	v_mfma_f32_16x16x32_bf16 v[84:87], v[180:183], v[232:235], v[84:87]
	v_mfma_f32_16x16x32_bf16 v[76:79], v[172:175], v[240:243], v[76:79]
	v_mfma_f32_16x16x32_bf16 v[68:71], v[180:183], v[240:243], v[68:71]
	v_mfma_f32_16x16x32_bf16 v[120:123], v[184:187], v[210:213], v[120:123]
	v_mfma_f32_16x16x32_bf16 v[112:115], v[192:195], v[210:213], v[112:115]
	v_mfma_f32_16x16x32_bf16 v[104:107], v[184:187], v[218:221], v[104:107]
	v_mfma_f32_16x16x32_bf16 v[96:99], v[192:195], v[218:221], v[96:99]
	v_mfma_f32_16x16x32_bf16 v[88:91], v[184:187], v[228:231], v[88:91]
	v_mfma_f32_16x16x32_bf16 v[80:83], v[192:195], v[228:231], v[80:83]
	v_mfma_f32_16x16x32_bf16 v[72:75], v[184:187], v[236:239], v[72:75]
	v_mfma_f32_16x16x32_bf16 v[64:67], v[192:195], v[236:239], v[64:67]
	v_mfma_f32_16x16x32_bf16 v[120:123], v[188:191], v[214:217], v[120:123]
	v_mfma_f32_16x16x32_bf16 v[112:115], v[196:199], v[214:217], v[112:115]
	v_mfma_f32_16x16x32_bf16 v[104:107], v[188:191], v[224:227], v[104:107]
	v_mfma_f32_16x16x32_bf16 v[96:99], v[196:199], v[224:227], v[96:99]
	v_mfma_f32_16x16x32_bf16 v[88:91], v[188:191], v[232:235], v[88:91]
	v_mfma_f32_16x16x32_bf16 v[80:83], v[196:199], v[232:235], v[80:83]
	v_mfma_f32_16x16x32_bf16 v[72:75], v[188:191], v[240:243], v[72:75]
	v_mfma_f32_16x16x32_bf16 v[64:67], v[196:199], v[240:243], v[64:67]
	s_setprio 0
	s_barrier
	s_add_i32 s86, s92, s67
	v_lshl_add_u64 v[142:143], v[142:143], 0, s[22:23]
	s_mov_b32 m0, s86
	ds_read_b128 v[210:213], v148 offset:49152
	ds_read_b128 v[214:217], v148 offset:50176
	ds_read_b128 v[218:221], v148 offset:51200
	ds_read_b128 v[224:227], v148 offset:52224
	ds_read_b128 v[228:231], v148 offset:53248
	ds_read_b128 v[232:235], v148 offset:54272
	ds_read_b128 v[236:239], v148 offset:55296
	ds_read_b128 v[240:243], v148 offset:56320
	global_load_lds_dwordx4 v[142:143], off
	s_add_i32 m0, s86, 0x2000
	s_add_u32 s62, s62, 0x40080
	v_lshl_add_u64 v[142:143], v[150:151], 0, s[22:23]
	s_addc_u32 s63, s63, 0
	s_add_i32 s86, s93, s67
	global_load_lds_dwordx4 v[142:143], off
	v_lshl_add_u64 v[142:143], s[62:63], 0, v[152:153]
	s_mov_b32 m0, s86
	s_nop 0
	global_load_lds_dwordx4 v[142:143], off
	v_lshl_add_u64 v[142:143], s[62:63], 0, v[128:129]
	s_add_i32 m0, s86, 0x2000
	s_nop 0
	global_load_lds_dwordx4 v[142:143], off
	v_lshl_add_u64 v[142:143], v[244:245], 0, s[22:23]
	s_mov_b32 m0, s77
	s_nop 0
	global_load_lds_dwordx4 v[142:143], off
	v_lshl_add_u64 v[142:143], v[246:247], 0, s[22:23]
	s_mov_b32 m0, s78
	s_nop 0
	global_load_lds_dwordx4 v[142:143], off
	s_waitcnt vmcnt(8)
	s_waitcnt lgkmcnt(0)
	s_barrier
	s_setprio 1
	s_waitcnt lgkmcnt(0)
	v_mfma_f32_16x16x32_bf16 v[60:63], v[138:141], v[210:213], v[60:63]
	v_mfma_f32_16x16x32_bf16 v[52:55], v[176:179], v[210:213], v[52:55]
	v_mfma_f32_16x16x32_bf16 v[44:47], v[138:141], v[218:221], v[44:47]
	v_mfma_f32_16x16x32_bf16 v[36:39], v[176:179], v[218:221], v[36:39]
	v_mfma_f32_16x16x32_bf16 v[28:31], v[138:141], v[228:231], v[28:31]
	v_mfma_f32_16x16x32_bf16 v[20:23], v[176:179], v[228:231], v[20:23]
	v_mfma_f32_16x16x32_bf16 v[12:15], v[138:141], v[236:239], v[12:15]
	v_mfma_f32_16x16x32_bf16 v[4:7], v[176:179], v[236:239], v[4:7]
	v_mfma_f32_16x16x32_bf16 v[60:63], v[172:175], v[214:217], v[60:63]
	v_mfma_f32_16x16x32_bf16 v[52:55], v[180:183], v[214:217], v[52:55]
	v_mfma_f32_16x16x32_bf16 v[44:47], v[172:175], v[224:227], v[44:47]
	v_mfma_f32_16x16x32_bf16 v[36:39], v[180:183], v[224:227], v[36:39]
	v_mfma_f32_16x16x32_bf16 v[28:31], v[172:175], v[232:235], v[28:31]
	v_mfma_f32_16x16x32_bf16 v[20:23], v[180:183], v[232:235], v[20:23]
	v_mfma_f32_16x16x32_bf16 v[12:15], v[172:175], v[240:243], v[12:15]
	v_mfma_f32_16x16x32_bf16 v[4:7], v[180:183], v[240:243], v[4:7]
	v_mfma_f32_16x16x32_bf16 v[56:59], v[184:187], v[210:213], v[56:59]
	v_mfma_f32_16x16x32_bf16 v[48:51], v[192:195], v[210:213], v[48:51]
	v_mfma_f32_16x16x32_bf16 v[40:43], v[184:187], v[218:221], v[40:43]
	v_mfma_f32_16x16x32_bf16 v[32:35], v[192:195], v[218:221], v[32:35]
	v_mfma_f32_16x16x32_bf16 v[24:27], v[184:187], v[228:231], v[24:27]
	v_mfma_f32_16x16x32_bf16 v[16:19], v[192:195], v[228:231], v[16:19]
	v_mfma_f32_16x16x32_bf16 v[8:11], v[184:187], v[236:239], v[8:11]
	v_mfma_f32_16x16x32_bf16 v[0:3], v[192:195], v[236:239], v[0:3]
	v_mfma_f32_16x16x32_bf16 v[56:59], v[188:191], v[214:217], v[56:59]
	v_mfma_f32_16x16x32_bf16 v[48:51], v[196:199], v[214:217], v[48:51]
	v_mfma_f32_16x16x32_bf16 v[40:43], v[188:191], v[224:227], v[40:43]
	v_mfma_f32_16x16x32_bf16 v[32:35], v[196:199], v[224:227], v[32:35]
	v_mfma_f32_16x16x32_bf16 v[24:27], v[188:191], v[232:235], v[24:27]
	v_mfma_f32_16x16x32_bf16 v[16:19], v[196:199], v[232:235], v[16:19]
	v_mfma_f32_16x16x32_bf16 v[8:11], v[188:191], v[240:243], v[8:11]
	v_mfma_f32_16x16x32_bf16 v[0:3], v[196:199], v[240:243], v[0:3]
	s_setprio 0
	s_barrier
	s_add_i32 s85, s85, 2
	s_add_u32 s89, s89, 0x100
	s_addc_u32 s84, s84, 0
	s_add_u32 s60, s60, 0x100
	s_addc_u32 s61, s61, 0
	s_cmp_gt_u32 s85, 13
	.p2align	6
.LBB0_180:
	s_add_u32 s62, s60, 0xfffc0080
	s_addc_u32 s63, s61, -1
	s_add_i32 s86, 0, 0x10000
	s_cmp_eq_u32 s85, 12
	s_cselect_b32 vcc_hi, s47, s63
	s_cselect_b32 vcc_lo, s82, s62
	v_add_u32_e32 v142, s86, v145
	s_cselect_b32 s63, s21, s84
	s_cselect_b32 s62, s83, s89
	s_add_i32 s92, 0, 0x14000
	ds_read_b128 v[138:141], v142
	ds_read_b128 v[172:175], v142 offset:1024
	ds_read_b128 v[176:179], v142 offset:2048
	ds_read_b128 v[180:183], v142 offset:3072
	v_add_u32_e32 v142, s92, v145
	ds_read_b128 v[184:187], v142
	ds_read_b128 v[188:191], v142 offset:1024
	ds_read_b128 v[192:195], v142 offset:2048
	ds_read_b128 v[196:199], v142 offset:3072
	v_lshl_add_u64 v[142:143], s[60:61], 0, v[136:137]
	s_add_i32 m0, s68, 0xc000
	ds_read_b128 v[210:213], v148
	ds_read_b128 v[214:217], v148 offset:1024
	ds_read_b128 v[218:221], v148 offset:2048
	ds_read_b128 v[224:227], v148 offset:3072
	ds_read_b128 v[228:231], v148 offset:4096
	ds_read_b128 v[232:235], v148 offset:5120
	ds_read_b128 v[236:239], v148 offset:6144
	ds_read_b128 v[240:243], v148 offset:7168
	global_load_lds_dwordx4 v[142:143], off
	v_lshl_add_u64 v[142:143], s[60:61], 0, v[134:135]
	s_add_i32 m0, s68, 0xe000
	s_nop 0
	global_load_lds_dwordx4 v[142:143], off
	s_waitcnt vmcnt(8)
	s_waitcnt lgkmcnt(0)
	s_barrier
	s_setprio 1
	s_waitcnt lgkmcnt(0)
	v_mfma_f32_16x16x32_bf16 v[124:127], v[138:141], v[210:213], v[124:127]
	v_mfma_f32_16x16x32_bf16 v[116:119], v[176:179], v[210:213], v[116:119]
	v_mfma_f32_16x16x32_bf16 v[108:111], v[138:141], v[218:221], v[108:111]
	v_mfma_f32_16x16x32_bf16 v[100:103], v[176:179], v[218:221], v[100:103]
	v_mfma_f32_16x16x32_bf16 v[92:95], v[138:141], v[228:231], v[92:95]
	v_mfma_f32_16x16x32_bf16 v[84:87], v[176:179], v[228:231], v[84:87]
	v_mfma_f32_16x16x32_bf16 v[76:79], v[138:141], v[236:239], v[76:79]
	v_mfma_f32_16x16x32_bf16 v[68:71], v[176:179], v[236:239], v[68:71]
	v_mfma_f32_16x16x32_bf16 v[124:127], v[172:175], v[214:217], v[124:127]
	v_mfma_f32_16x16x32_bf16 v[116:119], v[180:183], v[214:217], v[116:119]
	v_mfma_f32_16x16x32_bf16 v[108:111], v[172:175], v[224:227], v[108:111]
	v_mfma_f32_16x16x32_bf16 v[100:103], v[180:183], v[224:227], v[100:103]
	v_mfma_f32_16x16x32_bf16 v[92:95], v[172:175], v[232:235], v[92:95]
	v_mfma_f32_16x16x32_bf16 v[84:87], v[180:183], v[232:235], v[84:87]
	v_mfma_f32_16x16x32_bf16 v[76:79], v[172:175], v[240:243], v[76:79]
	v_mfma_f32_16x16x32_bf16 v[68:71], v[180:183], v[240:243], v[68:71]
	v_mfma_f32_16x16x32_bf16 v[120:123], v[184:187], v[210:213], v[120:123]
	v_mfma_f32_16x16x32_bf16 v[112:115], v[192:195], v[210:213], v[112:115]
	v_mfma_f32_16x16x32_bf16 v[104:107], v[184:187], v[218:221], v[104:107]
	v_mfma_f32_16x16x32_bf16 v[96:99], v[192:195], v[218:221], v[96:99]
	v_mfma_f32_16x16x32_bf16 v[88:91], v[184:187], v[228:231], v[88:91]
	v_mfma_f32_16x16x32_bf16 v[80:83], v[192:195], v[228:231], v[80:83]
	v_mfma_f32_16x16x32_bf16 v[72:75], v[184:187], v[236:239], v[72:75]
	v_mfma_f32_16x16x32_bf16 v[64:67], v[192:195], v[236:239], v[64:67]
	v_mfma_f32_16x16x32_bf16 v[120:123], v[188:191], v[214:217], v[120:123]
	v_mfma_f32_16x16x32_bf16 v[112:115], v[196:199], v[214:217], v[112:115]
	v_mfma_f32_16x16x32_bf16 v[104:107], v[188:191], v[224:227], v[104:107]
	v_mfma_f32_16x16x32_bf16 v[96:99], v[196:199], v[224:227], v[96:99]
	v_mfma_f32_16x16x32_bf16 v[88:91], v[188:191], v[232:235], v[88:91]
	v_mfma_f32_16x16x32_bf16 v[80:83], v[196:199], v[232:235], v[80:83]
	v_mfma_f32_16x16x32_bf16 v[72:75], v[188:191], v[240:243], v[72:75]
	v_mfma_f32_16x16x32_bf16 v[64:67], v[196:199], v[240:243], v[64:67]
	s_setprio 0
	s_barrier
	s_add_i32 s86, s86, s67
	v_lshl_add_u64 v[142:143], s[62:63], 0, v[152:153]
	s_mov_b32 m0, s86
	ds_read_b128 v[210:213], v148 offset:16384
	ds_read_b128 v[214:217], v148 offset:17408
	ds_read_b128 v[218:221], v148 offset:18432
	ds_read_b128 v[224:227], v148 offset:19456
	ds_read_b128 v[228:231], v148 offset:20480
	ds_read_b128 v[232:235], v148 offset:21504
	ds_read_b128 v[236:239], v148 offset:22528
	ds_read_b128 v[240:243], v148 offset:23552
	global_load_lds_dwordx4 v[142:143], off
	s_add_i32 m0, s86, 0x2000
	s_add_u32 s86, s62, 0x40000
	v_lshl_add_u64 v[150:151], s[62:63], 0, v[128:129]
	s_addc_u32 s87, s63, 0
	s_add_i32 s92, s92, s67
	global_load_lds_dwordx4 v[150:151], off
	v_lshl_add_u64 v[244:245], s[86:87], 0, v[152:153]
	s_mov_b32 m0, s92
	v_lshl_add_u64 v[246:247], vcc, 0, v[130:131]
	global_load_lds_dwordx4 v[244:245], off
	v_lshl_add_u64 v[244:245], s[86:87], 0, v[128:129]
	s_add_i32 m0, s92, 0x2000
	s_nop 0
	global_load_lds_dwordx4 v[244:245], off
	v_lshl_add_u64 v[244:245], vcc, 0, v[132:133]
	s_mov_b32 m0, s68
	s_nop 0
	global_load_lds_dwordx4 v[244:245], off
	s_mov_b32 m0, s69
	s_nop 0
	global_load_lds_dwordx4 v[246:247], off
	s_waitcnt vmcnt(8)
	s_waitcnt lgkmcnt(0)
	s_barrier
	s_setprio 1
	s_waitcnt lgkmcnt(0)
	v_mfma_f32_16x16x32_bf16 v[60:63], v[138:141], v[210:213], v[60:63]
	v_mfma_f32_16x16x32_bf16 v[52:55], v[176:179], v[210:213], v[52:55]
	v_mfma_f32_16x16x32_bf16 v[44:47], v[138:141], v[218:221], v[44:47]
	v_mfma_f32_16x16x32_bf16 v[36:39], v[176:179], v[218:221], v[36:39]
	v_mfma_f32_16x16x32_bf16 v[28:31], v[138:141], v[228:231], v[28:31]
	v_mfma_f32_16x16x32_bf16 v[20:23], v[176:179], v[228:231], v[20:23]
	v_mfma_f32_16x16x32_bf16 v[12:15], v[138:141], v[236:239], v[12:15]
	v_mfma_f32_16x16x32_bf16 v[4:7], v[176:179], v[236:239], v[4:7]
	v_mfma_f32_16x16x32_bf16 v[60:63], v[172:175], v[214:217], v[60:63]
	v_mfma_f32_16x16x32_bf16 v[52:55], v[180:183], v[214:217], v[52:55]
	v_mfma_f32_16x16x32_bf16 v[44:47], v[172:175], v[224:227], v[44:47]
	v_mfma_f32_16x16x32_bf16 v[36:39], v[180:183], v[224:227], v[36:39]
	v_mfma_f32_16x16x32_bf16 v[28:31], v[172:175], v[232:235], v[28:31]
	v_mfma_f32_16x16x32_bf16 v[20:23], v[180:183], v[232:235], v[20:23]
	v_mfma_f32_16x16x32_bf16 v[12:15], v[172:175], v[240:243], v[12:15]
	v_mfma_f32_16x16x32_bf16 v[4:7], v[180:183], v[240:243], v[4:7]
	v_mfma_f32_16x16x32_bf16 v[56:59], v[184:187], v[210:213], v[56:59]
	v_mfma_f32_16x16x32_bf16 v[48:51], v[192:195], v[210:213], v[48:51]
	v_mfma_f32_16x16x32_bf16 v[40:43], v[184:187], v[218:221], v[40:43]
	v_mfma_f32_16x16x32_bf16 v[32:35], v[192:195], v[218:221], v[32:35]
	v_mfma_f32_16x16x32_bf16 v[24:27], v[184:187], v[228:231], v[24:27]
	v_mfma_f32_16x16x32_bf16 v[16:19], v[192:195], v[228:231], v[16:19]
	v_mfma_f32_16x16x32_bf16 v[8:11], v[184:187], v[236:239], v[8:11]
	v_mfma_f32_16x16x32_bf16 v[0:3], v[192:195], v[236:239], v[0:3]
	v_mfma_f32_16x16x32_bf16 v[56:59], v[188:191], v[214:217], v[56:59]
	v_mfma_f32_16x16x32_bf16 v[48:51], v[196:199], v[214:217], v[48:51]
	v_mfma_f32_16x16x32_bf16 v[40:43], v[188:191], v[224:227], v[40:43]
	v_mfma_f32_16x16x32_bf16 v[32:35], v[196:199], v[224:227], v[32:35]
	v_mfma_f32_16x16x32_bf16 v[24:27], v[188:191], v[232:235], v[24:27]
	v_mfma_f32_16x16x32_bf16 v[16:19], v[196:199], v[232:235], v[16:19]
	v_mfma_f32_16x16x32_bf16 v[8:11], v[188:191], v[240:243], v[8:11]
	v_mfma_f32_16x16x32_bf16 v[0:3], v[196:199], v[240:243], v[0:3]
	s_setprio 0
	s_barrier
	s_add_i32 s92, 0, 0x18000
	v_add_u32_e32 v149, s92, v145
	s_add_i32 s93, 0, 0x1c000
	ds_read_b128 v[138:141], v149
	ds_read_b128 v[172:175], v149 offset:1024
	ds_read_b128 v[176:179], v149 offset:2048
	ds_read_b128 v[180:183], v149 offset:3072
	v_add_u32_e32 v149, s93, v145
	ds_read_b128 v[184:187], v149
	ds_read_b128 v[188:191], v149 offset:1024
	ds_read_b128 v[192:195], v149 offset:2048
	ds_read_b128 v[196:199], v149 offset:3072
	s_add_u32 s86, vcc_lo, 0x40000
	s_addc_u32 s87, vcc_hi, 0
	s_mov_b32 m0, s74
	v_lshl_add_u64 v[248:249], s[86:87], 0, v[132:133]
	ds_read_b128 v[210:213], v148 offset:32768
	ds_read_b128 v[214:217], v148 offset:33792
	ds_read_b128 v[218:221], v148 offset:34816
	ds_read_b128 v[224:227], v148 offset:35840
	ds_read_b128 v[228:231], v148 offset:36864
	ds_read_b128 v[232:235], v148 offset:37888
	ds_read_b128 v[236:239], v148 offset:38912
	ds_read_b128 v[240:243], v148 offset:39936
	global_load_lds_dwordx4 v[248:249], off
	v_lshl_add_u64 v[248:249], s[86:87], 0, v[130:131]
	s_mov_b32 m0, s75
	s_nop 0
	global_load_lds_dwordx4 v[248:249], off
	s_waitcnt vmcnt(8)
	s_waitcnt lgkmcnt(0)
	s_barrier
	s_setprio 1
	s_waitcnt lgkmcnt(0)
	v_mfma_f32_16x16x32_bf16 v[124:127], v[138:141], v[210:213], v[124:127]
	v_mfma_f32_16x16x32_bf16 v[116:119], v[176:179], v[210:213], v[116:119]
	v_mfma_f32_16x16x32_bf16 v[108:111], v[138:141], v[218:221], v[108:111]
	v_mfma_f32_16x16x32_bf16 v[100:103], v[176:179], v[218:221], v[100:103]
	v_mfma_f32_16x16x32_bf16 v[92:95], v[138:141], v[228:231], v[92:95]
	v_mfma_f32_16x16x32_bf16 v[84:87], v[176:179], v[228:231], v[84:87]
	v_mfma_f32_16x16x32_bf16 v[76:79], v[138:141], v[236:239], v[76:79]
	v_mfma_f32_16x16x32_bf16 v[68:71], v[176:179], v[236:239], v[68:71]
	v_mfma_f32_16x16x32_bf16 v[124:127], v[172:175], v[214:217], v[124:127]
	v_mfma_f32_16x16x32_bf16 v[116:119], v[180:183], v[214:217], v[116:119]
	v_mfma_f32_16x16x32_bf16 v[108:111], v[172:175], v[224:227], v[108:111]
	v_mfma_f32_16x16x32_bf16 v[100:103], v[180:183], v[224:227], v[100:103]
	v_mfma_f32_16x16x32_bf16 v[92:95], v[172:175], v[232:235], v[92:95]
	v_mfma_f32_16x16x32_bf16 v[84:87], v[180:183], v[232:235], v[84:87]
	v_mfma_f32_16x16x32_bf16 v[76:79], v[172:175], v[240:243], v[76:79]
	v_mfma_f32_16x16x32_bf16 v[68:71], v[180:183], v[240:243], v[68:71]
	v_mfma_f32_16x16x32_bf16 v[120:123], v[184:187], v[210:213], v[120:123]
	v_mfma_f32_16x16x32_bf16 v[112:115], v[192:195], v[210:213], v[112:115]
	v_mfma_f32_16x16x32_bf16 v[104:107], v[184:187], v[218:221], v[104:107]
	v_mfma_f32_16x16x32_bf16 v[96:99], v[192:195], v[218:221], v[96:99]
	v_mfma_f32_16x16x32_bf16 v[88:91], v[184:187], v[228:231], v[88:91]
	v_mfma_f32_16x16x32_bf16 v[80:83], v[192:195], v[228:231], v[80:83]
	v_mfma_f32_16x16x32_bf16 v[72:75], v[184:187], v[236:239], v[72:75]
	v_mfma_f32_16x16x32_bf16 v[64:67], v[192:195], v[236:239], v[64:67]
	v_mfma_f32_16x16x32_bf16 v[120:123], v[188:191], v[214:217], v[120:123]
	v_mfma_f32_16x16x32_bf16 v[112:115], v[196:199], v[214:217], v[112:115]
	v_mfma_f32_16x16x32_bf16 v[104:107], v[188:191], v[224:227], v[104:107]
	v_mfma_f32_16x16x32_bf16 v[96:99], v[196:199], v[224:227], v[96:99]
	v_mfma_f32_16x16x32_bf16 v[88:91], v[188:191], v[232:235], v[88:91]
	v_mfma_f32_16x16x32_bf16 v[80:83], v[196:199], v[232:235], v[80:83]
	v_mfma_f32_16x16x32_bf16 v[72:75], v[188:191], v[240:243], v[72:75]
	v_mfma_f32_16x16x32_bf16 v[64:67], v[196:199], v[240:243], v[64:67]
	s_setprio 0
	s_barrier
	s_add_i32 s86, s92, s67
	v_lshl_add_u64 v[142:143], v[142:143], 0, s[22:23]
	s_mov_b32 m0, s86
	ds_read_b128 v[210:213], v148 offset:49152
	ds_read_b128 v[214:217], v148 offset:50176
	ds_read_b128 v[218:221], v148 offset:51200
	ds_read_b128 v[224:227], v148 offset:52224
	ds_read_b128 v[228:231], v148 offset:53248
	ds_read_b128 v[232:235], v148 offset:54272
	ds_read_b128 v[236:239], v148 offset:55296
	ds_read_b128 v[240:243], v148 offset:56320
	global_load_lds_dwordx4 v[142:143], off
	s_add_i32 m0, s86, 0x2000
	s_add_u32 s62, s62, 0x40080
	v_lshl_add_u64 v[142:143], v[150:151], 0, s[22:23]
	s_addc_u32 s63, s63, 0
	s_add_i32 s86, s93, s67
	global_load_lds_dwordx4 v[142:143], off
	v_lshl_add_u64 v[142:143], s[62:63], 0, v[152:153]
	s_mov_b32 m0, s86
	s_nop 0
	global_load_lds_dwordx4 v[142:143], off
	v_lshl_add_u64 v[142:143], s[62:63], 0, v[128:129]
	s_add_i32 m0, s86, 0x2000
	s_nop 0
	global_load_lds_dwordx4 v[142:143], off
	v_lshl_add_u64 v[142:143], v[244:245], 0, s[22:23]
	s_mov_b32 m0, s77
	s_nop 0
	global_load_lds_dwordx4 v[142:143], off
	v_lshl_add_u64 v[142:143], v[246:247], 0, s[22:23]
	s_mov_b32 m0, s78
	s_nop 0
	global_load_lds_dwordx4 v[142:143], off
	s_waitcnt vmcnt(8)
	s_waitcnt lgkmcnt(0)
	s_barrier
	s_setprio 1
	s_waitcnt lgkmcnt(0)
	v_mfma_f32_16x16x32_bf16 v[60:63], v[138:141], v[210:213], v[60:63]
	v_mfma_f32_16x16x32_bf16 v[52:55], v[176:179], v[210:213], v[52:55]
	v_mfma_f32_16x16x32_bf16 v[44:47], v[138:141], v[218:221], v[44:47]
	v_mfma_f32_16x16x32_bf16 v[36:39], v[176:179], v[218:221], v[36:39]
	v_mfma_f32_16x16x32_bf16 v[28:31], v[138:141], v[228:231], v[28:31]
	v_mfma_f32_16x16x32_bf16 v[20:23], v[176:179], v[228:231], v[20:23]
	v_mfma_f32_16x16x32_bf16 v[12:15], v[138:141], v[236:239], v[12:15]
	v_mfma_f32_16x16x32_bf16 v[4:7], v[176:179], v[236:239], v[4:7]
	v_mfma_f32_16x16x32_bf16 v[60:63], v[172:175], v[214:217], v[60:63]
	v_mfma_f32_16x16x32_bf16 v[52:55], v[180:183], v[214:217], v[52:55]
	v_mfma_f32_16x16x32_bf16 v[44:47], v[172:175], v[224:227], v[44:47]
	v_mfma_f32_16x16x32_bf16 v[36:39], v[180:183], v[224:227], v[36:39]
	v_mfma_f32_16x16x32_bf16 v[28:31], v[172:175], v[232:235], v[28:31]
	v_mfma_f32_16x16x32_bf16 v[20:23], v[180:183], v[232:235], v[20:23]
	v_mfma_f32_16x16x32_bf16 v[12:15], v[172:175], v[240:243], v[12:15]
	v_mfma_f32_16x16x32_bf16 v[4:7], v[180:183], v[240:243], v[4:7]
	v_mfma_f32_16x16x32_bf16 v[56:59], v[184:187], v[210:213], v[56:59]
	v_mfma_f32_16x16x32_bf16 v[48:51], v[192:195], v[210:213], v[48:51]
	v_mfma_f32_16x16x32_bf16 v[40:43], v[184:187], v[218:221], v[40:43]
	v_mfma_f32_16x16x32_bf16 v[32:35], v[192:195], v[218:221], v[32:35]
	v_mfma_f32_16x16x32_bf16 v[24:27], v[184:187], v[228:231], v[24:27]
	v_mfma_f32_16x16x32_bf16 v[16:19], v[192:195], v[228:231], v[16:19]
	v_mfma_f32_16x16x32_bf16 v[8:11], v[184:187], v[236:239], v[8:11]
	v_mfma_f32_16x16x32_bf16 v[0:3], v[192:195], v[236:239], v[0:3]
	v_mfma_f32_16x16x32_bf16 v[56:59], v[188:191], v[214:217], v[56:59]
	v_mfma_f32_16x16x32_bf16 v[48:51], v[196:199], v[214:217], v[48:51]
	v_mfma_f32_16x16x32_bf16 v[40:43], v[188:191], v[224:227], v[40:43]
	v_mfma_f32_16x16x32_bf16 v[32:35], v[196:199], v[224:227], v[32:35]
	v_mfma_f32_16x16x32_bf16 v[24:27], v[188:191], v[232:235], v[24:27]
	v_mfma_f32_16x16x32_bf16 v[16:19], v[196:199], v[232:235], v[16:19]
	v_mfma_f32_16x16x32_bf16 v[8:11], v[188:191], v[240:243], v[8:11]
	v_mfma_f32_16x16x32_bf16 v[0:3], v[196:199], v[240:243], v[0:3]
	s_setprio 0
	s_barrier
	s_add_i32 s85, s85, 2
	s_add_u32 s89, s89, 0x100
	s_addc_u32 s84, s84, 0
	s_add_u32 s60, s60, 0x100
	s_addc_u32 s61, s61, 0
	s_cmp_gt_u32 s85, 13
	s_cbranch_scc0 .LBB0_180
	s_and_b64 vcc, exec, s[18:19]
	s_cbranch_vccz .LBB0_183
	s_barrier

.LBB0_280:
	s_add_u32 s84, s18, 0x100
	s_addc_u32 s85, s19, 0
	s_mov_b32 s86, -2
	s_add_u32 vcc_lo, s60, 0x100
	s_addc_u32 vcc_hi, s61, 0
	s_cmp_eq_u32 s86, 40
	s_cselect_b32 s67, s51, vcc_hi
	s_cselect_b32 s66, s50, vcc_lo
	s_cselect_b32 s19, s45, s85
	s_cselect_b32 s18, s44, s84
	v_lshl_add_u64 v[198:199], s[60:61], 0, v[180:181]
	s_add_i32 m0, s69, 0xc000
	global_load_lds_dwordx4 v[198:199], off
	v_lshl_add_u64 v[198:199], s[60:61], 0, v[178:179]
	s_add_i32 m0, s69, 0xe000
	s_nop 0
	global_load_lds_dwordx4 v[198:199], off
	s_waitcnt vmcnt(8)
	s_waitcnt lgkmcnt(0)
	s_barrier
	s_setprio 1
	s_waitcnt lgkmcnt(0)
	v_mfma_f32_16x16x32_bf16 v[124:127], v[128:131], v[190:193], 0
	v_mfma_f32_16x16x32_bf16 v[120:123], v[136:139], v[190:193], 0
	v_mfma_f32_16x16x32_bf16 v[108:111], v[128:131], v[214:217], 0
	v_mfma_f32_16x16x32_bf16 v[104:107], v[136:139], v[214:217], 0
	v_mfma_f32_16x16x32_bf16 v[92:95], v[128:131], v[224:227], 0
	v_mfma_f32_16x16x32_bf16 v[88:91], v[136:139], v[224:227], 0
	v_mfma_f32_16x16x32_bf16 v[76:79], v[128:131], v[232:235], 0
	v_mfma_f32_16x16x32_bf16 v[72:75], v[136:139], v[232:235], 0
	v_mfma_f32_16x16x32_bf16 v[124:127], v[132:135], v[194:197], v[124:127]
	v_mfma_f32_16x16x32_bf16 v[120:123], v[140:143], v[194:197], v[120:123]
	v_mfma_f32_16x16x32_bf16 v[108:111], v[132:135], v[218:221], v[108:111]
	v_mfma_f32_16x16x32_bf16 v[104:107], v[140:143], v[218:221], v[104:107]
	v_mfma_f32_16x16x32_bf16 v[92:95], v[132:135], v[228:231], v[92:95]
	v_mfma_f32_16x16x32_bf16 v[88:91], v[140:143], v[228:231], v[88:91]
	v_mfma_f32_16x16x32_bf16 v[76:79], v[132:135], v[236:239], v[76:79]
	v_mfma_f32_16x16x32_bf16 v[72:75], v[140:143], v[236:239], v[72:75]
	v_mfma_f32_16x16x32_bf16 v[116:119], v[144:147], v[190:193], 0
	v_mfma_f32_16x16x32_bf16 v[112:115], v[182:185], v[190:193], 0
	v_mfma_f32_16x16x32_bf16 v[100:103], v[144:147], v[214:217], 0
	v_mfma_f32_16x16x32_bf16 v[96:99], v[182:185], v[214:217], 0
	v_mfma_f32_16x16x32_bf16 v[84:87], v[144:147], v[224:227], 0
	v_mfma_f32_16x16x32_bf16 v[80:83], v[182:185], v[224:227], 0
	v_mfma_f32_16x16x32_bf16 v[68:71], v[144:147], v[232:235], 0
	v_mfma_f32_16x16x32_bf16 v[64:67], v[182:185], v[232:235], 0
	v_mfma_f32_16x16x32_bf16 v[116:119], v[148:151], v[194:197], v[116:119]
	v_mfma_f32_16x16x32_bf16 v[112:115], v[186:189], v[194:197], v[112:115]
	v_mfma_f32_16x16x32_bf16 v[100:103], v[148:151], v[218:221], v[100:103]
	v_mfma_f32_16x16x32_bf16 v[96:99], v[186:189], v[218:221], v[96:99]
	v_mfma_f32_16x16x32_bf16 v[84:87], v[148:151], v[228:231], v[84:87]
	v_mfma_f32_16x16x32_bf16 v[80:83], v[186:189], v[228:231], v[80:83]
	v_mfma_f32_16x16x32_bf16 v[68:71], v[148:151], v[236:239], v[68:71]
	v_mfma_f32_16x16x32_bf16 v[64:67], v[186:189], v[236:239], v[64:67]
	s_setprio 0
	s_barrier
	s_add_i32 s60, s87, s68
	v_lshl_add_u64 v[198:199], s[18:19], 0, v[152:153]
	s_mov_b32 m0, s60
	ds_read_b128 v[190:193], v212 offset:16384
	ds_read_b128 v[194:197], v212 offset:17408
	ds_read_b128 v[214:217], v212 offset:18432
	ds_read_b128 v[218:221], v212 offset:19456
	ds_read_b128 v[224:227], v212 offset:20480
	ds_read_b128 v[228:231], v212 offset:21504
	ds_read_b128 v[232:235], v212 offset:22528
	ds_read_b128 v[236:239], v212 offset:23552
	global_load_lds_dwordx4 v[198:199], off
	s_add_i32 m0, s60, 0x2000
	s_add_u32 s60, s18, 0xb0000
	v_lshl_add_u64 v[240:241], s[18:19], 0, v[172:173]
	s_addc_u32 s61, s19, 0
	s_add_i32 s87, s92, s68
	global_load_lds_dwordx4 v[240:241], off
	v_lshl_add_u64 v[242:243], s[60:61], 0, v[152:153]
	s_mov_b32 m0, s87
	v_lshl_add_u64 v[244:245], s[66:67], 0, v[174:175]
	global_load_lds_dwordx4 v[242:243], off
	v_lshl_add_u64 v[242:243], s[60:61], 0, v[172:173]
	s_add_i32 m0, s87, 0x2000
	s_nop 0
	global_load_lds_dwordx4 v[242:243], off
	v_lshl_add_u64 v[242:243], s[66:67], 0, v[176:177]
	s_mov_b32 m0, s69
	s_nop 0
	global_load_lds_dwordx4 v[242:243], off
	s_mov_b32 m0, s74
	s_nop 0
	global_load_lds_dwordx4 v[244:245], off
	s_waitcnt vmcnt(8)
	s_waitcnt lgkmcnt(0)
	s_barrier
	s_setprio 1
	s_waitcnt lgkmcnt(0)
	v_mfma_f32_16x16x32_bf16 v[60:63], v[128:131], v[190:193], 0
	v_mfma_f32_16x16x32_bf16 v[56:59], v[136:139], v[190:193], 0
	v_mfma_f32_16x16x32_bf16 v[44:47], v[128:131], v[214:217], 0
	v_mfma_f32_16x16x32_bf16 v[40:43], v[136:139], v[214:217], 0
	v_mfma_f32_16x16x32_bf16 v[28:31], v[128:131], v[224:227], 0
	v_mfma_f32_16x16x32_bf16 v[24:27], v[136:139], v[224:227], 0
	v_mfma_f32_16x16x32_bf16 v[12:15], v[128:131], v[232:235], 0
	v_mfma_f32_16x16x32_bf16 v[8:11], v[136:139], v[232:235], 0
	v_mfma_f32_16x16x32_bf16 v[60:63], v[132:135], v[194:197], v[60:63]
	v_mfma_f32_16x16x32_bf16 v[56:59], v[140:143], v[194:197], v[56:59]
	v_mfma_f32_16x16x32_bf16 v[44:47], v[132:135], v[218:221], v[44:47]
	v_mfma_f32_16x16x32_bf16 v[40:43], v[140:143], v[218:221], v[40:43]
	v_mfma_f32_16x16x32_bf16 v[28:31], v[132:135], v[228:231], v[28:31]
	v_mfma_f32_16x16x32_bf16 v[24:27], v[140:143], v[228:231], v[24:27]
	v_mfma_f32_16x16x32_bf16 v[12:15], v[132:135], v[236:239], v[12:15]
	v_mfma_f32_16x16x32_bf16 v[8:11], v[140:143], v[236:239], v[8:11]
	v_mfma_f32_16x16x32_bf16 v[52:55], v[144:147], v[190:193], 0
	v_mfma_f32_16x16x32_bf16 v[48:51], v[182:185], v[190:193], 0
	v_mfma_f32_16x16x32_bf16 v[36:39], v[144:147], v[214:217], 0
	v_mfma_f32_16x16x32_bf16 v[32:35], v[182:185], v[214:217], 0
	v_mfma_f32_16x16x32_bf16 v[20:23], v[144:147], v[224:227], 0
	v_mfma_f32_16x16x32_bf16 v[16:19], v[182:185], v[224:227], 0
	v_mfma_f32_16x16x32_bf16 v[4:7], v[144:147], v[232:235], 0
	v_mfma_f32_16x16x32_bf16 v[0:3], v[182:185], v[232:235], 0
	v_mfma_f32_16x16x32_bf16 v[52:55], v[148:151], v[194:197], v[52:55]
	v_mfma_f32_16x16x32_bf16 v[48:51], v[186:189], v[194:197], v[48:51]
	v_mfma_f32_16x16x32_bf16 v[36:39], v[148:151], v[218:221], v[36:39]
	v_mfma_f32_16x16x32_bf16 v[32:35], v[186:189], v[218:221], v[32:35]
	v_mfma_f32_16x16x32_bf16 v[20:23], v[148:151], v[228:231], v[20:23]
	v_mfma_f32_16x16x32_bf16 v[16:19], v[186:189], v[228:231], v[16:19]
	v_mfma_f32_16x16x32_bf16 v[4:7], v[148:151], v[236:239], v[4:7]
	v_mfma_f32_16x16x32_bf16 v[0:3], v[186:189], v[236:239], v[0:3]
	s_setprio 0
	s_barrier
	s_add_i32 s87, 0, 0x18000
	s_add_i32 s92, 0, 0x1c000
	v_add_u32_e32 v140, s87, v210
	v_add_u32_e32 v186, s92, v210
	ds_read_b128 v[128:131], v140
	ds_read_b128 v[132:135], v140 offset:1024
	ds_read_b128 v[136:139], v140 offset:2048
	ds_read_b128 v[140:143], v140 offset:3072
	ds_read_b128 v[144:147], v186
	ds_read_b128 v[148:151], v186 offset:1024
	ds_read_b128 v[182:185], v186 offset:2048
	ds_read_b128 v[186:189], v186 offset:3072
	s_add_u32 s60, s66, 0xb0000
	s_addc_u32 s61, s67, 0
	s_mov_b32 m0, s75
	v_lshl_add_u64 v[246:247], s[60:61], 0, v[176:177]
	ds_read_b128 v[190:193], v212 offset:32768
	ds_read_b128 v[194:197], v212 offset:33792
	ds_read_b128 v[214:217], v212 offset:34816
	ds_read_b128 v[218:221], v212 offset:35840
	ds_read_b128 v[224:227], v212 offset:36864
	ds_read_b128 v[228:231], v212 offset:37888
	ds_read_b128 v[232:235], v212 offset:38912
	ds_read_b128 v[236:239], v212 offset:39936
	global_load_lds_dwordx4 v[246:247], off
	v_lshl_add_u64 v[246:247], s[60:61], 0, v[174:175]
	s_mov_b32 m0, s76
	s_nop 0
	global_load_lds_dwordx4 v[246:247], off
	s_waitcnt vmcnt(8)
	s_waitcnt lgkmcnt(0)
	s_barrier
	s_setprio 1
	s_waitcnt lgkmcnt(0)
	v_mfma_f32_16x16x32_bf16 v[124:127], v[128:131], v[190:193], v[124:127]
	v_mfma_f32_16x16x32_bf16 v[120:123], v[136:139], v[190:193], v[120:123]
	v_mfma_f32_16x16x32_bf16 v[108:111], v[128:131], v[214:217], v[108:111]
	v_mfma_f32_16x16x32_bf16 v[104:107], v[136:139], v[214:217], v[104:107]
	v_mfma_f32_16x16x32_bf16 v[92:95], v[128:131], v[224:227], v[92:95]
	v_mfma_f32_16x16x32_bf16 v[88:91], v[136:139], v[224:227], v[88:91]
	v_mfma_f32_16x16x32_bf16 v[76:79], v[128:131], v[232:235], v[76:79]
	v_mfma_f32_16x16x32_bf16 v[72:75], v[136:139], v[232:235], v[72:75]
	v_mfma_f32_16x16x32_bf16 v[124:127], v[132:135], v[194:197], v[124:127]
	v_mfma_f32_16x16x32_bf16 v[120:123], v[140:143], v[194:197], v[120:123]
	v_mfma_f32_16x16x32_bf16 v[108:111], v[132:135], v[218:221], v[108:111]
	v_mfma_f32_16x16x32_bf16 v[104:107], v[140:143], v[218:221], v[104:107]
	v_mfma_f32_16x16x32_bf16 v[92:95], v[132:135], v[228:231], v[92:95]
	v_mfma_f32_16x16x32_bf16 v[88:91], v[140:143], v[228:231], v[88:91]
	v_mfma_f32_16x16x32_bf16 v[76:79], v[132:135], v[236:239], v[76:79]
	v_mfma_f32_16x16x32_bf16 v[72:75], v[140:143], v[236:239], v[72:75]
	v_mfma_f32_16x16x32_bf16 v[116:119], v[144:147], v[190:193], v[116:119]
	v_mfma_f32_16x16x32_bf16 v[112:115], v[182:185], v[190:193], v[112:115]
	v_mfma_f32_16x16x32_bf16 v[100:103], v[144:147], v[214:217], v[100:103]
	v_mfma_f32_16x16x32_bf16 v[96:99], v[182:185], v[214:217], v[96:99]
	v_mfma_f32_16x16x32_bf16 v[84:87], v[144:147], v[224:227], v[84:87]
	v_mfma_f32_16x16x32_bf16 v[80:83], v[182:185], v[224:227], v[80:83]
	v_mfma_f32_16x16x32_bf16 v[68:71], v[144:147], v[232:235], v[68:71]
	v_mfma_f32_16x16x32_bf16 v[64:67], v[182:185], v[232:235], v[64:67]
	v_mfma_f32_16x16x32_bf16 v[116:119], v[148:151], v[194:197], v[116:119]
	v_mfma_f32_16x16x32_bf16 v[112:115], v[186:189], v[194:197], v[112:115]
	v_mfma_f32_16x16x32_bf16 v[100:103], v[148:151], v[218:221], v[100:103]
	v_mfma_f32_16x16x32_bf16 v[96:99], v[186:189], v[218:221], v[96:99]
	v_mfma_f32_16x16x32_bf16 v[84:87], v[148:151], v[228:231], v[84:87]
	v_mfma_f32_16x16x32_bf16 v[80:83], v[186:189], v[228:231], v[80:83]
	v_mfma_f32_16x16x32_bf16 v[68:71], v[148:151], v[236:239], v[68:71]
	v_mfma_f32_16x16x32_bf16 v[64:67], v[186:189], v[236:239], v[64:67]
	s_setprio 0
	s_barrier
	s_add_i32 s60, s87, s68
	v_lshl_add_u64 v[198:199], v[198:199], 0, s[22:23]
	s_mov_b32 m0, s60
	ds_read_b128 v[190:193], v212 offset:49152
	ds_read_b128 v[194:197], v212 offset:50176
	ds_read_b128 v[214:217], v212 offset:51200
	ds_read_b128 v[218:221], v212 offset:52224
	ds_read_b128 v[224:227], v212 offset:53248
	ds_read_b128 v[228:231], v212 offset:54272
	ds_read_b128 v[232:235], v212 offset:55296
	ds_read_b128 v[236:239], v212 offset:56320
	global_load_lds_dwordx4 v[198:199], off
	s_add_i32 m0, s60, 0x2000
	s_add_u32 s18, s18, 0xb0080
	v_lshl_add_u64 v[198:199], v[240:241], 0, s[22:23]
	s_addc_u32 s19, s19, 0
	s_add_i32 s60, s92, s68
	global_load_lds_dwordx4 v[198:199], off
	v_lshl_add_u64 v[198:199], s[18:19], 0, v[152:153]
	s_mov_b32 m0, s60
	s_nop 0
	global_load_lds_dwordx4 v[198:199], off
	v_lshl_add_u64 v[198:199], s[18:19], 0, v[172:173]
	s_add_i32 m0, s60, 0x2000
	s_nop 0
	global_load_lds_dwordx4 v[198:199], off
	v_lshl_add_u64 v[198:199], v[242:243], 0, s[22:23]
	s_mov_b32 m0, s79
	s_nop 0
	global_load_lds_dwordx4 v[198:199], off
	v_lshl_add_u64 v[198:199], v[244:245], 0, s[22:23]
	s_mov_b32 m0, s80
	s_nop 0
	global_load_lds_dwordx4 v[198:199], off
	s_waitcnt vmcnt(8)
	s_waitcnt lgkmcnt(0)
	s_barrier
	s_setprio 1
	s_waitcnt lgkmcnt(0)
	v_mfma_f32_16x16x32_bf16 v[60:63], v[128:131], v[190:193], v[60:63]
	v_mfma_f32_16x16x32_bf16 v[56:59], v[136:139], v[190:193], v[56:59]
	v_mfma_f32_16x16x32_bf16 v[44:47], v[128:131], v[214:217], v[44:47]
	v_mfma_f32_16x16x32_bf16 v[40:43], v[136:139], v[214:217], v[40:43]
	v_mfma_f32_16x16x32_bf16 v[28:31], v[128:131], v[224:227], v[28:31]
	v_mfma_f32_16x16x32_bf16 v[24:27], v[136:139], v[224:227], v[24:27]
	v_mfma_f32_16x16x32_bf16 v[12:15], v[128:131], v[232:235], v[12:15]
	v_mfma_f32_16x16x32_bf16 v[8:11], v[136:139], v[232:235], v[8:11]
	v_mfma_f32_16x16x32_bf16 v[60:63], v[132:135], v[194:197], v[60:63]
	v_mfma_f32_16x16x32_bf16 v[56:59], v[140:143], v[194:197], v[56:59]
	v_mfma_f32_16x16x32_bf16 v[44:47], v[132:135], v[218:221], v[44:47]
	v_mfma_f32_16x16x32_bf16 v[40:43], v[140:143], v[218:221], v[40:43]
	v_mfma_f32_16x16x32_bf16 v[28:31], v[132:135], v[228:231], v[28:31]
	v_mfma_f32_16x16x32_bf16 v[24:27], v[140:143], v[228:231], v[24:27]
	v_mfma_f32_16x16x32_bf16 v[12:15], v[132:135], v[236:239], v[12:15]
	v_mfma_f32_16x16x32_bf16 v[8:11], v[140:143], v[236:239], v[8:11]
	v_mfma_f32_16x16x32_bf16 v[52:55], v[144:147], v[190:193], v[52:55]
	v_mfma_f32_16x16x32_bf16 v[48:51], v[182:185], v[190:193], v[48:51]
	v_mfma_f32_16x16x32_bf16 v[36:39], v[144:147], v[214:217], v[36:39]
	v_mfma_f32_16x16x32_bf16 v[32:35], v[182:185], v[214:217], v[32:35]
	v_mfma_f32_16x16x32_bf16 v[20:23], v[144:147], v[224:227], v[20:23]
	v_mfma_f32_16x16x32_bf16 v[16:19], v[182:185], v[224:227], v[16:19]
	v_mfma_f32_16x16x32_bf16 v[4:7], v[144:147], v[232:235], v[4:7]
	v_mfma_f32_16x16x32_bf16 v[0:3], v[182:185], v[232:235], v[0:3]
	v_mfma_f32_16x16x32_bf16 v[52:55], v[148:151], v[194:197], v[52:55]
	v_mfma_f32_16x16x32_bf16 v[48:51], v[186:189], v[194:197], v[48:51]
	v_mfma_f32_16x16x32_bf16 v[36:39], v[148:151], v[218:221], v[36:39]
	v_mfma_f32_16x16x32_bf16 v[32:35], v[186:189], v[218:221], v[32:35]
	v_mfma_f32_16x16x32_bf16 v[20:23], v[148:151], v[228:231], v[20:23]
	v_mfma_f32_16x16x32_bf16 v[16:19], v[186:189], v[228:231], v[16:19]
	v_mfma_f32_16x16x32_bf16 v[4:7], v[148:151], v[236:239], v[4:7]
	v_mfma_f32_16x16x32_bf16 v[0:3], v[186:189], v[236:239], v[0:3]
	s_setprio 0
	s_barrier
	s_add_i32 s86, s86, 2
	s_add_u32 s84, s84, 0x100
	s_addc_u32 s85, s85, 0
	s_cmp_gt_u32 s86, 41
	s_mov_b64 s[60:61], vcc
	.p2align	6
.LBB0_281:
	s_add_u32 vcc_lo, s60, 0x100
	s_addc_u32 vcc_hi, s61, 0
	s_add_i32 s87, 0, 0x10000
	s_cmp_eq_u32 s86, 40
	s_cselect_b32 s67, s51, vcc_hi
	s_cselect_b32 s66, s50, vcc_lo
	s_cselect_b32 s19, s45, s85
	s_cselect_b32 s18, s44, s84
	s_add_i32 s92, 0, 0x14000
	v_add_u32_e32 v140, s87, v210
	v_add_u32_e32 v186, s92, v210
	ds_read_b128 v[128:131], v140
	ds_read_b128 v[132:135], v140 offset:1024
	ds_read_b128 v[136:139], v140 offset:2048
	ds_read_b128 v[140:143], v140 offset:3072
	ds_read_b128 v[144:147], v186
	ds_read_b128 v[148:151], v186 offset:1024
	ds_read_b128 v[182:185], v186 offset:2048
	ds_read_b128 v[186:189], v186 offset:3072
	v_lshl_add_u64 v[198:199], s[60:61], 0, v[180:181]
	s_add_i32 m0, s69, 0xc000
	ds_read_b128 v[190:193], v212
	ds_read_b128 v[194:197], v212 offset:1024
	ds_read_b128 v[214:217], v212 offset:2048
	ds_read_b128 v[218:221], v212 offset:3072
	ds_read_b128 v[224:227], v212 offset:4096
	ds_read_b128 v[228:231], v212 offset:5120
	ds_read_b128 v[232:235], v212 offset:6144
	ds_read_b128 v[236:239], v212 offset:7168
	global_load_lds_dwordx4 v[198:199], off
	v_lshl_add_u64 v[198:199], s[60:61], 0, v[178:179]
	s_add_i32 m0, s69, 0xe000
	s_nop 0
	global_load_lds_dwordx4 v[198:199], off
	s_waitcnt vmcnt(8)
	s_waitcnt lgkmcnt(0)
	s_barrier
	s_setprio 1
	s_waitcnt lgkmcnt(0)
	v_mfma_f32_16x16x32_bf16 v[124:127], v[128:131], v[190:193], v[124:127]
	v_mfma_f32_16x16x32_bf16 v[120:123], v[136:139], v[190:193], v[120:123]
	v_mfma_f32_16x16x32_bf16 v[108:111], v[128:131], v[214:217], v[108:111]
	v_mfma_f32_16x16x32_bf16 v[104:107], v[136:139], v[214:217], v[104:107]
	v_mfma_f32_16x16x32_bf16 v[92:95], v[128:131], v[224:227], v[92:95]
	v_mfma_f32_16x16x32_bf16 v[88:91], v[136:139], v[224:227], v[88:91]
	v_mfma_f32_16x16x32_bf16 v[76:79], v[128:131], v[232:235], v[76:79]
	v_mfma_f32_16x16x32_bf16 v[72:75], v[136:139], v[232:235], v[72:75]
	v_mfma_f32_16x16x32_bf16 v[124:127], v[132:135], v[194:197], v[124:127]
	v_mfma_f32_16x16x32_bf16 v[120:123], v[140:143], v[194:197], v[120:123]
	v_mfma_f32_16x16x32_bf16 v[108:111], v[132:135], v[218:221], v[108:111]
	v_mfma_f32_16x16x32_bf16 v[104:107], v[140:143], v[218:221], v[104:107]
	v_mfma_f32_16x16x32_bf16 v[92:95], v[132:135], v[228:231], v[92:95]
	v_mfma_f32_16x16x32_bf16 v[88:91], v[140:143], v[228:231], v[88:91]
	v_mfma_f32_16x16x32_bf16 v[76:79], v[132:135], v[236:239], v[76:79]
	v_mfma_f32_16x16x32_bf16 v[72:75], v[140:143], v[236:239], v[72:75]
	v_mfma_f32_16x16x32_bf16 v[116:119], v[144:147], v[190:193], v[116:119]
	v_mfma_f32_16x16x32_bf16 v[112:115], v[182:185], v[190:193], v[112:115]
	v_mfma_f32_16x16x32_bf16 v[100:103], v[144:147], v[214:217], v[100:103]
	v_mfma_f32_16x16x32_bf16 v[96:99], v[182:185], v[214:217], v[96:99]
	v_mfma_f32_16x16x32_bf16 v[84:87], v[144:147], v[224:227], v[84:87]
	v_mfma_f32_16x16x32_bf16 v[80:83], v[182:185], v[224:227], v[80:83]
	v_mfma_f32_16x16x32_bf16 v[68:71], v[144:147], v[232:235], v[68:71]
	v_mfma_f32_16x16x32_bf16 v[64:67], v[182:185], v[232:235], v[64:67]
	v_mfma_f32_16x16x32_bf16 v[116:119], v[148:151], v[194:197], v[116:119]
	v_mfma_f32_16x16x32_bf16 v[112:115], v[186:189], v[194:197], v[112:115]
	v_mfma_f32_16x16x32_bf16 v[100:103], v[148:151], v[218:221], v[100:103]
	v_mfma_f32_16x16x32_bf16 v[96:99], v[186:189], v[218:221], v[96:99]
	v_mfma_f32_16x16x32_bf16 v[84:87], v[148:151], v[228:231], v[84:87]
	v_mfma_f32_16x16x32_bf16 v[80:83], v[186:189], v[228:231], v[80:83]
	v_mfma_f32_16x16x32_bf16 v[68:71], v[148:151], v[236:239], v[68:71]
	v_mfma_f32_16x16x32_bf16 v[64:67], v[186:189], v[236:239], v[64:67]
	s_setprio 0
	s_barrier
	s_add_i32 s60, s87, s68
	v_lshl_add_u64 v[198:199], s[18:19], 0, v[152:153]
	s_mov_b32 m0, s60
	ds_read_b128 v[190:193], v212 offset:16384
	ds_read_b128 v[194:197], v212 offset:17408
	ds_read_b128 v[214:217], v212 offset:18432
	ds_read_b128 v[218:221], v212 offset:19456
	ds_read_b128 v[224:227], v212 offset:20480
	ds_read_b128 v[228:231], v212 offset:21504
	ds_read_b128 v[232:235], v212 offset:22528
	ds_read_b128 v[236:239], v212 offset:23552
	global_load_lds_dwordx4 v[198:199], off
	s_add_i32 m0, s60, 0x2000
	s_add_u32 s60, s18, 0xb0000
	v_lshl_add_u64 v[240:241], s[18:19], 0, v[172:173]
	s_addc_u32 s61, s19, 0
	s_add_i32 s87, s92, s68
	global_load_lds_dwordx4 v[240:241], off
	v_lshl_add_u64 v[242:243], s[60:61], 0, v[152:153]
	s_mov_b32 m0, s87
	v_lshl_add_u64 v[244:245], s[66:67], 0, v[174:175]
	global_load_lds_dwordx4 v[242:243], off
	v_lshl_add_u64 v[242:243], s[60:61], 0, v[172:173]
	s_add_i32 m0, s87, 0x2000
	s_nop 0
	global_load_lds_dwordx4 v[242:243], off
	v_lshl_add_u64 v[242:243], s[66:67], 0, v[176:177]
	s_mov_b32 m0, s69
	s_nop 0
	global_load_lds_dwordx4 v[242:243], off
	s_mov_b32 m0, s74
	s_nop 0
	global_load_lds_dwordx4 v[244:245], off
	s_waitcnt vmcnt(8)
	s_waitcnt lgkmcnt(0)
	s_barrier
	s_setprio 1
	s_waitcnt lgkmcnt(0)
	v_mfma_f32_16x16x32_bf16 v[60:63], v[128:131], v[190:193], v[60:63]
	v_mfma_f32_16x16x32_bf16 v[56:59], v[136:139], v[190:193], v[56:59]
	v_mfma_f32_16x16x32_bf16 v[44:47], v[128:131], v[214:217], v[44:47]
	v_mfma_f32_16x16x32_bf16 v[40:43], v[136:139], v[214:217], v[40:43]
	v_mfma_f32_16x16x32_bf16 v[28:31], v[128:131], v[224:227], v[28:31]
	v_mfma_f32_16x16x32_bf16 v[24:27], v[136:139], v[224:227], v[24:27]
	v_mfma_f32_16x16x32_bf16 v[12:15], v[128:131], v[232:235], v[12:15]
	v_mfma_f32_16x16x32_bf16 v[8:11], v[136:139], v[232:235], v[8:11]
	v_mfma_f32_16x16x32_bf16 v[60:63], v[132:135], v[194:197], v[60:63]
	v_mfma_f32_16x16x32_bf16 v[56:59], v[140:143], v[194:197], v[56:59]
	v_mfma_f32_16x16x32_bf16 v[44:47], v[132:135], v[218:221], v[44:47]
	v_mfma_f32_16x16x32_bf16 v[40:43], v[140:143], v[218:221], v[40:43]
	v_mfma_f32_16x16x32_bf16 v[28:31], v[132:135], v[228:231], v[28:31]
	v_mfma_f32_16x16x32_bf16 v[24:27], v[140:143], v[228:231], v[24:27]
	v_mfma_f32_16x16x32_bf16 v[12:15], v[132:135], v[236:239], v[12:15]
	v_mfma_f32_16x16x32_bf16 v[8:11], v[140:143], v[236:239], v[8:11]
	v_mfma_f32_16x16x32_bf16 v[52:55], v[144:147], v[190:193], v[52:55]
	v_mfma_f32_16x16x32_bf16 v[48:51], v[182:185], v[190:193], v[48:51]
	v_mfma_f32_16x16x32_bf16 v[36:39], v[144:147], v[214:217], v[36:39]
	v_mfma_f32_16x16x32_bf16 v[32:35], v[182:185], v[214:217], v[32:35]
	v_mfma_f32_16x16x32_bf16 v[20:23], v[144:147], v[224:227], v[20:23]
	v_mfma_f32_16x16x32_bf16 v[16:19], v[182:185], v[224:227], v[16:19]
	v_mfma_f32_16x16x32_bf16 v[4:7], v[144:147], v[232:235], v[4:7]
	v_mfma_f32_16x16x32_bf16 v[0:3], v[182:185], v[232:235], v[0:3]
	v_mfma_f32_16x16x32_bf16 v[52:55], v[148:151], v[194:197], v[52:55]
	v_mfma_f32_16x16x32_bf16 v[48:51], v[186:189], v[194:197], v[48:51]
	v_mfma_f32_16x16x32_bf16 v[36:39], v[148:151], v[218:221], v[36:39]
	v_mfma_f32_16x16x32_bf16 v[32:35], v[186:189], v[218:221], v[32:35]
	v_mfma_f32_16x16x32_bf16 v[20:23], v[148:151], v[228:231], v[20:23]
	v_mfma_f32_16x16x32_bf16 v[16:19], v[186:189], v[228:231], v[16:19]
	v_mfma_f32_16x16x32_bf16 v[4:7], v[148:151], v[236:239], v[4:7]
	v_mfma_f32_16x16x32_bf16 v[0:3], v[186:189], v[236:239], v[0:3]
	s_setprio 0
	s_barrier
	s_add_i32 s87, 0, 0x18000
	s_add_i32 s92, 0, 0x1c000
	v_add_u32_e32 v140, s87, v210
	v_add_u32_e32 v186, s92, v210
	ds_read_b128 v[128:131], v140
	ds_read_b128 v[132:135], v140 offset:1024
	ds_read_b128 v[136:139], v140 offset:2048
	ds_read_b128 v[140:143], v140 offset:3072
	ds_read_b128 v[144:147], v186
	ds_read_b128 v[148:151], v186 offset:1024
	ds_read_b128 v[182:185], v186 offset:2048
	ds_read_b128 v[186:189], v186 offset:3072
	s_add_u32 s60, s66, 0xb0000
	s_addc_u32 s61, s67, 0
	s_mov_b32 m0, s75
	v_lshl_add_u64 v[246:247], s[60:61], 0, v[176:177]
	ds_read_b128 v[190:193], v212 offset:32768
	ds_read_b128 v[194:197], v212 offset:33792
	ds_read_b128 v[214:217], v212 offset:34816
	ds_read_b128 v[218:221], v212 offset:35840
	ds_read_b128 v[224:227], v212 offset:36864
	ds_read_b128 v[228:231], v212 offset:37888
	ds_read_b128 v[232:235], v212 offset:38912
	ds_read_b128 v[236:239], v212 offset:39936
	global_load_lds_dwordx4 v[246:247], off
	v_lshl_add_u64 v[246:247], s[60:61], 0, v[174:175]
	s_mov_b32 m0, s76
	s_nop 0
	global_load_lds_dwordx4 v[246:247], off
	s_waitcnt vmcnt(8)
	s_waitcnt lgkmcnt(0)
	s_barrier
	s_setprio 1
	s_waitcnt lgkmcnt(0)
	v_mfma_f32_16x16x32_bf16 v[124:127], v[128:131], v[190:193], v[124:127]
	v_mfma_f32_16x16x32_bf16 v[120:123], v[136:139], v[190:193], v[120:123]
	v_mfma_f32_16x16x32_bf16 v[108:111], v[128:131], v[214:217], v[108:111]
	v_mfma_f32_16x16x32_bf16 v[104:107], v[136:139], v[214:217], v[104:107]
	v_mfma_f32_16x16x32_bf16 v[92:95], v[128:131], v[224:227], v[92:95]
	v_mfma_f32_16x16x32_bf16 v[88:91], v[136:139], v[224:227], v[88:91]
	v_mfma_f32_16x16x32_bf16 v[76:79], v[128:131], v[232:235], v[76:79]
	v_mfma_f32_16x16x32_bf16 v[72:75], v[136:139], v[232:235], v[72:75]
	v_mfma_f32_16x16x32_bf16 v[124:127], v[132:135], v[194:197], v[124:127]
	v_mfma_f32_16x16x32_bf16 v[120:123], v[140:143], v[194:197], v[120:123]
	v_mfma_f32_16x16x32_bf16 v[108:111], v[132:135], v[218:221], v[108:111]
	v_mfma_f32_16x16x32_bf16 v[104:107], v[140:143], v[218:221], v[104:107]
	v_mfma_f32_16x16x32_bf16 v[92:95], v[132:135], v[228:231], v[92:95]
	v_mfma_f32_16x16x32_bf16 v[88:91], v[140:143], v[228:231], v[88:91]
	v_mfma_f32_16x16x32_bf16 v[76:79], v[132:135], v[236:239], v[76:79]
	v_mfma_f32_16x16x32_bf16 v[72:75], v[140:143], v[236:239], v[72:75]
	v_mfma_f32_16x16x32_bf16 v[116:119], v[144:147], v[190:193], v[116:119]
	v_mfma_f32_16x16x32_bf16 v[112:115], v[182:185], v[190:193], v[112:115]
	v_mfma_f32_16x16x32_bf16 v[100:103], v[144:147], v[214:217], v[100:103]
	v_mfma_f32_16x16x32_bf16 v[96:99], v[182:185], v[214:217], v[96:99]
	v_mfma_f32_16x16x32_bf16 v[84:87], v[144:147], v[224:227], v[84:87]
	v_mfma_f32_16x16x32_bf16 v[80:83], v[182:185], v[224:227], v[80:83]
	v_mfma_f32_16x16x32_bf16 v[68:71], v[144:147], v[232:235], v[68:71]
	v_mfma_f32_16x16x32_bf16 v[64:67], v[182:185], v[232:235], v[64:67]
	v_mfma_f32_16x16x32_bf16 v[116:119], v[148:151], v[194:197], v[116:119]
	v_mfma_f32_16x16x32_bf16 v[112:115], v[186:189], v[194:197], v[112:115]
	v_mfma_f32_16x16x32_bf16 v[100:103], v[148:151], v[218:221], v[100:103]
	v_mfma_f32_16x16x32_bf16 v[96:99], v[186:189], v[218:221], v[96:99]
	v_mfma_f32_16x16x32_bf16 v[84:87], v[148:151], v[228:231], v[84:87]
	v_mfma_f32_16x16x32_bf16 v[80:83], v[186:189], v[228:231], v[80:83]
	v_mfma_f32_16x16x32_bf16 v[68:71], v[148:151], v[236:239], v[68:71]
	v_mfma_f32_16x16x32_bf16 v[64:67], v[186:189], v[236:239], v[64:67]
	s_setprio 0
	s_barrier
	s_add_i32 s60, s87, s68
	v_lshl_add_u64 v[198:199], v[198:199], 0, s[22:23]
	s_mov_b32 m0, s60
	ds_read_b128 v[190:193], v212 offset:49152
	ds_read_b128 v[194:197], v212 offset:50176
	ds_read_b128 v[214:217], v212 offset:51200
	ds_read_b128 v[218:221], v212 offset:52224
	ds_read_b128 v[224:227], v212 offset:53248
	ds_read_b128 v[228:231], v212 offset:54272
	ds_read_b128 v[232:235], v212 offset:55296
	ds_read_b128 v[236:239], v212 offset:56320
	global_load_lds_dwordx4 v[198:199], off
	s_add_i32 m0, s60, 0x2000
	s_add_u32 s18, s18, 0xb0080
	v_lshl_add_u64 v[198:199], v[240:241], 0, s[22:23]
	s_addc_u32 s19, s19, 0
	s_add_i32 s60, s92, s68
	global_load_lds_dwordx4 v[198:199], off
	v_lshl_add_u64 v[198:199], s[18:19], 0, v[152:153]
	s_mov_b32 m0, s60
	s_nop 0
	global_load_lds_dwordx4 v[198:199], off
	v_lshl_add_u64 v[198:199], s[18:19], 0, v[172:173]
	s_add_i32 m0, s60, 0x2000
	s_nop 0
	global_load_lds_dwordx4 v[198:199], off
	v_lshl_add_u64 v[198:199], v[242:243], 0, s[22:23]
	s_mov_b32 m0, s79
	s_nop 0
	global_load_lds_dwordx4 v[198:199], off
	v_lshl_add_u64 v[198:199], v[244:245], 0, s[22:23]
	s_mov_b32 m0, s80
	s_nop 0
	global_load_lds_dwordx4 v[198:199], off
	s_waitcnt vmcnt(8)
	s_waitcnt lgkmcnt(0)
	s_barrier
	s_setprio 1
	s_waitcnt lgkmcnt(0)
	v_mfma_f32_16x16x32_bf16 v[60:63], v[128:131], v[190:193], v[60:63]
	v_mfma_f32_16x16x32_bf16 v[56:59], v[136:139], v[190:193], v[56:59]
	v_mfma_f32_16x16x32_bf16 v[44:47], v[128:131], v[214:217], v[44:47]
	v_mfma_f32_16x16x32_bf16 v[40:43], v[136:139], v[214:217], v[40:43]
	v_mfma_f32_16x16x32_bf16 v[28:31], v[128:131], v[224:227], v[28:31]
	v_mfma_f32_16x16x32_bf16 v[24:27], v[136:139], v[224:227], v[24:27]
	v_mfma_f32_16x16x32_bf16 v[12:15], v[128:131], v[232:235], v[12:15]
	v_mfma_f32_16x16x32_bf16 v[8:11], v[136:139], v[232:235], v[8:11]
	v_mfma_f32_16x16x32_bf16 v[60:63], v[132:135], v[194:197], v[60:63]
	v_mfma_f32_16x16x32_bf16 v[56:59], v[140:143], v[194:197], v[56:59]
	v_mfma_f32_16x16x32_bf16 v[44:47], v[132:135], v[218:221], v[44:47]
	v_mfma_f32_16x16x32_bf16 v[40:43], v[140:143], v[218:221], v[40:43]
	v_mfma_f32_16x16x32_bf16 v[28:31], v[132:135], v[228:231], v[28:31]
	v_mfma_f32_16x16x32_bf16 v[24:27], v[140:143], v[228:231], v[24:27]
	v_mfma_f32_16x16x32_bf16 v[12:15], v[132:135], v[236:239], v[12:15]
	v_mfma_f32_16x16x32_bf16 v[8:11], v[140:143], v[236:239], v[8:11]
	v_mfma_f32_16x16x32_bf16 v[52:55], v[144:147], v[190:193], v[52:55]
	v_mfma_f32_16x16x32_bf16 v[48:51], v[182:185], v[190:193], v[48:51]
	v_mfma_f32_16x16x32_bf16 v[36:39], v[144:147], v[214:217], v[36:39]
	v_mfma_f32_16x16x32_bf16 v[32:35], v[182:185], v[214:217], v[32:35]
	v_mfma_f32_16x16x32_bf16 v[20:23], v[144:147], v[224:227], v[20:23]
	v_mfma_f32_16x16x32_bf16 v[16:19], v[182:185], v[224:227], v[16:19]
	v_mfma_f32_16x16x32_bf16 v[4:7], v[144:147], v[232:235], v[4:7]
	v_mfma_f32_16x16x32_bf16 v[0:3], v[182:185], v[232:235], v[0:3]
	v_mfma_f32_16x16x32_bf16 v[52:55], v[148:151], v[194:197], v[52:55]
	v_mfma_f32_16x16x32_bf16 v[48:51], v[186:189], v[194:197], v[48:51]
	v_mfma_f32_16x16x32_bf16 v[36:39], v[148:151], v[218:221], v[36:39]
	v_mfma_f32_16x16x32_bf16 v[32:35], v[186:189], v[218:221], v[32:35]
	v_mfma_f32_16x16x32_bf16 v[20:23], v[148:151], v[228:231], v[20:23]
	v_mfma_f32_16x16x32_bf16 v[16:19], v[186:189], v[228:231], v[16:19]
	v_mfma_f32_16x16x32_bf16 v[4:7], v[148:151], v[236:239], v[4:7]
	v_mfma_f32_16x16x32_bf16 v[0:3], v[186:189], v[236:239], v[0:3]
	s_setprio 0
	s_barrier
	s_add_i32 s86, s86, 2
	s_add_u32 s84, s84, 0x100
	s_addc_u32 s85, s85, 0
	s_cmp_gt_u32 s86, 41
	s_mov_b64 s[60:61], vcc
	s_cbranch_scc0 .LBB0_281
	s_and_b64 vcc, exec, s[10:11]
	s_cbranch_vccz .LBB0_284
	s_barrier

.LBB0_418:
	s_ashr_i32 s21, s20, 31
	s_lshl_b64 s[50:51], s[20:21], 19
	s_add_u32 s50, s26, s50
	s_addc_u32 s51, s27, s51
	s_and_b64 s[60:61], s[46:47], exec
	s_cselect_b32 s21, s51, s45
	s_cselect_b32 s78, s50, s44
	s_ashr_i32 s19, s18, 31
	s_lshl_b64 s[60:61], s[18:19], 19
	v_readlane_b32 s19, v254, 42
	s_add_u32 s60, s19, s60
	v_readlane_b32 s19, v254, 43
	s_addc_u32 s61, s19, s61
	s_and_b64 s[62:63], s[46:47], exec
	s_cselect_b32 s19, s61, s49
	s_cselect_b32 s79, s60, s48
	s_add_u32 s80, s48, 0x100
	s_addc_u32 s81, s49, 0
	s_add_u32 s48, s44, 0x40080
	s_addc_u32 s49, s45, 0
	s_mov_b32 s82, -2
	s_add_u32 s44, s48, 0xfffc0080
	s_addc_u32 s45, s49, -1
	s_cmp_eq_u32 s82, 12
	s_cselect_b32 s63, s21, s45
	s_cselect_b32 s62, s78, s44
	s_cselect_b32 s45, s19, s81
	s_cselect_b32 s44, s79, s80
	v_lshl_add_u64 v[182:183], s[48:49], 0, v[172:173]
	s_add_i32 m0, s59, 0xc000
	global_load_lds_dwordx4 v[182:183], off
	v_lshl_add_u64 v[182:183], s[48:49], 0, v[150:151]
	s_add_i32 m0, s59, 0xe000
	s_nop 0
	global_load_lds_dwordx4 v[182:183], off
	s_waitcnt vmcnt(8)
	s_waitcnt lgkmcnt(0)
	s_barrier
	s_setprio 1
	s_waitcnt lgkmcnt(0)
	v_mfma_f32_16x16x32_bf16 v[140:143], v[72:75], v[210:213], 0
	v_mfma_f32_16x16x32_bf16 v[136:139], v[80:83], v[210:213], 0
	v_mfma_f32_16x16x32_bf16 v[124:127], v[72:75], v[218:221], 0
	v_mfma_f32_16x16x32_bf16 v[120:123], v[80:83], v[218:221], 0
	v_mfma_f32_16x16x32_bf16 v[108:111], v[72:75], v[228:231], 0
	v_mfma_f32_16x16x32_bf16 v[104:107], v[80:83], v[228:231], 0
	v_mfma_f32_16x16x32_bf16 v[92:95], v[72:75], v[236:239], 0
	v_mfma_f32_16x16x32_bf16 v[84:87], v[80:83], v[236:239], 0
	v_mfma_f32_16x16x32_bf16 v[140:143], v[76:79], v[214:217], v[140:143]
	v_mfma_f32_16x16x32_bf16 v[136:139], v[88:91], v[214:217], v[136:139]
	v_mfma_f32_16x16x32_bf16 v[124:127], v[76:79], v[224:227], v[124:127]
	v_mfma_f32_16x16x32_bf16 v[120:123], v[88:91], v[224:227], v[120:123]
	v_mfma_f32_16x16x32_bf16 v[108:111], v[76:79], v[232:235], v[108:111]
	v_mfma_f32_16x16x32_bf16 v[104:107], v[88:91], v[232:235], v[104:107]
	v_mfma_f32_16x16x32_bf16 v[92:95], v[76:79], v[240:243], v[92:95]
	v_mfma_f32_16x16x32_bf16 v[84:87], v[88:91], v[240:243], v[84:87]
	v_mfma_f32_16x16x32_bf16 v[132:135], v[174:177], v[210:213], 0
	v_mfma_f32_16x16x32_bf16 v[128:131], v[190:193], v[210:213], 0
	v_mfma_f32_16x16x32_bf16 v[116:119], v[174:177], v[218:221], 0
	v_mfma_f32_16x16x32_bf16 v[112:115], v[190:193], v[218:221], 0
	v_mfma_f32_16x16x32_bf16 v[100:103], v[174:177], v[228:231], 0
	v_mfma_f32_16x16x32_bf16 v[96:99], v[190:193], v[228:231], 0
	v_mfma_f32_16x16x32_bf16 v[68:71], v[174:177], v[236:239], 0
	v_mfma_f32_16x16x32_bf16 v[64:67], v[190:193], v[236:239], 0
	v_mfma_f32_16x16x32_bf16 v[132:135], v[178:181], v[214:217], v[132:135]
	v_mfma_f32_16x16x32_bf16 v[128:131], v[194:197], v[214:217], v[128:131]
	v_mfma_f32_16x16x32_bf16 v[116:119], v[178:181], v[224:227], v[116:119]
	v_mfma_f32_16x16x32_bf16 v[112:115], v[194:197], v[224:227], v[112:115]
	v_mfma_f32_16x16x32_bf16 v[100:103], v[178:181], v[232:235], v[100:103]
	v_mfma_f32_16x16x32_bf16 v[96:99], v[194:197], v[232:235], v[96:99]
	v_mfma_f32_16x16x32_bf16 v[68:71], v[178:181], v[240:243], v[68:71]
	v_mfma_f32_16x16x32_bf16 v[64:67], v[194:197], v[240:243], v[64:67]
	s_setprio 0
	s_barrier
	s_add_i32 s83, s83, s8
	v_lshl_add_u64 v[182:183], s[44:45], 0, v[152:153]
	s_mov_b32 m0, s83
	ds_read_b128 v[210:213], v188 offset:16384
	ds_read_b128 v[214:217], v188 offset:17408
	ds_read_b128 v[218:221], v188 offset:18432
	ds_read_b128 v[224:227], v188 offset:19456
	ds_read_b128 v[228:231], v188 offset:20480
	ds_read_b128 v[232:235], v188 offset:21504
	ds_read_b128 v[236:239], v188 offset:22528
	ds_read_b128 v[240:243], v188 offset:23552
	global_load_lds_dwordx4 v[182:183], off
	s_add_i32 m0, s83, 0x2000
	s_add_u32 s84, s44, 0x40000
	v_lshl_add_u64 v[198:199], s[44:45], 0, v[144:145]
	s_addc_u32 s85, s45, 0
	s_add_i32 s83, s86, s8
	global_load_lds_dwordx4 v[198:199], off
	v_lshl_add_u64 v[244:245], s[84:85], 0, v[152:153]
	s_mov_b32 m0, s83
	v_lshl_add_u64 v[246:247], s[62:63], 0, v[146:147]
	global_load_lds_dwordx4 v[244:245], off
	v_lshl_add_u64 v[244:245], s[84:85], 0, v[144:145]
	s_add_i32 m0, s83, 0x2000
	s_nop 0
	global_load_lds_dwordx4 v[244:245], off
	v_lshl_add_u64 v[244:245], s[62:63], 0, v[148:149]
	s_mov_b32 m0, s59
	s_nop 0
	global_load_lds_dwordx4 v[244:245], off
	s_mov_b32 m0, s66
	s_nop 0
	global_load_lds_dwordx4 v[246:247], off
	s_waitcnt vmcnt(8)
	s_waitcnt lgkmcnt(0)
	s_barrier
	s_setprio 1
	s_waitcnt lgkmcnt(0)
	v_mfma_f32_16x16x32_bf16 v[60:63], v[72:75], v[210:213], 0
	v_mfma_f32_16x16x32_bf16 v[56:59], v[80:83], v[210:213], 0
	v_mfma_f32_16x16x32_bf16 v[44:47], v[72:75], v[218:221], 0
	v_mfma_f32_16x16x32_bf16 v[40:43], v[80:83], v[218:221], 0
	v_mfma_f32_16x16x32_bf16 v[28:31], v[72:75], v[228:231], 0
	v_mfma_f32_16x16x32_bf16 v[24:27], v[80:83], v[228:231], 0
	v_mfma_f32_16x16x32_bf16 v[12:15], v[72:75], v[236:239], 0
	v_mfma_f32_16x16x32_bf16 v[8:11], v[80:83], v[236:239], 0
	v_mfma_f32_16x16x32_bf16 v[60:63], v[76:79], v[214:217], v[60:63]
	v_mfma_f32_16x16x32_bf16 v[56:59], v[88:91], v[214:217], v[56:59]
	v_mfma_f32_16x16x32_bf16 v[44:47], v[76:79], v[224:227], v[44:47]
	v_mfma_f32_16x16x32_bf16 v[40:43], v[88:91], v[224:227], v[40:43]
	v_mfma_f32_16x16x32_bf16 v[28:31], v[76:79], v[232:235], v[28:31]
	v_mfma_f32_16x16x32_bf16 v[24:27], v[88:91], v[232:235], v[24:27]
	v_mfma_f32_16x16x32_bf16 v[12:15], v[76:79], v[240:243], v[12:15]
	v_mfma_f32_16x16x32_bf16 v[8:11], v[88:91], v[240:243], v[8:11]
	v_mfma_f32_16x16x32_bf16 v[52:55], v[174:177], v[210:213], 0
	v_mfma_f32_16x16x32_bf16 v[48:51], v[190:193], v[210:213], 0
	v_mfma_f32_16x16x32_bf16 v[36:39], v[174:177], v[218:221], 0
	v_mfma_f32_16x16x32_bf16 v[32:35], v[190:193], v[218:221], 0
	v_mfma_f32_16x16x32_bf16 v[20:23], v[174:177], v[228:231], 0
	v_mfma_f32_16x16x32_bf16 v[16:19], v[190:193], v[228:231], 0
	v_mfma_f32_16x16x32_bf16 v[4:7], v[174:177], v[236:239], 0
	v_mfma_f32_16x16x32_bf16 v[0:3], v[190:193], v[236:239], 0
	v_mfma_f32_16x16x32_bf16 v[52:55], v[178:181], v[214:217], v[52:55]
	v_mfma_f32_16x16x32_bf16 v[48:51], v[194:197], v[214:217], v[48:51]
	v_mfma_f32_16x16x32_bf16 v[36:39], v[178:181], v[224:227], v[36:39]
	v_mfma_f32_16x16x32_bf16 v[32:35], v[194:197], v[224:227], v[32:35]
	v_mfma_f32_16x16x32_bf16 v[20:23], v[178:181], v[232:235], v[20:23]
	v_mfma_f32_16x16x32_bf16 v[16:19], v[194:197], v[232:235], v[16:19]
	v_mfma_f32_16x16x32_bf16 v[4:7], v[178:181], v[240:243], v[4:7]
	v_mfma_f32_16x16x32_bf16 v[0:3], v[194:197], v[240:243], v[0:3]
	s_setprio 0
	s_barrier
	s_add_i32 s83, 0, 0x18000
	s_add_i32 s84, 0, 0x1c000
	v_add_u32_e32 v88, s83, v185
	v_add_u32_e32 v189, s84, v185
	ds_read_b128 v[72:75], v88
	ds_read_b128 v[76:79], v88 offset:1024
	ds_read_b128 v[80:83], v88 offset:2048
	ds_read_b128 v[88:91], v88 offset:3072
	ds_read_b128 v[174:177], v189
	ds_read_b128 v[178:181], v189 offset:1024
	ds_read_b128 v[190:193], v189 offset:2048
	ds_read_b128 v[194:197], v189 offset:3072
	s_add_u32 s62, s62, 0x40000
	s_addc_u32 s63, s63, 0
	s_mov_b32 m0, s67
	v_lshl_add_u64 v[248:249], s[62:63], 0, v[148:149]
	ds_read_b128 v[210:213], v188 offset:32768
	ds_read_b128 v[214:217], v188 offset:33792
	ds_read_b128 v[218:221], v188 offset:34816
	ds_read_b128 v[224:227], v188 offset:35840
	ds_read_b128 v[228:231], v188 offset:36864
	ds_read_b128 v[232:235], v188 offset:37888
	ds_read_b128 v[236:239], v188 offset:38912
	ds_read_b128 v[240:243], v188 offset:39936
	global_load_lds_dwordx4 v[248:249], off
	v_lshl_add_u64 v[248:249], s[62:63], 0, v[146:147]
	s_mov_b32 m0, s68
	s_nop 0
	global_load_lds_dwordx4 v[248:249], off
	s_waitcnt vmcnt(8)
	s_waitcnt lgkmcnt(0)
	s_barrier
	s_setprio 1
	s_waitcnt lgkmcnt(0)
	v_mfma_f32_16x16x32_bf16 v[140:143], v[72:75], v[210:213], v[140:143]
	v_mfma_f32_16x16x32_bf16 v[136:139], v[80:83], v[210:213], v[136:139]
	v_mfma_f32_16x16x32_bf16 v[124:127], v[72:75], v[218:221], v[124:127]
	v_mfma_f32_16x16x32_bf16 v[120:123], v[80:83], v[218:221], v[120:123]
	v_mfma_f32_16x16x32_bf16 v[108:111], v[72:75], v[228:231], v[108:111]
	v_mfma_f32_16x16x32_bf16 v[104:107], v[80:83], v[228:231], v[104:107]
	v_mfma_f32_16x16x32_bf16 v[92:95], v[72:75], v[236:239], v[92:95]
	v_mfma_f32_16x16x32_bf16 v[84:87], v[80:83], v[236:239], v[84:87]
	v_mfma_f32_16x16x32_bf16 v[140:143], v[76:79], v[214:217], v[140:143]
	v_mfma_f32_16x16x32_bf16 v[136:139], v[88:91], v[214:217], v[136:139]
	v_mfma_f32_16x16x32_bf16 v[124:127], v[76:79], v[224:227], v[124:127]
	v_mfma_f32_16x16x32_bf16 v[120:123], v[88:91], v[224:227], v[120:123]
	v_mfma_f32_16x16x32_bf16 v[108:111], v[76:79], v[232:235], v[108:111]
	v_mfma_f32_16x16x32_bf16 v[104:107], v[88:91], v[232:235], v[104:107]
	v_mfma_f32_16x16x32_bf16 v[92:95], v[76:79], v[240:243], v[92:95]
	v_mfma_f32_16x16x32_bf16 v[84:87], v[88:91], v[240:243], v[84:87]
	v_mfma_f32_16x16x32_bf16 v[132:135], v[174:177], v[210:213], v[132:135]
	v_mfma_f32_16x16x32_bf16 v[128:131], v[190:193], v[210:213], v[128:131]
	v_mfma_f32_16x16x32_bf16 v[116:119], v[174:177], v[218:221], v[116:119]
	v_mfma_f32_16x16x32_bf16 v[112:115], v[190:193], v[218:221], v[112:115]
	v_mfma_f32_16x16x32_bf16 v[100:103], v[174:177], v[228:231], v[100:103]
	v_mfma_f32_16x16x32_bf16 v[96:99], v[190:193], v[228:231], v[96:99]
	v_mfma_f32_16x16x32_bf16 v[68:71], v[174:177], v[236:239], v[68:71]
	v_mfma_f32_16x16x32_bf16 v[64:67], v[190:193], v[236:239], v[64:67]
	v_mfma_f32_16x16x32_bf16 v[132:135], v[178:181], v[214:217], v[132:135]
	v_mfma_f32_16x16x32_bf16 v[128:131], v[194:197], v[214:217], v[128:131]
	v_mfma_f32_16x16x32_bf16 v[116:119], v[178:181], v[224:227], v[116:119]
	v_mfma_f32_16x16x32_bf16 v[112:115], v[194:197], v[224:227], v[112:115]
	v_mfma_f32_16x16x32_bf16 v[100:103], v[178:181], v[232:235], v[100:103]
	v_mfma_f32_16x16x32_bf16 v[96:99], v[194:197], v[232:235], v[96:99]
	v_mfma_f32_16x16x32_bf16 v[68:71], v[178:181], v[240:243], v[68:71]
	v_mfma_f32_16x16x32_bf16 v[64:67], v[194:197], v[240:243], v[64:67]
	s_setprio 0
	s_barrier
	s_add_i32 s62, s83, s8
	v_lshl_add_u64 v[182:183], v[182:183], 0, s[22:23]
	s_mov_b32 m0, s62
	ds_read_b128 v[210:213], v188 offset:49152
	ds_read_b128 v[214:217], v188 offset:50176
	ds_read_b128 v[218:221], v188 offset:51200
	ds_read_b128 v[224:227], v188 offset:52224
	ds_read_b128 v[228:231], v188 offset:53248
	ds_read_b128 v[232:235], v188 offset:54272
	ds_read_b128 v[236:239], v188 offset:55296
	ds_read_b128 v[240:243], v188 offset:56320
	global_load_lds_dwordx4 v[182:183], off
	s_add_i32 m0, s62, 0x2000
	s_add_u32 s44, s44, 0x40080
	v_lshl_add_u64 v[182:183], v[198:199], 0, s[22:23]
	s_addc_u32 s45, s45, 0
	s_add_i32 s62, s84, s8
	global_load_lds_dwordx4 v[182:183], off
	v_lshl_add_u64 v[182:183], s[44:45], 0, v[152:153]
	s_mov_b32 m0, s62
	s_nop 0
	global_load_lds_dwordx4 v[182:183], off
	v_lshl_add_u64 v[182:183], s[44:45], 0, v[144:145]
	s_add_i32 m0, s62, 0x2000
	s_nop 0
	global_load_lds_dwordx4 v[182:183], off
	v_lshl_add_u64 v[182:183], v[244:245], 0, s[22:23]
	s_mov_b32 m0, s69
	s_nop 0
	global_load_lds_dwordx4 v[182:183], off
	v_lshl_add_u64 v[182:183], v[246:247], 0, s[22:23]
	s_mov_b32 m0, s74
	s_nop 0
	global_load_lds_dwordx4 v[182:183], off
	s_waitcnt vmcnt(8)
	s_waitcnt lgkmcnt(0)
	s_barrier
	s_setprio 1
	s_waitcnt lgkmcnt(0)
	v_mfma_f32_16x16x32_bf16 v[60:63], v[72:75], v[210:213], v[60:63]
	v_mfma_f32_16x16x32_bf16 v[56:59], v[80:83], v[210:213], v[56:59]
	v_mfma_f32_16x16x32_bf16 v[44:47], v[72:75], v[218:221], v[44:47]
	v_mfma_f32_16x16x32_bf16 v[40:43], v[80:83], v[218:221], v[40:43]
	v_mfma_f32_16x16x32_bf16 v[28:31], v[72:75], v[228:231], v[28:31]
	v_mfma_f32_16x16x32_bf16 v[24:27], v[80:83], v[228:231], v[24:27]
	v_mfma_f32_16x16x32_bf16 v[12:15], v[72:75], v[236:239], v[12:15]
	v_mfma_f32_16x16x32_bf16 v[8:11], v[80:83], v[236:239], v[8:11]
	v_mfma_f32_16x16x32_bf16 v[60:63], v[76:79], v[214:217], v[60:63]
	v_mfma_f32_16x16x32_bf16 v[56:59], v[88:91], v[214:217], v[56:59]
	v_mfma_f32_16x16x32_bf16 v[44:47], v[76:79], v[224:227], v[44:47]
	v_mfma_f32_16x16x32_bf16 v[40:43], v[88:91], v[224:227], v[40:43]
	v_mfma_f32_16x16x32_bf16 v[28:31], v[76:79], v[232:235], v[28:31]
	v_mfma_f32_16x16x32_bf16 v[24:27], v[88:91], v[232:235], v[24:27]
	v_mfma_f32_16x16x32_bf16 v[12:15], v[76:79], v[240:243], v[12:15]
	v_mfma_f32_16x16x32_bf16 v[8:11], v[88:91], v[240:243], v[8:11]
	v_mfma_f32_16x16x32_bf16 v[52:55], v[174:177], v[210:213], v[52:55]
	v_mfma_f32_16x16x32_bf16 v[48:51], v[190:193], v[210:213], v[48:51]
	v_mfma_f32_16x16x32_bf16 v[36:39], v[174:177], v[218:221], v[36:39]
	v_mfma_f32_16x16x32_bf16 v[32:35], v[190:193], v[218:221], v[32:35]
	v_mfma_f32_16x16x32_bf16 v[20:23], v[174:177], v[228:231], v[20:23]
	v_mfma_f32_16x16x32_bf16 v[16:19], v[190:193], v[228:231], v[16:19]
	v_mfma_f32_16x16x32_bf16 v[4:7], v[174:177], v[236:239], v[4:7]
	v_mfma_f32_16x16x32_bf16 v[0:3], v[190:193], v[236:239], v[0:3]
	v_mfma_f32_16x16x32_bf16 v[52:55], v[178:181], v[214:217], v[52:55]
	v_mfma_f32_16x16x32_bf16 v[48:51], v[194:197], v[214:217], v[48:51]
	v_mfma_f32_16x16x32_bf16 v[36:39], v[178:181], v[224:227], v[36:39]
	v_mfma_f32_16x16x32_bf16 v[32:35], v[194:197], v[224:227], v[32:35]
	v_mfma_f32_16x16x32_bf16 v[20:23], v[178:181], v[232:235], v[20:23]
	v_mfma_f32_16x16x32_bf16 v[16:19], v[194:197], v[232:235], v[16:19]
	v_mfma_f32_16x16x32_bf16 v[4:7], v[178:181], v[240:243], v[4:7]
	v_mfma_f32_16x16x32_bf16 v[0:3], v[194:197], v[240:243], v[0:3]
	s_setprio 0
	s_barrier
	s_add_i32 s82, s82, 2
	s_add_u32 s80, s80, 0x100
	s_addc_u32 s81, s81, 0
	s_add_u32 s48, s48, 0x100
	s_addc_u32 s49, s49, 0
	s_cmp_gt_u32 s82, 13
	.p2align	6
.LBB0_419:
	s_add_u32 s44, s48, 0xfffc0080
	s_addc_u32 s45, s49, -1
	s_add_i32 s83, 0, 0x10000
	s_cmp_eq_u32 s82, 12
	s_cselect_b32 s63, s21, s45
	s_cselect_b32 s62, s78, s44
	s_cselect_b32 s45, s19, s81
	s_cselect_b32 s44, s79, s80
	s_add_i32 s86, 0, 0x14000
	v_add_u32_e32 v88, s83, v185
	v_add_u32_e32 v182, s86, v185
	ds_read_b128 v[72:75], v88
	ds_read_b128 v[76:79], v88 offset:1024
	ds_read_b128 v[80:83], v88 offset:2048
	ds_read_b128 v[88:91], v88 offset:3072
	ds_read_b128 v[174:177], v182
	ds_read_b128 v[178:181], v182 offset:1024
	ds_read_b128 v[190:193], v182 offset:2048
	ds_read_b128 v[194:197], v182 offset:3072
	v_lshl_add_u64 v[182:183], s[48:49], 0, v[172:173]
	s_add_i32 m0, s59, 0xc000
	ds_read_b128 v[210:213], v188
	ds_read_b128 v[214:217], v188 offset:1024
	ds_read_b128 v[218:221], v188 offset:2048
	ds_read_b128 v[224:227], v188 offset:3072
	ds_read_b128 v[228:231], v188 offset:4096
	ds_read_b128 v[232:235], v188 offset:5120
	ds_read_b128 v[236:239], v188 offset:6144
	ds_read_b128 v[240:243], v188 offset:7168
	global_load_lds_dwordx4 v[182:183], off
	v_lshl_add_u64 v[182:183], s[48:49], 0, v[150:151]
	s_add_i32 m0, s59, 0xe000
	s_nop 0
	global_load_lds_dwordx4 v[182:183], off
	s_waitcnt vmcnt(8)
	s_waitcnt lgkmcnt(0)
	s_barrier
	s_setprio 1
	s_waitcnt lgkmcnt(0)
	v_mfma_f32_16x16x32_bf16 v[140:143], v[72:75], v[210:213], v[140:143]
	v_mfma_f32_16x16x32_bf16 v[136:139], v[80:83], v[210:213], v[136:139]
	v_mfma_f32_16x16x32_bf16 v[124:127], v[72:75], v[218:221], v[124:127]
	v_mfma_f32_16x16x32_bf16 v[120:123], v[80:83], v[218:221], v[120:123]
	v_mfma_f32_16x16x32_bf16 v[108:111], v[72:75], v[228:231], v[108:111]
	v_mfma_f32_16x16x32_bf16 v[104:107], v[80:83], v[228:231], v[104:107]
	v_mfma_f32_16x16x32_bf16 v[92:95], v[72:75], v[236:239], v[92:95]
	v_mfma_f32_16x16x32_bf16 v[84:87], v[80:83], v[236:239], v[84:87]
	v_mfma_f32_16x16x32_bf16 v[140:143], v[76:79], v[214:217], v[140:143]
	v_mfma_f32_16x16x32_bf16 v[136:139], v[88:91], v[214:217], v[136:139]
	v_mfma_f32_16x16x32_bf16 v[124:127], v[76:79], v[224:227], v[124:127]
	v_mfma_f32_16x16x32_bf16 v[120:123], v[88:91], v[224:227], v[120:123]
	v_mfma_f32_16x16x32_bf16 v[108:111], v[76:79], v[232:235], v[108:111]
	v_mfma_f32_16x16x32_bf16 v[104:107], v[88:91], v[232:235], v[104:107]
	v_mfma_f32_16x16x32_bf16 v[92:95], v[76:79], v[240:243], v[92:95]
	v_mfma_f32_16x16x32_bf16 v[84:87], v[88:91], v[240:243], v[84:87]
	v_mfma_f32_16x16x32_bf16 v[132:135], v[174:177], v[210:213], v[132:135]
	v_mfma_f32_16x16x32_bf16 v[128:131], v[190:193], v[210:213], v[128:131]
	v_mfma_f32_16x16x32_bf16 v[116:119], v[174:177], v[218:221], v[116:119]
	v_mfma_f32_16x16x32_bf16 v[112:115], v[190:193], v[218:221], v[112:115]
	v_mfma_f32_16x16x32_bf16 v[100:103], v[174:177], v[228:231], v[100:103]
	v_mfma_f32_16x16x32_bf16 v[96:99], v[190:193], v[228:231], v[96:99]
	v_mfma_f32_16x16x32_bf16 v[68:71], v[174:177], v[236:239], v[68:71]
	v_mfma_f32_16x16x32_bf16 v[64:67], v[190:193], v[236:239], v[64:67]
	v_mfma_f32_16x16x32_bf16 v[132:135], v[178:181], v[214:217], v[132:135]
	v_mfma_f32_16x16x32_bf16 v[128:131], v[194:197], v[214:217], v[128:131]
	v_mfma_f32_16x16x32_bf16 v[116:119], v[178:181], v[224:227], v[116:119]
	v_mfma_f32_16x16x32_bf16 v[112:115], v[194:197], v[224:227], v[112:115]
	v_mfma_f32_16x16x32_bf16 v[100:103], v[178:181], v[232:235], v[100:103]
	v_mfma_f32_16x16x32_bf16 v[96:99], v[194:197], v[232:235], v[96:99]
	v_mfma_f32_16x16x32_bf16 v[68:71], v[178:181], v[240:243], v[68:71]
	v_mfma_f32_16x16x32_bf16 v[64:67], v[194:197], v[240:243], v[64:67]
	s_setprio 0
	s_barrier
	s_add_i32 s83, s83, s8
	v_lshl_add_u64 v[182:183], s[44:45], 0, v[152:153]
	s_mov_b32 m0, s83
	ds_read_b128 v[210:213], v188 offset:16384
	ds_read_b128 v[214:217], v188 offset:17408
	ds_read_b128 v[218:221], v188 offset:18432
	ds_read_b128 v[224:227], v188 offset:19456
	ds_read_b128 v[228:231], v188 offset:20480
	ds_read_b128 v[232:235], v188 offset:21504
	ds_read_b128 v[236:239], v188 offset:22528
	ds_read_b128 v[240:243], v188 offset:23552
	global_load_lds_dwordx4 v[182:183], off
	s_add_i32 m0, s83, 0x2000
	s_add_u32 s84, s44, 0x40000
	v_lshl_add_u64 v[198:199], s[44:45], 0, v[144:145]
	s_addc_u32 s85, s45, 0
	s_add_i32 s83, s86, s8
	global_load_lds_dwordx4 v[198:199], off
	v_lshl_add_u64 v[244:245], s[84:85], 0, v[152:153]
	s_mov_b32 m0, s83
	v_lshl_add_u64 v[246:247], s[62:63], 0, v[146:147]
	global_load_lds_dwordx4 v[244:245], off
	v_lshl_add_u64 v[244:245], s[84:85], 0, v[144:145]
	s_add_i32 m0, s83, 0x2000
	s_nop 0
	global_load_lds_dwordx4 v[244:245], off
	v_lshl_add_u64 v[244:245], s[62:63], 0, v[148:149]
	s_mov_b32 m0, s59
	s_nop 0
	global_load_lds_dwordx4 v[244:245], off
	s_mov_b32 m0, s66
	s_nop 0
	global_load_lds_dwordx4 v[246:247], off
	s_waitcnt vmcnt(8)
	s_waitcnt lgkmcnt(0)
	s_barrier
	s_setprio 1
	s_waitcnt lgkmcnt(0)
	v_mfma_f32_16x16x32_bf16 v[60:63], v[72:75], v[210:213], v[60:63]
	v_mfma_f32_16x16x32_bf16 v[56:59], v[80:83], v[210:213], v[56:59]
	v_mfma_f32_16x16x32_bf16 v[44:47], v[72:75], v[218:221], v[44:47]
	v_mfma_f32_16x16x32_bf16 v[40:43], v[80:83], v[218:221], v[40:43]
	v_mfma_f32_16x16x32_bf16 v[28:31], v[72:75], v[228:231], v[28:31]
	v_mfma_f32_16x16x32_bf16 v[24:27], v[80:83], v[228:231], v[24:27]
	v_mfma_f32_16x16x32_bf16 v[12:15], v[72:75], v[236:239], v[12:15]
	v_mfma_f32_16x16x32_bf16 v[8:11], v[80:83], v[236:239], v[8:11]
	v_mfma_f32_16x16x32_bf16 v[60:63], v[76:79], v[214:217], v[60:63]
	v_mfma_f32_16x16x32_bf16 v[56:59], v[88:91], v[214:217], v[56:59]
	v_mfma_f32_16x16x32_bf16 v[44:47], v[76:79], v[224:227], v[44:47]
	v_mfma_f32_16x16x32_bf16 v[40:43], v[88:91], v[224:227], v[40:43]
	v_mfma_f32_16x16x32_bf16 v[28:31], v[76:79], v[232:235], v[28:31]
	v_mfma_f32_16x16x32_bf16 v[24:27], v[88:91], v[232:235], v[24:27]
	v_mfma_f32_16x16x32_bf16 v[12:15], v[76:79], v[240:243], v[12:15]
	v_mfma_f32_16x16x32_bf16 v[8:11], v[88:91], v[240:243], v[8:11]
	v_mfma_f32_16x16x32_bf16 v[52:55], v[174:177], v[210:213], v[52:55]
	v_mfma_f32_16x16x32_bf16 v[48:51], v[190:193], v[210:213], v[48:51]
	v_mfma_f32_16x16x32_bf16 v[36:39], v[174:177], v[218:221], v[36:39]
	v_mfma_f32_16x16x32_bf16 v[32:35], v[190:193], v[218:221], v[32:35]
	v_mfma_f32_16x16x32_bf16 v[20:23], v[174:177], v[228:231], v[20:23]
	v_mfma_f32_16x16x32_bf16 v[16:19], v[190:193], v[228:231], v[16:19]
	v_mfma_f32_16x16x32_bf16 v[4:7], v[174:177], v[236:239], v[4:7]
	v_mfma_f32_16x16x32_bf16 v[0:3], v[190:193], v[236:239], v[0:3]
	v_mfma_f32_16x16x32_bf16 v[52:55], v[178:181], v[214:217], v[52:55]
	v_mfma_f32_16x16x32_bf16 v[48:51], v[194:197], v[214:217], v[48:51]
	v_mfma_f32_16x16x32_bf16 v[36:39], v[178:181], v[224:227], v[36:39]
	v_mfma_f32_16x16x32_bf16 v[32:35], v[194:197], v[224:227], v[32:35]
	v_mfma_f32_16x16x32_bf16 v[20:23], v[178:181], v[232:235], v[20:23]
	v_mfma_f32_16x16x32_bf16 v[16:19], v[194:197], v[232:235], v[16:19]
	v_mfma_f32_16x16x32_bf16 v[4:7], v[178:181], v[240:243], v[4:7]
	v_mfma_f32_16x16x32_bf16 v[0:3], v[194:197], v[240:243], v[0:3]
	s_setprio 0
	s_barrier
	s_add_i32 s83, 0, 0x18000
	s_add_i32 s84, 0, 0x1c000
	v_add_u32_e32 v88, s83, v185
	v_add_u32_e32 v189, s84, v185
	ds_read_b128 v[72:75], v88
	ds_read_b128 v[76:79], v88 offset:1024
	ds_read_b128 v[80:83], v88 offset:2048
	ds_read_b128 v[88:91], v88 offset:3072
	ds_read_b128 v[174:177], v189
	ds_read_b128 v[178:181], v189 offset:1024
	ds_read_b128 v[190:193], v189 offset:2048
	ds_read_b128 v[194:197], v189 offset:3072
	s_add_u32 s62, s62, 0x40000
	s_addc_u32 s63, s63, 0
	s_mov_b32 m0, s67
	v_lshl_add_u64 v[248:249], s[62:63], 0, v[148:149]
	ds_read_b128 v[210:213], v188 offset:32768
	ds_read_b128 v[214:217], v188 offset:33792
	ds_read_b128 v[218:221], v188 offset:34816
	ds_read_b128 v[224:227], v188 offset:35840
	ds_read_b128 v[228:231], v188 offset:36864
	ds_read_b128 v[232:235], v188 offset:37888
	ds_read_b128 v[236:239], v188 offset:38912
	ds_read_b128 v[240:243], v188 offset:39936
	global_load_lds_dwordx4 v[248:249], off
	v_lshl_add_u64 v[248:249], s[62:63], 0, v[146:147]
	s_mov_b32 m0, s68
	s_nop 0
	global_load_lds_dwordx4 v[248:249], off
	s_waitcnt vmcnt(8)
	s_waitcnt lgkmcnt(0)
	s_barrier
	s_setprio 1
	s_waitcnt lgkmcnt(0)
	v_mfma_f32_16x16x32_bf16 v[140:143], v[72:75], v[210:213], v[140:143]
	v_mfma_f32_16x16x32_bf16 v[136:139], v[80:83], v[210:213], v[136:139]
	v_mfma_f32_16x16x32_bf16 v[124:127], v[72:75], v[218:221], v[124:127]
	v_mfma_f32_16x16x32_bf16 v[120:123], v[80:83], v[218:221], v[120:123]
	v_mfma_f32_16x16x32_bf16 v[108:111], v[72:75], v[228:231], v[108:111]
	v_mfma_f32_16x16x32_bf16 v[104:107], v[80:83], v[228:231], v[104:107]
	v_mfma_f32_16x16x32_bf16 v[92:95], v[72:75], v[236:239], v[92:95]
	v_mfma_f32_16x16x32_bf16 v[84:87], v[80:83], v[236:239], v[84:87]
	v_mfma_f32_16x16x32_bf16 v[140:143], v[76:79], v[214:217], v[140:143]
	v_mfma_f32_16x16x32_bf16 v[136:139], v[88:91], v[214:217], v[136:139]
	v_mfma_f32_16x16x32_bf16 v[124:127], v[76:79], v[224:227], v[124:127]
	v_mfma_f32_16x16x32_bf16 v[120:123], v[88:91], v[224:227], v[120:123]
	v_mfma_f32_16x16x32_bf16 v[108:111], v[76:79], v[232:235], v[108:111]
	v_mfma_f32_16x16x32_bf16 v[104:107], v[88:91], v[232:235], v[104:107]
	v_mfma_f32_16x16x32_bf16 v[92:95], v[76:79], v[240:243], v[92:95]
	v_mfma_f32_16x16x32_bf16 v[84:87], v[88:91], v[240:243], v[84:87]
	v_mfma_f32_16x16x32_bf16 v[132:135], v[174:177], v[210:213], v[132:135]
	v_mfma_f32_16x16x32_bf16 v[128:131], v[190:193], v[210:213], v[128:131]
	v_mfma_f32_16x16x32_bf16 v[116:119], v[174:177], v[218:221], v[116:119]
	v_mfma_f32_16x16x32_bf16 v[112:115], v[190:193], v[218:221], v[112:115]
	v_mfma_f32_16x16x32_bf16 v[100:103], v[174:177], v[228:231], v[100:103]
	v_mfma_f32_16x16x32_bf16 v[96:99], v[190:193], v[228:231], v[96:99]
	v_mfma_f32_16x16x32_bf16 v[68:71], v[174:177], v[236:239], v[68:71]
	v_mfma_f32_16x16x32_bf16 v[64:67], v[190:193], v[236:239], v[64:67]
	v_mfma_f32_16x16x32_bf16 v[132:135], v[178:181], v[214:217], v[132:135]
	v_mfma_f32_16x16x32_bf16 v[128:131], v[194:197], v[214:217], v[128:131]
	v_mfma_f32_16x16x32_bf16 v[116:119], v[178:181], v[224:227], v[116:119]
	v_mfma_f32_16x16x32_bf16 v[112:115], v[194:197], v[224:227], v[112:115]
	v_mfma_f32_16x16x32_bf16 v[100:103], v[178:181], v[232:235], v[100:103]
	v_mfma_f32_16x16x32_bf16 v[96:99], v[194:197], v[232:235], v[96:99]
	v_mfma_f32_16x16x32_bf16 v[68:71], v[178:181], v[240:243], v[68:71]
	v_mfma_f32_16x16x32_bf16 v[64:67], v[194:197], v[240:243], v[64:67]
	s_setprio 0
	s_barrier
	s_add_i32 s62, s83, s8
	v_lshl_add_u64 v[182:183], v[182:183], 0, s[22:23]
	s_mov_b32 m0, s62
	ds_read_b128 v[210:213], v188 offset:49152
	ds_read_b128 v[214:217], v188 offset:50176
	ds_read_b128 v[218:221], v188 offset:51200
	ds_read_b128 v[224:227], v188 offset:52224
	ds_read_b128 v[228:231], v188 offset:53248
	ds_read_b128 v[232:235], v188 offset:54272
	ds_read_b128 v[236:239], v188 offset:55296
	ds_read_b128 v[240:243], v188 offset:56320
	global_load_lds_dwordx4 v[182:183], off
	s_add_i32 m0, s62, 0x2000
	s_add_u32 s44, s44, 0x40080
	v_lshl_add_u64 v[182:183], v[198:199], 0, s[22:23]
	s_addc_u32 s45, s45, 0
	s_add_i32 s62, s84, s8
	global_load_lds_dwordx4 v[182:183], off
	v_lshl_add_u64 v[182:183], s[44:45], 0, v[152:153]
	s_mov_b32 m0, s62
	s_nop 0
	global_load_lds_dwordx4 v[182:183], off
	v_lshl_add_u64 v[182:183], s[44:45], 0, v[144:145]
	s_add_i32 m0, s62, 0x2000
	s_nop 0
	global_load_lds_dwordx4 v[182:183], off
	v_lshl_add_u64 v[182:183], v[244:245], 0, s[22:23]
	s_mov_b32 m0, s69
	s_nop 0
	global_load_lds_dwordx4 v[182:183], off
	v_lshl_add_u64 v[182:183], v[246:247], 0, s[22:23]
	s_mov_b32 m0, s74
	s_nop 0
	global_load_lds_dwordx4 v[182:183], off
	s_waitcnt vmcnt(8)
	s_waitcnt lgkmcnt(0)
	s_barrier
	s_setprio 1
	s_waitcnt lgkmcnt(0)
	v_mfma_f32_16x16x32_bf16 v[60:63], v[72:75], v[210:213], v[60:63]
	v_mfma_f32_16x16x32_bf16 v[56:59], v[80:83], v[210:213], v[56:59]
	v_mfma_f32_16x16x32_bf16 v[44:47], v[72:75], v[218:221], v[44:47]
	v_mfma_f32_16x16x32_bf16 v[40:43], v[80:83], v[218:221], v[40:43]
	v_mfma_f32_16x16x32_bf16 v[28:31], v[72:75], v[228:231], v[28:31]
	v_mfma_f32_16x16x32_bf16 v[24:27], v[80:83], v[228:231], v[24:27]
	v_mfma_f32_16x16x32_bf16 v[12:15], v[72:75], v[236:239], v[12:15]
	v_mfma_f32_16x16x32_bf16 v[8:11], v[80:83], v[236:239], v[8:11]
	v_mfma_f32_16x16x32_bf16 v[60:63], v[76:79], v[214:217], v[60:63]
	v_mfma_f32_16x16x32_bf16 v[56:59], v[88:91], v[214:217], v[56:59]
	v_mfma_f32_16x16x32_bf16 v[44:47], v[76:79], v[224:227], v[44:47]
	v_mfma_f32_16x16x32_bf16 v[40:43], v[88:91], v[224:227], v[40:43]
	v_mfma_f32_16x16x32_bf16 v[28:31], v[76:79], v[232:235], v[28:31]
	v_mfma_f32_16x16x32_bf16 v[24:27], v[88:91], v[232:235], v[24:27]
	v_mfma_f32_16x16x32_bf16 v[12:15], v[76:79], v[240:243], v[12:15]
	v_mfma_f32_16x16x32_bf16 v[8:11], v[88:91], v[240:243], v[8:11]
	v_mfma_f32_16x16x32_bf16 v[52:55], v[174:177], v[210:213], v[52:55]
	v_mfma_f32_16x16x32_bf16 v[48:51], v[190:193], v[210:213], v[48:51]
	v_mfma_f32_16x16x32_bf16 v[36:39], v[174:177], v[218:221], v[36:39]
	v_mfma_f32_16x16x32_bf16 v[32:35], v[190:193], v[218:221], v[32:35]
	v_mfma_f32_16x16x32_bf16 v[20:23], v[174:177], v[228:231], v[20:23]
	v_mfma_f32_16x16x32_bf16 v[16:19], v[190:193], v[228:231], v[16:19]
	v_mfma_f32_16x16x32_bf16 v[4:7], v[174:177], v[236:239], v[4:7]
	v_mfma_f32_16x16x32_bf16 v[0:3], v[190:193], v[236:239], v[0:3]
	v_mfma_f32_16x16x32_bf16 v[52:55], v[178:181], v[214:217], v[52:55]
	v_mfma_f32_16x16x32_bf16 v[48:51], v[194:197], v[214:217], v[48:51]
	v_mfma_f32_16x16x32_bf16 v[36:39], v[178:181], v[224:227], v[36:39]
	v_mfma_f32_16x16x32_bf16 v[32:35], v[194:197], v[224:227], v[32:35]
	v_mfma_f32_16x16x32_bf16 v[20:23], v[178:181], v[232:235], v[20:23]
	v_mfma_f32_16x16x32_bf16 v[16:19], v[194:197], v[232:235], v[16:19]
	v_mfma_f32_16x16x32_bf16 v[4:7], v[178:181], v[240:243], v[4:7]
	v_mfma_f32_16x16x32_bf16 v[0:3], v[194:197], v[240:243], v[0:3]
	s_setprio 0
	s_barrier
	s_add_i32 s82, s82, 2
	s_add_u32 s80, s80, 0x100
	s_addc_u32 s81, s81, 0
	s_add_u32 s48, s48, 0x100
	s_addc_u32 s49, s49, 0
	s_cmp_gt_u32 s82, 13
	s_cbranch_scc0 .LBB0_419
	s_and_b64 vcc, exec, s[16:17]
	s_cbranch_vccz .LBB0_422
	s_barrier

.LBB0_704:
	s_ashr_i32 s21, s20, 31
	s_lshl_b64 s[48:49], s[20:21], 18
	v_readlane_b32 s19, v254, 14
	s_add_u32 s48, s19, s48
	v_readlane_b32 s19, v254, 15
	s_addc_u32 s49, s19, s49
	s_and_b64 s[50:51], s[46:47], exec
	s_cselect_b32 s21, s49, s45
	s_cselect_b32 s78, s48, s44
	s_ashr_i32 s19, s18, 31
	s_lshl_b64 s[50:51], s[18:19], 18
	v_readlane_b32 s19, v254, 10
	s_add_u32 s50, s19, s50
	v_readlane_b32 s19, v254, 11
	s_addc_u32 s51, s19, s51
	s_and_b64 s[62:63], s[46:47], exec
	s_cselect_b32 s19, s51, s61
	s_cselect_b32 s79, s50, s60
	s_add_u32 s80, s60, 0x100
	s_addc_u32 s81, s61, 0
	s_add_u32 s60, s44, 0x20080
	s_addc_u32 s61, s45, 0
	s_mov_b32 s82, -2
	s_add_u32 s44, s60, 0xfffe0080
	s_addc_u32 s45, s61, -1
	s_cmp_eq_u32 s82, 4
	s_cselect_b32 s63, s21, s45
	s_cselect_b32 s62, s78, s44
	s_cselect_b32 s45, s19, s81
	s_cselect_b32 s44, s79, s80
	v_lshl_add_u64 v[198:199], s[60:61], 0, v[180:181]
	s_add_i32 m0, s59, 0xc000
	global_load_lds_dwordx4 v[198:199], off
	v_lshl_add_u64 v[198:199], s[60:61], 0, v[178:179]
	s_add_i32 m0, s59, 0xe000
	s_nop 0
	global_load_lds_dwordx4 v[198:199], off
	s_waitcnt vmcnt(8)
	s_waitcnt lgkmcnt(0)
	s_barrier
	s_setprio 1
	s_waitcnt lgkmcnt(0)
	v_mfma_f32_16x16x32_bf16 v[128:131], v[124:127], v[190:193], 0
	v_mfma_f32_16x16x32_bf16 v[120:123], v[136:139], v[190:193], 0
	v_mfma_f32_16x16x32_bf16 v[108:111], v[124:127], v[214:217], 0
	v_mfma_f32_16x16x32_bf16 v[104:107], v[136:139], v[214:217], 0
	v_mfma_f32_16x16x32_bf16 v[92:95], v[124:127], v[224:227], 0
	v_mfma_f32_16x16x32_bf16 v[88:91], v[136:139], v[224:227], 0
	v_mfma_f32_16x16x32_bf16 v[76:79], v[124:127], v[232:235], 0
	v_mfma_f32_16x16x32_bf16 v[72:75], v[136:139], v[232:235], 0
	v_mfma_f32_16x16x32_bf16 v[128:131], v[132:135], v[210:213], v[128:131]
	v_mfma_f32_16x16x32_bf16 v[120:123], v[140:143], v[210:213], v[120:123]
	v_mfma_f32_16x16x32_bf16 v[108:111], v[132:135], v[218:221], v[108:111]
	v_mfma_f32_16x16x32_bf16 v[104:107], v[140:143], v[218:221], v[104:107]
	v_mfma_f32_16x16x32_bf16 v[92:95], v[132:135], v[228:231], v[92:95]
	v_mfma_f32_16x16x32_bf16 v[88:91], v[140:143], v[228:231], v[88:91]
	v_mfma_f32_16x16x32_bf16 v[76:79], v[132:135], v[236:239], v[76:79]
	v_mfma_f32_16x16x32_bf16 v[72:75], v[140:143], v[236:239], v[72:75]
	v_mfma_f32_16x16x32_bf16 v[116:119], v[144:147], v[190:193], 0
	v_mfma_f32_16x16x32_bf16 v[112:115], v[182:185], v[190:193], 0
	v_mfma_f32_16x16x32_bf16 v[100:103], v[144:147], v[214:217], 0
	v_mfma_f32_16x16x32_bf16 v[96:99], v[182:185], v[214:217], 0
	v_mfma_f32_16x16x32_bf16 v[84:87], v[144:147], v[224:227], 0
	v_mfma_f32_16x16x32_bf16 v[80:83], v[182:185], v[224:227], 0
	v_mfma_f32_16x16x32_bf16 v[68:71], v[144:147], v[232:235], 0
	v_mfma_f32_16x16x32_bf16 v[64:67], v[182:185], v[232:235], 0
	v_mfma_f32_16x16x32_bf16 v[116:119], v[148:151], v[210:213], v[116:119]
	v_mfma_f32_16x16x32_bf16 v[112:115], v[186:189], v[210:213], v[112:115]
	v_mfma_f32_16x16x32_bf16 v[100:103], v[148:151], v[218:221], v[100:103]
	v_mfma_f32_16x16x32_bf16 v[96:99], v[186:189], v[218:221], v[96:99]
	v_mfma_f32_16x16x32_bf16 v[84:87], v[148:151], v[228:231], v[84:87]
	v_mfma_f32_16x16x32_bf16 v[80:83], v[186:189], v[228:231], v[80:83]
	v_mfma_f32_16x16x32_bf16 v[68:71], v[148:151], v[236:239], v[68:71]
	v_mfma_f32_16x16x32_bf16 v[64:67], v[186:189], v[236:239], v[64:67]
	s_setprio 0
	s_barrier
	s_add_i32 s83, s83, s8
	v_lshl_add_u64 v[198:199], s[44:45], 0, v[152:153]
	s_mov_b32 m0, s83
	ds_read_b128 v[190:193], v197 offset:16384
	ds_read_b128 v[210:213], v197 offset:17408
	ds_read_b128 v[214:217], v197 offset:18432
	ds_read_b128 v[218:221], v197 offset:19456
	ds_read_b128 v[224:227], v197 offset:20480
	ds_read_b128 v[228:231], v197 offset:21504
	ds_read_b128 v[232:235], v197 offset:22528
	ds_read_b128 v[236:239], v197 offset:23552
	global_load_lds_dwordx4 v[198:199], off
	s_add_i32 m0, s83, 0x2000
	s_add_u32 s84, s44, 0x20000
	v_lshl_add_u64 v[240:241], s[44:45], 0, v[172:173]
	s_addc_u32 s85, s45, 0
	s_add_i32 s83, s86, s8
	global_load_lds_dwordx4 v[240:241], off
	v_lshl_add_u64 v[242:243], s[84:85], 0, v[152:153]
	s_mov_b32 m0, s83
	v_lshl_add_u64 v[244:245], s[62:63], 0, v[174:175]
	global_load_lds_dwordx4 v[242:243], off
	v_lshl_add_u64 v[242:243], s[84:85], 0, v[172:173]
	s_add_i32 m0, s83, 0x2000
	s_nop 0
	global_load_lds_dwordx4 v[242:243], off
	v_lshl_add_u64 v[242:243], s[62:63], 0, v[176:177]
	s_mov_b32 m0, s59
	s_nop 0
	global_load_lds_dwordx4 v[242:243], off
	s_mov_b32 m0, s66
	s_nop 0
	global_load_lds_dwordx4 v[244:245], off
	s_waitcnt vmcnt(8)
	s_waitcnt lgkmcnt(0)
	s_barrier
	s_setprio 1
	s_waitcnt lgkmcnt(0)
	v_mfma_f32_16x16x32_bf16 v[60:63], v[124:127], v[190:193], 0
	v_mfma_f32_16x16x32_bf16 v[56:59], v[136:139], v[190:193], 0
	v_mfma_f32_16x16x32_bf16 v[48:51], v[124:127], v[214:217], 0
	v_mfma_f32_16x16x32_bf16 v[40:43], v[136:139], v[214:217], 0
	v_mfma_f32_16x16x32_bf16 v[32:35], v[124:127], v[224:227], 0
	v_mfma_f32_16x16x32_bf16 v[24:27], v[136:139], v[224:227], 0
	v_mfma_f32_16x16x32_bf16 v[16:19], v[124:127], v[232:235], 0
	v_mfma_f32_16x16x32_bf16 v[8:11], v[136:139], v[232:235], 0
	v_mfma_f32_16x16x32_bf16 v[60:63], v[132:135], v[210:213], v[60:63]
	v_mfma_f32_16x16x32_bf16 v[56:59], v[140:143], v[210:213], v[56:59]
	v_mfma_f32_16x16x32_bf16 v[48:51], v[132:135], v[218:221], v[48:51]
	v_mfma_f32_16x16x32_bf16 v[40:43], v[140:143], v[218:221], v[40:43]
	v_mfma_f32_16x16x32_bf16 v[32:35], v[132:135], v[228:231], v[32:35]
	v_mfma_f32_16x16x32_bf16 v[24:27], v[140:143], v[228:231], v[24:27]
	v_mfma_f32_16x16x32_bf16 v[16:19], v[132:135], v[236:239], v[16:19]
	v_mfma_f32_16x16x32_bf16 v[8:11], v[140:143], v[236:239], v[8:11]
	v_mfma_f32_16x16x32_bf16 v[52:55], v[144:147], v[190:193], 0
	v_mfma_f32_16x16x32_bf16 v[44:47], v[182:185], v[190:193], 0
	v_mfma_f32_16x16x32_bf16 v[36:39], v[144:147], v[214:217], 0
	v_mfma_f32_16x16x32_bf16 v[28:31], v[182:185], v[214:217], 0
	v_mfma_f32_16x16x32_bf16 v[20:23], v[144:147], v[224:227], 0
	v_mfma_f32_16x16x32_bf16 v[12:15], v[182:185], v[224:227], 0
	v_mfma_f32_16x16x32_bf16 v[4:7], v[144:147], v[232:235], 0
	v_mfma_f32_16x16x32_bf16 v[0:3], v[182:185], v[232:235], 0
	v_mfma_f32_16x16x32_bf16 v[52:55], v[148:151], v[210:213], v[52:55]
	v_mfma_f32_16x16x32_bf16 v[44:47], v[186:189], v[210:213], v[44:47]
	v_mfma_f32_16x16x32_bf16 v[36:39], v[148:151], v[218:221], v[36:39]
	v_mfma_f32_16x16x32_bf16 v[28:31], v[186:189], v[218:221], v[28:31]
	v_mfma_f32_16x16x32_bf16 v[20:23], v[148:151], v[228:231], v[20:23]
	v_mfma_f32_16x16x32_bf16 v[12:15], v[186:189], v[228:231], v[12:15]
	v_mfma_f32_16x16x32_bf16 v[4:7], v[148:151], v[236:239], v[4:7]
	v_mfma_f32_16x16x32_bf16 v[0:3], v[186:189], v[236:239], v[0:3]
	s_setprio 0
	s_barrier
	s_add_i32 s83, 0, 0x18000
	s_add_i32 s84, 0, 0x1c000
	v_add_u32_e32 v140, s83, v195
	v_add_u32_e32 v186, s84, v195
	ds_read_b128 v[124:127], v140
	ds_read_b128 v[132:135], v140 offset:1024
	ds_read_b128 v[136:139], v140 offset:2048
	ds_read_b128 v[140:143], v140 offset:3072
	ds_read_b128 v[144:147], v186
	ds_read_b128 v[148:151], v186 offset:1024
	ds_read_b128 v[182:185], v186 offset:2048
	ds_read_b128 v[186:189], v186 offset:3072
	s_add_u32 s62, s62, 0x20000
	s_addc_u32 s63, s63, 0
	s_mov_b32 m0, s67
	v_lshl_add_u64 v[246:247], s[62:63], 0, v[176:177]
	ds_read_b128 v[190:193], v197 offset:32768
	ds_read_b128 v[210:213], v197 offset:33792
	ds_read_b128 v[214:217], v197 offset:34816
	ds_read_b128 v[218:221], v197 offset:35840
	ds_read_b128 v[224:227], v197 offset:36864
	ds_read_b128 v[228:231], v197 offset:37888
	ds_read_b128 v[232:235], v197 offset:38912
	ds_read_b128 v[236:239], v197 offset:39936
	global_load_lds_dwordx4 v[246:247], off
	v_lshl_add_u64 v[246:247], s[62:63], 0, v[174:175]
	s_mov_b32 m0, s68
	s_nop 0
	global_load_lds_dwordx4 v[246:247], off
	s_waitcnt vmcnt(8)
	s_waitcnt lgkmcnt(0)
	s_barrier
	s_setprio 1
	s_waitcnt lgkmcnt(0)
	v_mfma_f32_16x16x32_bf16 v[128:131], v[124:127], v[190:193], v[128:131]
	v_mfma_f32_16x16x32_bf16 v[120:123], v[136:139], v[190:193], v[120:123]
	v_mfma_f32_16x16x32_bf16 v[108:111], v[124:127], v[214:217], v[108:111]
	v_mfma_f32_16x16x32_bf16 v[104:107], v[136:139], v[214:217], v[104:107]
	v_mfma_f32_16x16x32_bf16 v[92:95], v[124:127], v[224:227], v[92:95]
	v_mfma_f32_16x16x32_bf16 v[88:91], v[136:139], v[224:227], v[88:91]
	v_mfma_f32_16x16x32_bf16 v[76:79], v[124:127], v[232:235], v[76:79]
	v_mfma_f32_16x16x32_bf16 v[72:75], v[136:139], v[232:235], v[72:75]
	v_mfma_f32_16x16x32_bf16 v[128:131], v[132:135], v[210:213], v[128:131]
	v_mfma_f32_16x16x32_bf16 v[120:123], v[140:143], v[210:213], v[120:123]
	v_mfma_f32_16x16x32_bf16 v[108:111], v[132:135], v[218:221], v[108:111]
	v_mfma_f32_16x16x32_bf16 v[104:107], v[140:143], v[218:221], v[104:107]
	v_mfma_f32_16x16x32_bf16 v[92:95], v[132:135], v[228:231], v[92:95]
	v_mfma_f32_16x16x32_bf16 v[88:91], v[140:143], v[228:231], v[88:91]
	v_mfma_f32_16x16x32_bf16 v[76:79], v[132:135], v[236:239], v[76:79]
	v_mfma_f32_16x16x32_bf16 v[72:75], v[140:143], v[236:239], v[72:75]
	v_mfma_f32_16x16x32_bf16 v[116:119], v[144:147], v[190:193], v[116:119]
	v_mfma_f32_16x16x32_bf16 v[112:115], v[182:185], v[190:193], v[112:115]
	v_mfma_f32_16x16x32_bf16 v[100:103], v[144:147], v[214:217], v[100:103]
	v_mfma_f32_16x16x32_bf16 v[96:99], v[182:185], v[214:217], v[96:99]
	v_mfma_f32_16x16x32_bf16 v[84:87], v[144:147], v[224:227], v[84:87]
	v_mfma_f32_16x16x32_bf16 v[80:83], v[182:185], v[224:227], v[80:83]
	v_mfma_f32_16x16x32_bf16 v[68:71], v[144:147], v[232:235], v[68:71]
	v_mfma_f32_16x16x32_bf16 v[64:67], v[182:185], v[232:235], v[64:67]
	v_mfma_f32_16x16x32_bf16 v[116:119], v[148:151], v[210:213], v[116:119]
	v_mfma_f32_16x16x32_bf16 v[112:115], v[186:189], v[210:213], v[112:115]
	v_mfma_f32_16x16x32_bf16 v[100:103], v[148:151], v[218:221], v[100:103]
	v_mfma_f32_16x16x32_bf16 v[96:99], v[186:189], v[218:221], v[96:99]
	v_mfma_f32_16x16x32_bf16 v[84:87], v[148:151], v[228:231], v[84:87]
	v_mfma_f32_16x16x32_bf16 v[80:83], v[186:189], v[228:231], v[80:83]
	v_mfma_f32_16x16x32_bf16 v[68:71], v[148:151], v[236:239], v[68:71]
	v_mfma_f32_16x16x32_bf16 v[64:67], v[186:189], v[236:239], v[64:67]
	s_setprio 0
	s_barrier
	s_add_i32 s62, s83, s8
	v_lshl_add_u64 v[198:199], v[198:199], 0, s[22:23]
	s_mov_b32 m0, s62
	ds_read_b128 v[190:193], v197 offset:49152
	ds_read_b128 v[210:213], v197 offset:50176
	ds_read_b128 v[214:217], v197 offset:51200
	ds_read_b128 v[218:221], v197 offset:52224
	ds_read_b128 v[224:227], v197 offset:53248
	ds_read_b128 v[228:231], v197 offset:54272
	ds_read_b128 v[232:235], v197 offset:55296
	ds_read_b128 v[236:239], v197 offset:56320
	global_load_lds_dwordx4 v[198:199], off
	s_add_i32 m0, s62, 0x2000
	s_add_u32 s44, s44, 0x20080
	v_lshl_add_u64 v[198:199], v[240:241], 0, s[22:23]
	s_addc_u32 s45, s45, 0
	s_add_i32 s62, s84, s8
	global_load_lds_dwordx4 v[198:199], off
	v_lshl_add_u64 v[198:199], s[44:45], 0, v[152:153]
	s_mov_b32 m0, s62
	s_nop 0
	global_load_lds_dwordx4 v[198:199], off
	v_lshl_add_u64 v[198:199], s[44:45], 0, v[172:173]
	s_add_i32 m0, s62, 0x2000
	s_nop 0
	global_load_lds_dwordx4 v[198:199], off
	v_lshl_add_u64 v[198:199], v[242:243], 0, s[22:23]
	s_mov_b32 m0, s69
	s_nop 0
	global_load_lds_dwordx4 v[198:199], off
	v_lshl_add_u64 v[198:199], v[244:245], 0, s[22:23]
	s_mov_b32 m0, s74
	s_nop 0
	global_load_lds_dwordx4 v[198:199], off
	s_waitcnt vmcnt(8)
	s_waitcnt lgkmcnt(0)
	s_barrier
	s_setprio 1
	s_waitcnt lgkmcnt(0)
	v_mfma_f32_16x16x32_bf16 v[60:63], v[124:127], v[190:193], v[60:63]
	v_mfma_f32_16x16x32_bf16 v[56:59], v[136:139], v[190:193], v[56:59]
	v_mfma_f32_16x16x32_bf16 v[48:51], v[124:127], v[214:217], v[48:51]
	v_mfma_f32_16x16x32_bf16 v[40:43], v[136:139], v[214:217], v[40:43]
	v_mfma_f32_16x16x32_bf16 v[32:35], v[124:127], v[224:227], v[32:35]
	v_mfma_f32_16x16x32_bf16 v[24:27], v[136:139], v[224:227], v[24:27]
	v_mfma_f32_16x16x32_bf16 v[16:19], v[124:127], v[232:235], v[16:19]
	v_mfma_f32_16x16x32_bf16 v[8:11], v[136:139], v[232:235], v[8:11]
	v_mfma_f32_16x16x32_bf16 v[60:63], v[132:135], v[210:213], v[60:63]
	v_mfma_f32_16x16x32_bf16 v[56:59], v[140:143], v[210:213], v[56:59]
	v_mfma_f32_16x16x32_bf16 v[48:51], v[132:135], v[218:221], v[48:51]
	v_mfma_f32_16x16x32_bf16 v[40:43], v[140:143], v[218:221], v[40:43]
	v_mfma_f32_16x16x32_bf16 v[32:35], v[132:135], v[228:231], v[32:35]
	v_mfma_f32_16x16x32_bf16 v[24:27], v[140:143], v[228:231], v[24:27]
	v_mfma_f32_16x16x32_bf16 v[16:19], v[132:135], v[236:239], v[16:19]
	v_mfma_f32_16x16x32_bf16 v[8:11], v[140:143], v[236:239], v[8:11]
	v_mfma_f32_16x16x32_bf16 v[52:55], v[144:147], v[190:193], v[52:55]
	v_mfma_f32_16x16x32_bf16 v[44:47], v[182:185], v[190:193], v[44:47]
	v_mfma_f32_16x16x32_bf16 v[36:39], v[144:147], v[214:217], v[36:39]
	v_mfma_f32_16x16x32_bf16 v[28:31], v[182:185], v[214:217], v[28:31]
	v_mfma_f32_16x16x32_bf16 v[20:23], v[144:147], v[224:227], v[20:23]
	v_mfma_f32_16x16x32_bf16 v[12:15], v[182:185], v[224:227], v[12:15]
	v_mfma_f32_16x16x32_bf16 v[4:7], v[144:147], v[232:235], v[4:7]
	v_mfma_f32_16x16x32_bf16 v[0:3], v[182:185], v[232:235], v[0:3]
	v_mfma_f32_16x16x32_bf16 v[52:55], v[148:151], v[210:213], v[52:55]
	v_mfma_f32_16x16x32_bf16 v[44:47], v[186:189], v[210:213], v[44:47]
	v_mfma_f32_16x16x32_bf16 v[36:39], v[148:151], v[218:221], v[36:39]
	v_mfma_f32_16x16x32_bf16 v[28:31], v[186:189], v[218:221], v[28:31]
	v_mfma_f32_16x16x32_bf16 v[20:23], v[148:151], v[228:231], v[20:23]
	v_mfma_f32_16x16x32_bf16 v[12:15], v[186:189], v[228:231], v[12:15]
	v_mfma_f32_16x16x32_bf16 v[4:7], v[148:151], v[236:239], v[4:7]
	v_mfma_f32_16x16x32_bf16 v[0:3], v[186:189], v[236:239], v[0:3]
	s_setprio 0
	s_barrier
	s_add_i32 s82, s82, 2
	s_add_u32 s80, s80, 0x100
	s_addc_u32 s81, s81, 0
	s_add_u32 s60, s60, 0x100
	s_addc_u32 s61, s61, 0
	s_cmp_gt_u32 s82, 5
	.p2align	6
.LBB0_705:
	s_add_u32 s44, s60, 0xfffe0080
	s_addc_u32 s45, s61, -1
	s_add_i32 s83, 0, 0x10000
	s_cmp_eq_u32 s82, 4
	s_cselect_b32 s63, s21, s45
	s_cselect_b32 s62, s78, s44
	s_cselect_b32 s45, s19, s81
	s_cselect_b32 s44, s79, s80
	s_add_i32 s86, 0, 0x14000
	v_add_u32_e32 v140, s83, v195
	v_add_u32_e32 v186, s86, v195
	ds_read_b128 v[124:127], v140
	ds_read_b128 v[132:135], v140 offset:1024
	ds_read_b128 v[136:139], v140 offset:2048
	ds_read_b128 v[140:143], v140 offset:3072
	ds_read_b128 v[144:147], v186
	ds_read_b128 v[148:151], v186 offset:1024
	ds_read_b128 v[182:185], v186 offset:2048
	ds_read_b128 v[186:189], v186 offset:3072
	v_lshl_add_u64 v[198:199], s[60:61], 0, v[180:181]
	s_add_i32 m0, s59, 0xc000
	ds_read_b128 v[190:193], v197
	ds_read_b128 v[210:213], v197 offset:1024
	ds_read_b128 v[214:217], v197 offset:2048
	ds_read_b128 v[218:221], v197 offset:3072
	ds_read_b128 v[224:227], v197 offset:4096
	ds_read_b128 v[228:231], v197 offset:5120
	ds_read_b128 v[232:235], v197 offset:6144
	ds_read_b128 v[236:239], v197 offset:7168
	global_load_lds_dwordx4 v[198:199], off
	v_lshl_add_u64 v[198:199], s[60:61], 0, v[178:179]
	s_add_i32 m0, s59, 0xe000
	s_nop 0
	global_load_lds_dwordx4 v[198:199], off
	s_waitcnt vmcnt(8)
	s_waitcnt lgkmcnt(0)
	s_barrier
	s_setprio 1
	s_waitcnt lgkmcnt(0)
	v_mfma_f32_16x16x32_bf16 v[128:131], v[124:127], v[190:193], v[128:131]
	v_mfma_f32_16x16x32_bf16 v[120:123], v[136:139], v[190:193], v[120:123]
	v_mfma_f32_16x16x32_bf16 v[108:111], v[124:127], v[214:217], v[108:111]
	v_mfma_f32_16x16x32_bf16 v[104:107], v[136:139], v[214:217], v[104:107]
	v_mfma_f32_16x16x32_bf16 v[92:95], v[124:127], v[224:227], v[92:95]
	v_mfma_f32_16x16x32_bf16 v[88:91], v[136:139], v[224:227], v[88:91]
	v_mfma_f32_16x16x32_bf16 v[76:79], v[124:127], v[232:235], v[76:79]
	v_mfma_f32_16x16x32_bf16 v[72:75], v[136:139], v[232:235], v[72:75]
	v_mfma_f32_16x16x32_bf16 v[128:131], v[132:135], v[210:213], v[128:131]
	v_mfma_f32_16x16x32_bf16 v[120:123], v[140:143], v[210:213], v[120:123]
	v_mfma_f32_16x16x32_bf16 v[108:111], v[132:135], v[218:221], v[108:111]
	v_mfma_f32_16x16x32_bf16 v[104:107], v[140:143], v[218:221], v[104:107]
	v_mfma_f32_16x16x32_bf16 v[92:95], v[132:135], v[228:231], v[92:95]
	v_mfma_f32_16x16x32_bf16 v[88:91], v[140:143], v[228:231], v[88:91]
	v_mfma_f32_16x16x32_bf16 v[76:79], v[132:135], v[236:239], v[76:79]
	v_mfma_f32_16x16x32_bf16 v[72:75], v[140:143], v[236:239], v[72:75]
	v_mfma_f32_16x16x32_bf16 v[116:119], v[144:147], v[190:193], v[116:119]
	v_mfma_f32_16x16x32_bf16 v[112:115], v[182:185], v[190:193], v[112:115]
	v_mfma_f32_16x16x32_bf16 v[100:103], v[144:147], v[214:217], v[100:103]
	v_mfma_f32_16x16x32_bf16 v[96:99], v[182:185], v[214:217], v[96:99]
	v_mfma_f32_16x16x32_bf16 v[84:87], v[144:147], v[224:227], v[84:87]
	v_mfma_f32_16x16x32_bf16 v[80:83], v[182:185], v[224:227], v[80:83]
	v_mfma_f32_16x16x32_bf16 v[68:71], v[144:147], v[232:235], v[68:71]
	v_mfma_f32_16x16x32_bf16 v[64:67], v[182:185], v[232:235], v[64:67]
	v_mfma_f32_16x16x32_bf16 v[116:119], v[148:151], v[210:213], v[116:119]
	v_mfma_f32_16x16x32_bf16 v[112:115], v[186:189], v[210:213], v[112:115]
	v_mfma_f32_16x16x32_bf16 v[100:103], v[148:151], v[218:221], v[100:103]
	v_mfma_f32_16x16x32_bf16 v[96:99], v[186:189], v[218:221], v[96:99]
	v_mfma_f32_16x16x32_bf16 v[84:87], v[148:151], v[228:231], v[84:87]
	v_mfma_f32_16x16x32_bf16 v[80:83], v[186:189], v[228:231], v[80:83]
	v_mfma_f32_16x16x32_bf16 v[68:71], v[148:151], v[236:239], v[68:71]
	v_mfma_f32_16x16x32_bf16 v[64:67], v[186:189], v[236:239], v[64:67]
	s_setprio 0
	s_barrier
	s_add_i32 s83, s83, s8
	v_lshl_add_u64 v[198:199], s[44:45], 0, v[152:153]
	s_mov_b32 m0, s83
	ds_read_b128 v[190:193], v197 offset:16384
	ds_read_b128 v[210:213], v197 offset:17408
	ds_read_b128 v[214:217], v197 offset:18432
	ds_read_b128 v[218:221], v197 offset:19456
	ds_read_b128 v[224:227], v197 offset:20480
	ds_read_b128 v[228:231], v197 offset:21504
	ds_read_b128 v[232:235], v197 offset:22528
	ds_read_b128 v[236:239], v197 offset:23552
	global_load_lds_dwordx4 v[198:199], off
	s_add_i32 m0, s83, 0x2000
	s_add_u32 s84, s44, 0x20000
	v_lshl_add_u64 v[240:241], s[44:45], 0, v[172:173]
	s_addc_u32 s85, s45, 0
	s_add_i32 s83, s86, s8
	global_load_lds_dwordx4 v[240:241], off
	v_lshl_add_u64 v[242:243], s[84:85], 0, v[152:153]
	s_mov_b32 m0, s83
	v_lshl_add_u64 v[244:245], s[62:63], 0, v[174:175]
	global_load_lds_dwordx4 v[242:243], off
	v_lshl_add_u64 v[242:243], s[84:85], 0, v[172:173]
	s_add_i32 m0, s83, 0x2000
	s_nop 0
	global_load_lds_dwordx4 v[242:243], off
	v_lshl_add_u64 v[242:243], s[62:63], 0, v[176:177]
	s_mov_b32 m0, s59
	s_nop 0
	global_load_lds_dwordx4 v[242:243], off
	s_mov_b32 m0, s66
	s_nop 0
	global_load_lds_dwordx4 v[244:245], off
	s_waitcnt vmcnt(8)
	s_waitcnt lgkmcnt(0)
	s_barrier
	s_setprio 1
	s_waitcnt lgkmcnt(0)
	v_mfma_f32_16x16x32_bf16 v[60:63], v[124:127], v[190:193], v[60:63]
	v_mfma_f32_16x16x32_bf16 v[56:59], v[136:139], v[190:193], v[56:59]
	v_mfma_f32_16x16x32_bf16 v[48:51], v[124:127], v[214:217], v[48:51]
	v_mfma_f32_16x16x32_bf16 v[40:43], v[136:139], v[214:217], v[40:43]
	v_mfma_f32_16x16x32_bf16 v[32:35], v[124:127], v[224:227], v[32:35]
	v_mfma_f32_16x16x32_bf16 v[24:27], v[136:139], v[224:227], v[24:27]
	v_mfma_f32_16x16x32_bf16 v[16:19], v[124:127], v[232:235], v[16:19]
	v_mfma_f32_16x16x32_bf16 v[8:11], v[136:139], v[232:235], v[8:11]
	v_mfma_f32_16x16x32_bf16 v[60:63], v[132:135], v[210:213], v[60:63]
	v_mfma_f32_16x16x32_bf16 v[56:59], v[140:143], v[210:213], v[56:59]
	v_mfma_f32_16x16x32_bf16 v[48:51], v[132:135], v[218:221], v[48:51]
	v_mfma_f32_16x16x32_bf16 v[40:43], v[140:143], v[218:221], v[40:43]
	v_mfma_f32_16x16x32_bf16 v[32:35], v[132:135], v[228:231], v[32:35]
	v_mfma_f32_16x16x32_bf16 v[24:27], v[140:143], v[228:231], v[24:27]
	v_mfma_f32_16x16x32_bf16 v[16:19], v[132:135], v[236:239], v[16:19]
	v_mfma_f32_16x16x32_bf16 v[8:11], v[140:143], v[236:239], v[8:11]
	v_mfma_f32_16x16x32_bf16 v[52:55], v[144:147], v[190:193], v[52:55]
	v_mfma_f32_16x16x32_bf16 v[44:47], v[182:185], v[190:193], v[44:47]
	v_mfma_f32_16x16x32_bf16 v[36:39], v[144:147], v[214:217], v[36:39]
	v_mfma_f32_16x16x32_bf16 v[28:31], v[182:185], v[214:217], v[28:31]
	v_mfma_f32_16x16x32_bf16 v[20:23], v[144:147], v[224:227], v[20:23]
	v_mfma_f32_16x16x32_bf16 v[12:15], v[182:185], v[224:227], v[12:15]
	v_mfma_f32_16x16x32_bf16 v[4:7], v[144:147], v[232:235], v[4:7]
	v_mfma_f32_16x16x32_bf16 v[0:3], v[182:185], v[232:235], v[0:3]
	v_mfma_f32_16x16x32_bf16 v[52:55], v[148:151], v[210:213], v[52:55]
	v_mfma_f32_16x16x32_bf16 v[44:47], v[186:189], v[210:213], v[44:47]
	v_mfma_f32_16x16x32_bf16 v[36:39], v[148:151], v[218:221], v[36:39]
	v_mfma_f32_16x16x32_bf16 v[28:31], v[186:189], v[218:221], v[28:31]
	v_mfma_f32_16x16x32_bf16 v[20:23], v[148:151], v[228:231], v[20:23]
	v_mfma_f32_16x16x32_bf16 v[12:15], v[186:189], v[228:231], v[12:15]
	v_mfma_f32_16x16x32_bf16 v[4:7], v[148:151], v[236:239], v[4:7]
	v_mfma_f32_16x16x32_bf16 v[0:3], v[186:189], v[236:239], v[0:3]
	s_setprio 0
	s_barrier
	s_add_i32 s83, 0, 0x18000
	s_add_i32 s84, 0, 0x1c000
	v_add_u32_e32 v140, s83, v195
	v_add_u32_e32 v186, s84, v195
	ds_read_b128 v[124:127], v140
	ds_read_b128 v[132:135], v140 offset:1024
	ds_read_b128 v[136:139], v140 offset:2048
	ds_read_b128 v[140:143], v140 offset:3072
	ds_read_b128 v[144:147], v186
	ds_read_b128 v[148:151], v186 offset:1024
	ds_read_b128 v[182:185], v186 offset:2048
	ds_read_b128 v[186:189], v186 offset:3072
	s_add_u32 s62, s62, 0x20000
	s_addc_u32 s63, s63, 0
	s_mov_b32 m0, s67
	v_lshl_add_u64 v[246:247], s[62:63], 0, v[176:177]
	ds_read_b128 v[190:193], v197 offset:32768
	ds_read_b128 v[210:213], v197 offset:33792
	ds_read_b128 v[214:217], v197 offset:34816
	ds_read_b128 v[218:221], v197 offset:35840
	ds_read_b128 v[224:227], v197 offset:36864
	ds_read_b128 v[228:231], v197 offset:37888
	ds_read_b128 v[232:235], v197 offset:38912
	ds_read_b128 v[236:239], v197 offset:39936
	global_load_lds_dwordx4 v[246:247], off
	v_lshl_add_u64 v[246:247], s[62:63], 0, v[174:175]
	s_mov_b32 m0, s68
	s_nop 0
	global_load_lds_dwordx4 v[246:247], off
	s_waitcnt vmcnt(8)
	s_waitcnt lgkmcnt(0)
	s_barrier
	s_setprio 1
	s_waitcnt lgkmcnt(0)
	v_mfma_f32_16x16x32_bf16 v[128:131], v[124:127], v[190:193], v[128:131]
	v_mfma_f32_16x16x32_bf16 v[120:123], v[136:139], v[190:193], v[120:123]
	v_mfma_f32_16x16x32_bf16 v[108:111], v[124:127], v[214:217], v[108:111]
	v_mfma_f32_16x16x32_bf16 v[104:107], v[136:139], v[214:217], v[104:107]
	v_mfma_f32_16x16x32_bf16 v[92:95], v[124:127], v[224:227], v[92:95]
	v_mfma_f32_16x16x32_bf16 v[88:91], v[136:139], v[224:227], v[88:91]
	v_mfma_f32_16x16x32_bf16 v[76:79], v[124:127], v[232:235], v[76:79]
	v_mfma_f32_16x16x32_bf16 v[72:75], v[136:139], v[232:235], v[72:75]
	v_mfma_f32_16x16x32_bf16 v[128:131], v[132:135], v[210:213], v[128:131]
	v_mfma_f32_16x16x32_bf16 v[120:123], v[140:143], v[210:213], v[120:123]
	v_mfma_f32_16x16x32_bf16 v[108:111], v[132:135], v[218:221], v[108:111]
	v_mfma_f32_16x16x32_bf16 v[104:107], v[140:143], v[218:221], v[104:107]
	v_mfma_f32_16x16x32_bf16 v[92:95], v[132:135], v[228:231], v[92:95]
	v_mfma_f32_16x16x32_bf16 v[88:91], v[140:143], v[228:231], v[88:91]
	v_mfma_f32_16x16x32_bf16 v[76:79], v[132:135], v[236:239], v[76:79]
	v_mfma_f32_16x16x32_bf16 v[72:75], v[140:143], v[236:239], v[72:75]
	v_mfma_f32_16x16x32_bf16 v[116:119], v[144:147], v[190:193], v[116:119]
	v_mfma_f32_16x16x32_bf16 v[112:115], v[182:185], v[190:193], v[112:115]
	v_mfma_f32_16x16x32_bf16 v[100:103], v[144:147], v[214:217], v[100:103]
	v_mfma_f32_16x16x32_bf16 v[96:99], v[182:185], v[214:217], v[96:99]
	v_mfma_f32_16x16x32_bf16 v[84:87], v[144:147], v[224:227], v[84:87]
	v_mfma_f32_16x16x32_bf16 v[80:83], v[182:185], v[224:227], v[80:83]
	v_mfma_f32_16x16x32_bf16 v[68:71], v[144:147], v[232:235], v[68:71]
	v_mfma_f32_16x16x32_bf16 v[64:67], v[182:185], v[232:235], v[64:67]
	v_mfma_f32_16x16x32_bf16 v[116:119], v[148:151], v[210:213], v[116:119]
	v_mfma_f32_16x16x32_bf16 v[112:115], v[186:189], v[210:213], v[112:115]
	v_mfma_f32_16x16x32_bf16 v[100:103], v[148:151], v[218:221], v[100:103]
	v_mfma_f32_16x16x32_bf16 v[96:99], v[186:189], v[218:221], v[96:99]
	v_mfma_f32_16x16x32_bf16 v[84:87], v[148:151], v[228:231], v[84:87]
	v_mfma_f32_16x16x32_bf16 v[80:83], v[186:189], v[228:231], v[80:83]
	v_mfma_f32_16x16x32_bf16 v[68:71], v[148:151], v[236:239], v[68:71]
	v_mfma_f32_16x16x32_bf16 v[64:67], v[186:189], v[236:239], v[64:67]
	s_setprio 0
	s_barrier
	s_add_i32 s62, s83, s8
	v_lshl_add_u64 v[198:199], v[198:199], 0, s[22:23]
	s_mov_b32 m0, s62
	ds_read_b128 v[190:193], v197 offset:49152
	ds_read_b128 v[210:213], v197 offset:50176
	ds_read_b128 v[214:217], v197 offset:51200
	ds_read_b128 v[218:221], v197 offset:52224
	ds_read_b128 v[224:227], v197 offset:53248
	ds_read_b128 v[228:231], v197 offset:54272
	ds_read_b128 v[232:235], v197 offset:55296
	ds_read_b128 v[236:239], v197 offset:56320
	global_load_lds_dwordx4 v[198:199], off
	s_add_i32 m0, s62, 0x2000
	s_add_u32 s44, s44, 0x20080
	v_lshl_add_u64 v[198:199], v[240:241], 0, s[22:23]
	s_addc_u32 s45, s45, 0
	s_add_i32 s62, s84, s8
	global_load_lds_dwordx4 v[198:199], off
	v_lshl_add_u64 v[198:199], s[44:45], 0, v[152:153]
	s_mov_b32 m0, s62
	s_nop 0
	global_load_lds_dwordx4 v[198:199], off
	v_lshl_add_u64 v[198:199], s[44:45], 0, v[172:173]
	s_add_i32 m0, s62, 0x2000
	s_nop 0
	global_load_lds_dwordx4 v[198:199], off
	v_lshl_add_u64 v[198:199], v[242:243], 0, s[22:23]
	s_mov_b32 m0, s69
	s_nop 0
	global_load_lds_dwordx4 v[198:199], off
	v_lshl_add_u64 v[198:199], v[244:245], 0, s[22:23]
	s_mov_b32 m0, s74
	s_nop 0
	global_load_lds_dwordx4 v[198:199], off
	s_waitcnt vmcnt(8)
	s_waitcnt lgkmcnt(0)
	s_barrier
	s_setprio 1
	s_waitcnt lgkmcnt(0)
	v_mfma_f32_16x16x32_bf16 v[60:63], v[124:127], v[190:193], v[60:63]
	v_mfma_f32_16x16x32_bf16 v[56:59], v[136:139], v[190:193], v[56:59]
	v_mfma_f32_16x16x32_bf16 v[48:51], v[124:127], v[214:217], v[48:51]
	v_mfma_f32_16x16x32_bf16 v[40:43], v[136:139], v[214:217], v[40:43]
	v_mfma_f32_16x16x32_bf16 v[32:35], v[124:127], v[224:227], v[32:35]
	v_mfma_f32_16x16x32_bf16 v[24:27], v[136:139], v[224:227], v[24:27]
	v_mfma_f32_16x16x32_bf16 v[16:19], v[124:127], v[232:235], v[16:19]
	v_mfma_f32_16x16x32_bf16 v[8:11], v[136:139], v[232:235], v[8:11]
	v_mfma_f32_16x16x32_bf16 v[60:63], v[132:135], v[210:213], v[60:63]
	v_mfma_f32_16x16x32_bf16 v[56:59], v[140:143], v[210:213], v[56:59]
	v_mfma_f32_16x16x32_bf16 v[48:51], v[132:135], v[218:221], v[48:51]
	v_mfma_f32_16x16x32_bf16 v[40:43], v[140:143], v[218:221], v[40:43]
	v_mfma_f32_16x16x32_bf16 v[32:35], v[132:135], v[228:231], v[32:35]
	v_mfma_f32_16x16x32_bf16 v[24:27], v[140:143], v[228:231], v[24:27]
	v_mfma_f32_16x16x32_bf16 v[16:19], v[132:135], v[236:239], v[16:19]
	v_mfma_f32_16x16x32_bf16 v[8:11], v[140:143], v[236:239], v[8:11]
	v_mfma_f32_16x16x32_bf16 v[52:55], v[144:147], v[190:193], v[52:55]
	v_mfma_f32_16x16x32_bf16 v[44:47], v[182:185], v[190:193], v[44:47]
	v_mfma_f32_16x16x32_bf16 v[36:39], v[144:147], v[214:217], v[36:39]
	v_mfma_f32_16x16x32_bf16 v[28:31], v[182:185], v[214:217], v[28:31]
	v_mfma_f32_16x16x32_bf16 v[20:23], v[144:147], v[224:227], v[20:23]
	v_mfma_f32_16x16x32_bf16 v[12:15], v[182:185], v[224:227], v[12:15]
	v_mfma_f32_16x16x32_bf16 v[4:7], v[144:147], v[232:235], v[4:7]
	v_mfma_f32_16x16x32_bf16 v[0:3], v[182:185], v[232:235], v[0:3]
	v_mfma_f32_16x16x32_bf16 v[52:55], v[148:151], v[210:213], v[52:55]
	v_mfma_f32_16x16x32_bf16 v[44:47], v[186:189], v[210:213], v[44:47]
	v_mfma_f32_16x16x32_bf16 v[36:39], v[148:151], v[218:221], v[36:39]
	v_mfma_f32_16x16x32_bf16 v[28:31], v[186:189], v[218:221], v[28:31]
	v_mfma_f32_16x16x32_bf16 v[20:23], v[148:151], v[228:231], v[20:23]
	v_mfma_f32_16x16x32_bf16 v[12:15], v[186:189], v[228:231], v[12:15]
	v_mfma_f32_16x16x32_bf16 v[4:7], v[148:151], v[236:239], v[4:7]
	v_mfma_f32_16x16x32_bf16 v[0:3], v[186:189], v[236:239], v[0:3]
	s_setprio 0
	s_barrier
	s_add_i32 s82, s82, 2
	s_add_u32 s80, s80, 0x100
	s_addc_u32 s81, s81, 0
	s_add_u32 s60, s60, 0x100
	s_addc_u32 s61, s61, 0
	s_cmp_gt_u32 s82, 5
	s_cbranch_scc0 .LBB0_705
	s_and_b64 vcc, exec, s[16:17]
	s_cbranch_vccz .LBB0_708
	s_barrier

.LBB0_724:
	s_ashr_i32 s21, s20, 31
	s_lshl_b64 s[48:49], s[20:21], 18
	v_readlane_b32 s19, v254, 28
	s_add_u32 s48, s19, s48
	v_readlane_b32 s19, v254, 29
	s_addc_u32 s49, s19, s49
	s_and_b64 s[50:51], s[46:47], exec
	s_cselect_b32 s21, s49, s45
	s_cselect_b32 s78, s48, s44
	s_ashr_i32 s19, s18, 31
	s_lshl_b64 s[50:51], s[18:19], 18
	v_readlane_b32 s19, v254, 24
	s_add_u32 s50, s19, s50
	v_readlane_b32 s19, v254, 25
	s_addc_u32 s51, s19, s51
	s_and_b64 s[62:63], s[46:47], exec
	s_cselect_b32 s19, s51, s61
	s_cselect_b32 s79, s50, s60
	s_add_u32 s80, s60, 0x100
	s_addc_u32 s81, s61, 0
	s_add_u32 s60, s44, 0x20080
	s_addc_u32 s61, s45, 0
	s_mov_b32 s82, -2
	s_add_u32 s44, s60, 0xfffe0080
	s_addc_u32 s45, s61, -1
	s_cmp_eq_u32 s82, 4
	s_cselect_b32 s63, s21, s45
	s_cselect_b32 s62, s78, s44
	s_cselect_b32 s45, s19, s81
	s_cselect_b32 s44, s79, s80
	v_lshl_add_u64 v[178:179], s[60:61], 0, v[172:173]
	s_add_i32 m0, s59, 0xc000
	global_load_lds_dwordx4 v[178:179], off
	v_lshl_add_u64 v[178:179], s[60:61], 0, v[150:151]
	s_add_i32 m0, s59, 0xe000
	s_nop 0
	global_load_lds_dwordx4 v[178:179], off
	s_waitcnt vmcnt(8)
	s_waitcnt lgkmcnt(0)
	s_barrier
	s_setprio 1
	s_waitcnt lgkmcnt(0)
	v_mfma_f32_16x16x32_bf16 v[124:127], v[128:131], v[196:199], 0
	v_mfma_f32_16x16x32_bf16 v[120:123], v[136:139], v[196:199], 0
	v_mfma_f32_16x16x32_bf16 v[108:111], v[128:131], v[214:217], 0
	v_mfma_f32_16x16x32_bf16 v[104:107], v[136:139], v[214:217], 0
	v_mfma_f32_16x16x32_bf16 v[92:95], v[128:131], v[224:227], 0
	v_mfma_f32_16x16x32_bf16 v[88:91], v[136:139], v[224:227], 0
	v_mfma_f32_16x16x32_bf16 v[76:79], v[128:131], v[232:235], 0
	v_mfma_f32_16x16x32_bf16 v[72:75], v[136:139], v[232:235], 0
	v_mfma_f32_16x16x32_bf16 v[124:127], v[132:135], v[210:213], v[124:127]
	v_mfma_f32_16x16x32_bf16 v[120:123], v[140:143], v[210:213], v[120:123]
	v_mfma_f32_16x16x32_bf16 v[108:111], v[132:135], v[218:221], v[108:111]
	v_mfma_f32_16x16x32_bf16 v[104:107], v[140:143], v[218:221], v[104:107]
	v_mfma_f32_16x16x32_bf16 v[92:95], v[132:135], v[228:231], v[92:95]
	v_mfma_f32_16x16x32_bf16 v[88:91], v[140:143], v[228:231], v[88:91]
	v_mfma_f32_16x16x32_bf16 v[76:79], v[132:135], v[236:239], v[76:79]
	v_mfma_f32_16x16x32_bf16 v[72:75], v[140:143], v[236:239], v[72:75]
	v_mfma_f32_16x16x32_bf16 v[116:119], v[174:177], v[196:199], 0
	v_mfma_f32_16x16x32_bf16 v[112:115], v[188:191], v[196:199], 0
	v_mfma_f32_16x16x32_bf16 v[100:103], v[174:177], v[214:217], 0
	v_mfma_f32_16x16x32_bf16 v[96:99], v[188:191], v[214:217], 0
	v_mfma_f32_16x16x32_bf16 v[84:87], v[174:177], v[224:227], 0
	v_mfma_f32_16x16x32_bf16 v[80:83], v[188:191], v[224:227], 0
	v_mfma_f32_16x16x32_bf16 v[68:71], v[174:177], v[232:235], 0
	v_mfma_f32_16x16x32_bf16 v[64:67], v[188:191], v[232:235], 0
	v_mfma_f32_16x16x32_bf16 v[116:119], v[184:187], v[210:213], v[116:119]
	v_mfma_f32_16x16x32_bf16 v[112:115], v[192:195], v[210:213], v[112:115]
	v_mfma_f32_16x16x32_bf16 v[100:103], v[184:187], v[218:221], v[100:103]
	v_mfma_f32_16x16x32_bf16 v[96:99], v[192:195], v[218:221], v[96:99]
	v_mfma_f32_16x16x32_bf16 v[84:87], v[184:187], v[228:231], v[84:87]
	v_mfma_f32_16x16x32_bf16 v[80:83], v[192:195], v[228:231], v[80:83]
	v_mfma_f32_16x16x32_bf16 v[68:71], v[184:187], v[236:239], v[68:71]
	v_mfma_f32_16x16x32_bf16 v[64:67], v[192:195], v[236:239], v[64:67]
	s_setprio 0
	s_barrier
	s_add_i32 s83, s83, s8
	v_lshl_add_u64 v[178:179], s[44:45], 0, v[152:153]
	s_mov_b32 m0, s83
	ds_read_b128 v[196:199], v183 offset:16384
	ds_read_b128 v[210:213], v183 offset:17408
	ds_read_b128 v[214:217], v183 offset:18432
	ds_read_b128 v[218:221], v183 offset:19456
	ds_read_b128 v[224:227], v183 offset:20480
	ds_read_b128 v[228:231], v183 offset:21504
	ds_read_b128 v[232:235], v183 offset:22528
	ds_read_b128 v[236:239], v183 offset:23552
	global_load_lds_dwordx4 v[178:179], off
	s_add_i32 m0, s83, 0x2000
	s_add_u32 s84, s44, 0x20000
	v_lshl_add_u64 v[240:241], s[44:45], 0, v[144:145]
	s_addc_u32 s85, s45, 0
	s_add_i32 s83, s86, s8
	global_load_lds_dwordx4 v[240:241], off
	v_lshl_add_u64 v[242:243], s[84:85], 0, v[152:153]
	s_mov_b32 m0, s83
	v_lshl_add_u64 v[244:245], s[62:63], 0, v[146:147]
	global_load_lds_dwordx4 v[242:243], off
	v_lshl_add_u64 v[242:243], s[84:85], 0, v[144:145]
	s_add_i32 m0, s83, 0x2000
	s_nop 0
	global_load_lds_dwordx4 v[242:243], off
	v_lshl_add_u64 v[242:243], s[62:63], 0, v[148:149]
	s_mov_b32 m0, s59
	s_nop 0
	global_load_lds_dwordx4 v[242:243], off
	s_mov_b32 m0, s66
	s_nop 0
	global_load_lds_dwordx4 v[244:245], off
	s_waitcnt vmcnt(8)
	s_waitcnt lgkmcnt(0)
	s_barrier
	s_setprio 1
	s_waitcnt lgkmcnt(0)
	v_mfma_f32_16x16x32_bf16 v[60:63], v[128:131], v[196:199], 0
	v_mfma_f32_16x16x32_bf16 v[56:59], v[136:139], v[196:199], 0
	v_mfma_f32_16x16x32_bf16 v[44:47], v[128:131], v[214:217], 0
	v_mfma_f32_16x16x32_bf16 v[40:43], v[136:139], v[214:217], 0
	v_mfma_f32_16x16x32_bf16 v[28:31], v[128:131], v[224:227], 0
	v_mfma_f32_16x16x32_bf16 v[24:27], v[136:139], v[224:227], 0
	v_mfma_f32_16x16x32_bf16 v[12:15], v[128:131], v[232:235], 0
	v_mfma_f32_16x16x32_bf16 v[8:11], v[136:139], v[232:235], 0
	v_mfma_f32_16x16x32_bf16 v[60:63], v[132:135], v[210:213], v[60:63]
	v_mfma_f32_16x16x32_bf16 v[56:59], v[140:143], v[210:213], v[56:59]
	v_mfma_f32_16x16x32_bf16 v[44:47], v[132:135], v[218:221], v[44:47]
	v_mfma_f32_16x16x32_bf16 v[40:43], v[140:143], v[218:221], v[40:43]
	v_mfma_f32_16x16x32_bf16 v[28:31], v[132:135], v[228:231], v[28:31]
	v_mfma_f32_16x16x32_bf16 v[24:27], v[140:143], v[228:231], v[24:27]
	v_mfma_f32_16x16x32_bf16 v[12:15], v[132:135], v[236:239], v[12:15]
	v_mfma_f32_16x16x32_bf16 v[8:11], v[140:143], v[236:239], v[8:11]
	v_mfma_f32_16x16x32_bf16 v[52:55], v[174:177], v[196:199], 0
	v_mfma_f32_16x16x32_bf16 v[48:51], v[188:191], v[196:199], 0
	v_mfma_f32_16x16x32_bf16 v[36:39], v[174:177], v[214:217], 0
	v_mfma_f32_16x16x32_bf16 v[32:35], v[188:191], v[214:217], 0
	v_mfma_f32_16x16x32_bf16 v[20:23], v[174:177], v[224:227], 0
	v_mfma_f32_16x16x32_bf16 v[16:19], v[188:191], v[224:227], 0
	v_mfma_f32_16x16x32_bf16 v[4:7], v[174:177], v[232:235], 0
	v_mfma_f32_16x16x32_bf16 v[0:3], v[188:191], v[232:235], 0
	v_mfma_f32_16x16x32_bf16 v[52:55], v[184:187], v[210:213], v[52:55]
	v_mfma_f32_16x16x32_bf16 v[48:51], v[192:195], v[210:213], v[48:51]
	v_mfma_f32_16x16x32_bf16 v[36:39], v[184:187], v[218:221], v[36:39]
	v_mfma_f32_16x16x32_bf16 v[32:35], v[192:195], v[218:221], v[32:35]
	v_mfma_f32_16x16x32_bf16 v[20:23], v[184:187], v[228:231], v[20:23]
	v_mfma_f32_16x16x32_bf16 v[16:19], v[192:195], v[228:231], v[16:19]
	v_mfma_f32_16x16x32_bf16 v[4:7], v[184:187], v[236:239], v[4:7]
	v_mfma_f32_16x16x32_bf16 v[0:3], v[192:195], v[236:239], v[0:3]
	s_setprio 0
	s_barrier
	s_add_i32 s83, 0, 0x18000
	s_add_i32 s84, 0, 0x1c000
	v_add_u32_e32 v140, s83, v181
	v_add_u32_e32 v192, s84, v181
	ds_read_b128 v[128:131], v140
	ds_read_b128 v[132:135], v140 offset:1024
	ds_read_b128 v[136:139], v140 offset:2048
	ds_read_b128 v[140:143], v140 offset:3072
	ds_read_b128 v[174:177], v192
	ds_read_b128 v[184:187], v192 offset:1024
	ds_read_b128 v[188:191], v192 offset:2048
	ds_read_b128 v[192:195], v192 offset:3072
	s_add_u32 s62, s62, 0x20000
	s_addc_u32 s63, s63, 0
	s_mov_b32 m0, s67
	v_lshl_add_u64 v[246:247], s[62:63], 0, v[148:149]
	ds_read_b128 v[196:199], v183 offset:32768
	ds_read_b128 v[210:213], v183 offset:33792
	ds_read_b128 v[214:217], v183 offset:34816
	ds_read_b128 v[218:221], v183 offset:35840
	ds_read_b128 v[224:227], v183 offset:36864
	ds_read_b128 v[228:231], v183 offset:37888
	ds_read_b128 v[232:235], v183 offset:38912
	ds_read_b128 v[236:239], v183 offset:39936
	global_load_lds_dwordx4 v[246:247], off
	v_lshl_add_u64 v[246:247], s[62:63], 0, v[146:147]
	s_mov_b32 m0, s68
	s_nop 0
	global_load_lds_dwordx4 v[246:247], off
	s_waitcnt vmcnt(8)
	s_waitcnt lgkmcnt(0)
	s_barrier
	s_setprio 1
	s_waitcnt lgkmcnt(0)
	v_mfma_f32_16x16x32_bf16 v[124:127], v[128:131], v[196:199], v[124:127]
	v_mfma_f32_16x16x32_bf16 v[120:123], v[136:139], v[196:199], v[120:123]
	v_mfma_f32_16x16x32_bf16 v[108:111], v[128:131], v[214:217], v[108:111]
	v_mfma_f32_16x16x32_bf16 v[104:107], v[136:139], v[214:217], v[104:107]
	v_mfma_f32_16x16x32_bf16 v[92:95], v[128:131], v[224:227], v[92:95]
	v_mfma_f32_16x16x32_bf16 v[88:91], v[136:139], v[224:227], v[88:91]
	v_mfma_f32_16x16x32_bf16 v[76:79], v[128:131], v[232:235], v[76:79]
	v_mfma_f32_16x16x32_bf16 v[72:75], v[136:139], v[232:235], v[72:75]
	v_mfma_f32_16x16x32_bf16 v[124:127], v[132:135], v[210:213], v[124:127]
	v_mfma_f32_16x16x32_bf16 v[120:123], v[140:143], v[210:213], v[120:123]
	v_mfma_f32_16x16x32_bf16 v[108:111], v[132:135], v[218:221], v[108:111]
	v_mfma_f32_16x16x32_bf16 v[104:107], v[140:143], v[218:221], v[104:107]
	v_mfma_f32_16x16x32_bf16 v[92:95], v[132:135], v[228:231], v[92:95]
	v_mfma_f32_16x16x32_bf16 v[88:91], v[140:143], v[228:231], v[88:91]
	v_mfma_f32_16x16x32_bf16 v[76:79], v[132:135], v[236:239], v[76:79]
	v_mfma_f32_16x16x32_bf16 v[72:75], v[140:143], v[236:239], v[72:75]
	v_mfma_f32_16x16x32_bf16 v[116:119], v[174:177], v[196:199], v[116:119]
	v_mfma_f32_16x16x32_bf16 v[112:115], v[188:191], v[196:199], v[112:115]
	v_mfma_f32_16x16x32_bf16 v[100:103], v[174:177], v[214:217], v[100:103]
	v_mfma_f32_16x16x32_bf16 v[96:99], v[188:191], v[214:217], v[96:99]
	v_mfma_f32_16x16x32_bf16 v[84:87], v[174:177], v[224:227], v[84:87]
	v_mfma_f32_16x16x32_bf16 v[80:83], v[188:191], v[224:227], v[80:83]
	v_mfma_f32_16x16x32_bf16 v[68:71], v[174:177], v[232:235], v[68:71]
	v_mfma_f32_16x16x32_bf16 v[64:67], v[188:191], v[232:235], v[64:67]
	v_mfma_f32_16x16x32_bf16 v[116:119], v[184:187], v[210:213], v[116:119]
	v_mfma_f32_16x16x32_bf16 v[112:115], v[192:195], v[210:213], v[112:115]
	v_mfma_f32_16x16x32_bf16 v[100:103], v[184:187], v[218:221], v[100:103]
	v_mfma_f32_16x16x32_bf16 v[96:99], v[192:195], v[218:221], v[96:99]
	v_mfma_f32_16x16x32_bf16 v[84:87], v[184:187], v[228:231], v[84:87]
	v_mfma_f32_16x16x32_bf16 v[80:83], v[192:195], v[228:231], v[80:83]
	v_mfma_f32_16x16x32_bf16 v[68:71], v[184:187], v[236:239], v[68:71]
	v_mfma_f32_16x16x32_bf16 v[64:67], v[192:195], v[236:239], v[64:67]
	s_setprio 0
	s_barrier
	s_add_i32 s62, s83, s8
	v_lshl_add_u64 v[178:179], v[178:179], 0, s[22:23]
	s_mov_b32 m0, s62
	ds_read_b128 v[196:199], v183 offset:49152
	ds_read_b128 v[210:213], v183 offset:50176
	ds_read_b128 v[214:217], v183 offset:51200
	ds_read_b128 v[218:221], v183 offset:52224
	ds_read_b128 v[224:227], v183 offset:53248
	ds_read_b128 v[228:231], v183 offset:54272
	ds_read_b128 v[232:235], v183 offset:55296
	ds_read_b128 v[236:239], v183 offset:56320
	global_load_lds_dwordx4 v[178:179], off
	s_add_i32 m0, s62, 0x2000
	s_add_u32 s44, s44, 0x20080
	v_lshl_add_u64 v[178:179], v[240:241], 0, s[22:23]
	s_addc_u32 s45, s45, 0
	s_add_i32 s62, s84, s8
	global_load_lds_dwordx4 v[178:179], off
	v_lshl_add_u64 v[178:179], s[44:45], 0, v[152:153]
	s_mov_b32 m0, s62
	s_nop 0
	global_load_lds_dwordx4 v[178:179], off
	v_lshl_add_u64 v[178:179], s[44:45], 0, v[144:145]
	s_add_i32 m0, s62, 0x2000
	s_nop 0
	global_load_lds_dwordx4 v[178:179], off
	v_lshl_add_u64 v[178:179], v[242:243], 0, s[22:23]
	s_mov_b32 m0, s69
	s_nop 0
	global_load_lds_dwordx4 v[178:179], off
	v_lshl_add_u64 v[178:179], v[244:245], 0, s[22:23]
	s_mov_b32 m0, s74
	s_nop 0
	global_load_lds_dwordx4 v[178:179], off
	s_waitcnt vmcnt(8)
	s_waitcnt lgkmcnt(0)
	s_barrier
	s_setprio 1
	s_waitcnt lgkmcnt(0)
	v_mfma_f32_16x16x32_bf16 v[60:63], v[128:131], v[196:199], v[60:63]
	v_mfma_f32_16x16x32_bf16 v[56:59], v[136:139], v[196:199], v[56:59]
	v_mfma_f32_16x16x32_bf16 v[44:47], v[128:131], v[214:217], v[44:47]
	v_mfma_f32_16x16x32_bf16 v[40:43], v[136:139], v[214:217], v[40:43]
	v_mfma_f32_16x16x32_bf16 v[28:31], v[128:131], v[224:227], v[28:31]
	v_mfma_f32_16x16x32_bf16 v[24:27], v[136:139], v[224:227], v[24:27]
	v_mfma_f32_16x16x32_bf16 v[12:15], v[128:131], v[232:235], v[12:15]
	v_mfma_f32_16x16x32_bf16 v[8:11], v[136:139], v[232:235], v[8:11]
	v_mfma_f32_16x16x32_bf16 v[60:63], v[132:135], v[210:213], v[60:63]
	v_mfma_f32_16x16x32_bf16 v[56:59], v[140:143], v[210:213], v[56:59]
	v_mfma_f32_16x16x32_bf16 v[44:47], v[132:135], v[218:221], v[44:47]
	v_mfma_f32_16x16x32_bf16 v[40:43], v[140:143], v[218:221], v[40:43]
	v_mfma_f32_16x16x32_bf16 v[28:31], v[132:135], v[228:231], v[28:31]
	v_mfma_f32_16x16x32_bf16 v[24:27], v[140:143], v[228:231], v[24:27]
	v_mfma_f32_16x16x32_bf16 v[12:15], v[132:135], v[236:239], v[12:15]
	v_mfma_f32_16x16x32_bf16 v[8:11], v[140:143], v[236:239], v[8:11]
	v_mfma_f32_16x16x32_bf16 v[52:55], v[174:177], v[196:199], v[52:55]
	v_mfma_f32_16x16x32_bf16 v[48:51], v[188:191], v[196:199], v[48:51]
	v_mfma_f32_16x16x32_bf16 v[36:39], v[174:177], v[214:217], v[36:39]
	v_mfma_f32_16x16x32_bf16 v[32:35], v[188:191], v[214:217], v[32:35]
	v_mfma_f32_16x16x32_bf16 v[20:23], v[174:177], v[224:227], v[20:23]
	v_mfma_f32_16x16x32_bf16 v[16:19], v[188:191], v[224:227], v[16:19]
	v_mfma_f32_16x16x32_bf16 v[4:7], v[174:177], v[232:235], v[4:7]
	v_mfma_f32_16x16x32_bf16 v[0:3], v[188:191], v[232:235], v[0:3]
	v_mfma_f32_16x16x32_bf16 v[52:55], v[184:187], v[210:213], v[52:55]
	v_mfma_f32_16x16x32_bf16 v[48:51], v[192:195], v[210:213], v[48:51]
	v_mfma_f32_16x16x32_bf16 v[36:39], v[184:187], v[218:221], v[36:39]
	v_mfma_f32_16x16x32_bf16 v[32:35], v[192:195], v[218:221], v[32:35]
	v_mfma_f32_16x16x32_bf16 v[20:23], v[184:187], v[228:231], v[20:23]
	v_mfma_f32_16x16x32_bf16 v[16:19], v[192:195], v[228:231], v[16:19]
	v_mfma_f32_16x16x32_bf16 v[4:7], v[184:187], v[236:239], v[4:7]
	v_mfma_f32_16x16x32_bf16 v[0:3], v[192:195], v[236:239], v[0:3]
	s_setprio 0
	s_barrier
	s_add_i32 s82, s82, 2
	s_add_u32 s80, s80, 0x100
	s_addc_u32 s81, s81, 0
	s_add_u32 s60, s60, 0x100
	s_addc_u32 s61, s61, 0
	s_cmp_gt_u32 s82, 5
	.p2align	6
.LBB0_725:
	s_add_u32 s44, s60, 0xfffe0080
	s_addc_u32 s45, s61, -1
	s_add_i32 s83, 0, 0x10000
	s_cmp_eq_u32 s82, 4
	s_cselect_b32 s63, s21, s45
	s_cselect_b32 s62, s78, s44
	s_cselect_b32 s45, s19, s81
	s_cselect_b32 s44, s79, s80
	s_add_i32 s86, 0, 0x14000
	v_add_u32_e32 v140, s83, v181
	v_add_u32_e32 v178, s86, v181
	ds_read_b128 v[128:131], v140
	ds_read_b128 v[132:135], v140 offset:1024
	ds_read_b128 v[136:139], v140 offset:2048
	ds_read_b128 v[140:143], v140 offset:3072
	ds_read_b128 v[174:177], v178
	ds_read_b128 v[184:187], v178 offset:1024
	ds_read_b128 v[188:191], v178 offset:2048
	ds_read_b128 v[192:195], v178 offset:3072
	v_lshl_add_u64 v[178:179], s[60:61], 0, v[172:173]
	s_add_i32 m0, s59, 0xc000
	ds_read_b128 v[196:199], v183
	ds_read_b128 v[210:213], v183 offset:1024
	ds_read_b128 v[214:217], v183 offset:2048
	ds_read_b128 v[218:221], v183 offset:3072
	ds_read_b128 v[224:227], v183 offset:4096
	ds_read_b128 v[228:231], v183 offset:5120
	ds_read_b128 v[232:235], v183 offset:6144
	ds_read_b128 v[236:239], v183 offset:7168
	global_load_lds_dwordx4 v[178:179], off
	v_lshl_add_u64 v[178:179], s[60:61], 0, v[150:151]
	s_add_i32 m0, s59, 0xe000
	s_nop 0
	global_load_lds_dwordx4 v[178:179], off
	s_waitcnt vmcnt(8)
	s_waitcnt lgkmcnt(0)
	s_barrier
	s_setprio 1
	s_waitcnt lgkmcnt(0)
	v_mfma_f32_16x16x32_bf16 v[124:127], v[128:131], v[196:199], v[124:127]
	v_mfma_f32_16x16x32_bf16 v[120:123], v[136:139], v[196:199], v[120:123]
	v_mfma_f32_16x16x32_bf16 v[108:111], v[128:131], v[214:217], v[108:111]
	v_mfma_f32_16x16x32_bf16 v[104:107], v[136:139], v[214:217], v[104:107]
	v_mfma_f32_16x16x32_bf16 v[92:95], v[128:131], v[224:227], v[92:95]
	v_mfma_f32_16x16x32_bf16 v[88:91], v[136:139], v[224:227], v[88:91]
	v_mfma_f32_16x16x32_bf16 v[76:79], v[128:131], v[232:235], v[76:79]
	v_mfma_f32_16x16x32_bf16 v[72:75], v[136:139], v[232:235], v[72:75]
	v_mfma_f32_16x16x32_bf16 v[124:127], v[132:135], v[210:213], v[124:127]
	v_mfma_f32_16x16x32_bf16 v[120:123], v[140:143], v[210:213], v[120:123]
	v_mfma_f32_16x16x32_bf16 v[108:111], v[132:135], v[218:221], v[108:111]
	v_mfma_f32_16x16x32_bf16 v[104:107], v[140:143], v[218:221], v[104:107]
	v_mfma_f32_16x16x32_bf16 v[92:95], v[132:135], v[228:231], v[92:95]
	v_mfma_f32_16x16x32_bf16 v[88:91], v[140:143], v[228:231], v[88:91]
	v_mfma_f32_16x16x32_bf16 v[76:79], v[132:135], v[236:239], v[76:79]
	v_mfma_f32_16x16x32_bf16 v[72:75], v[140:143], v[236:239], v[72:75]
	v_mfma_f32_16x16x32_bf16 v[116:119], v[174:177], v[196:199], v[116:119]
	v_mfma_f32_16x16x32_bf16 v[112:115], v[188:191], v[196:199], v[112:115]
	v_mfma_f32_16x16x32_bf16 v[100:103], v[174:177], v[214:217], v[100:103]
	v_mfma_f32_16x16x32_bf16 v[96:99], v[188:191], v[214:217], v[96:99]
	v_mfma_f32_16x16x32_bf16 v[84:87], v[174:177], v[224:227], v[84:87]
	v_mfma_f32_16x16x32_bf16 v[80:83], v[188:191], v[224:227], v[80:83]
	v_mfma_f32_16x16x32_bf16 v[68:71], v[174:177], v[232:235], v[68:71]
	v_mfma_f32_16x16x32_bf16 v[64:67], v[188:191], v[232:235], v[64:67]
	v_mfma_f32_16x16x32_bf16 v[116:119], v[184:187], v[210:213], v[116:119]
	v_mfma_f32_16x16x32_bf16 v[112:115], v[192:195], v[210:213], v[112:115]
	v_mfma_f32_16x16x32_bf16 v[100:103], v[184:187], v[218:221], v[100:103]
	v_mfma_f32_16x16x32_bf16 v[96:99], v[192:195], v[218:221], v[96:99]
	v_mfma_f32_16x16x32_bf16 v[84:87], v[184:187], v[228:231], v[84:87]
	v_mfma_f32_16x16x32_bf16 v[80:83], v[192:195], v[228:231], v[80:83]
	v_mfma_f32_16x16x32_bf16 v[68:71], v[184:187], v[236:239], v[68:71]
	v_mfma_f32_16x16x32_bf16 v[64:67], v[192:195], v[236:239], v[64:67]
	s_setprio 0
	s_barrier
	s_add_i32 s83, s83, s8
	v_lshl_add_u64 v[178:179], s[44:45], 0, v[152:153]
	s_mov_b32 m0, s83
	ds_read_b128 v[196:199], v183 offset:16384
	ds_read_b128 v[210:213], v183 offset:17408
	ds_read_b128 v[214:217], v183 offset:18432
	ds_read_b128 v[218:221], v183 offset:19456
	ds_read_b128 v[224:227], v183 offset:20480
	ds_read_b128 v[228:231], v183 offset:21504
	ds_read_b128 v[232:235], v183 offset:22528
	ds_read_b128 v[236:239], v183 offset:23552
	global_load_lds_dwordx4 v[178:179], off
	s_add_i32 m0, s83, 0x2000
	s_add_u32 s84, s44, 0x20000
	v_lshl_add_u64 v[240:241], s[44:45], 0, v[144:145]
	s_addc_u32 s85, s45, 0
	s_add_i32 s83, s86, s8
	global_load_lds_dwordx4 v[240:241], off
	v_lshl_add_u64 v[242:243], s[84:85], 0, v[152:153]
	s_mov_b32 m0, s83
	v_lshl_add_u64 v[244:245], s[62:63], 0, v[146:147]
	global_load_lds_dwordx4 v[242:243], off
	v_lshl_add_u64 v[242:243], s[84:85], 0, v[144:145]
	s_add_i32 m0, s83, 0x2000
	s_nop 0
	global_load_lds_dwordx4 v[242:243], off
	v_lshl_add_u64 v[242:243], s[62:63], 0, v[148:149]
	s_mov_b32 m0, s59
	s_nop 0
	global_load_lds_dwordx4 v[242:243], off
	s_mov_b32 m0, s66
	s_nop 0
	global_load_lds_dwordx4 v[244:245], off
	s_waitcnt vmcnt(8)
	s_waitcnt lgkmcnt(0)
	s_barrier
	s_setprio 1
	s_waitcnt lgkmcnt(0)
	v_mfma_f32_16x16x32_bf16 v[60:63], v[128:131], v[196:199], v[60:63]
	v_mfma_f32_16x16x32_bf16 v[56:59], v[136:139], v[196:199], v[56:59]
	v_mfma_f32_16x16x32_bf16 v[44:47], v[128:131], v[214:217], v[44:47]
	v_mfma_f32_16x16x32_bf16 v[40:43], v[136:139], v[214:217], v[40:43]
	v_mfma_f32_16x16x32_bf16 v[28:31], v[128:131], v[224:227], v[28:31]
	v_mfma_f32_16x16x32_bf16 v[24:27], v[136:139], v[224:227], v[24:27]
	v_mfma_f32_16x16x32_bf16 v[12:15], v[128:131], v[232:235], v[12:15]
	v_mfma_f32_16x16x32_bf16 v[8:11], v[136:139], v[232:235], v[8:11]
	v_mfma_f32_16x16x32_bf16 v[60:63], v[132:135], v[210:213], v[60:63]
	v_mfma_f32_16x16x32_bf16 v[56:59], v[140:143], v[210:213], v[56:59]
	v_mfma_f32_16x16x32_bf16 v[44:47], v[132:135], v[218:221], v[44:47]
	v_mfma_f32_16x16x32_bf16 v[40:43], v[140:143], v[218:221], v[40:43]
	v_mfma_f32_16x16x32_bf16 v[28:31], v[132:135], v[228:231], v[28:31]
	v_mfma_f32_16x16x32_bf16 v[24:27], v[140:143], v[228:231], v[24:27]
	v_mfma_f32_16x16x32_bf16 v[12:15], v[132:135], v[236:239], v[12:15]
	v_mfma_f32_16x16x32_bf16 v[8:11], v[140:143], v[236:239], v[8:11]
	v_mfma_f32_16x16x32_bf16 v[52:55], v[174:177], v[196:199], v[52:55]
	v_mfma_f32_16x16x32_bf16 v[48:51], v[188:191], v[196:199], v[48:51]
	v_mfma_f32_16x16x32_bf16 v[36:39], v[174:177], v[214:217], v[36:39]
	v_mfma_f32_16x16x32_bf16 v[32:35], v[188:191], v[214:217], v[32:35]
	v_mfma_f32_16x16x32_bf16 v[20:23], v[174:177], v[224:227], v[20:23]
	v_mfma_f32_16x16x32_bf16 v[16:19], v[188:191], v[224:227], v[16:19]
	v_mfma_f32_16x16x32_bf16 v[4:7], v[174:177], v[232:235], v[4:7]
	v_mfma_f32_16x16x32_bf16 v[0:3], v[188:191], v[232:235], v[0:3]
	v_mfma_f32_16x16x32_bf16 v[52:55], v[184:187], v[210:213], v[52:55]
	v_mfma_f32_16x16x32_bf16 v[48:51], v[192:195], v[210:213], v[48:51]
	v_mfma_f32_16x16x32_bf16 v[36:39], v[184:187], v[218:221], v[36:39]
	v_mfma_f32_16x16x32_bf16 v[32:35], v[192:195], v[218:221], v[32:35]
	v_mfma_f32_16x16x32_bf16 v[20:23], v[184:187], v[228:231], v[20:23]
	v_mfma_f32_16x16x32_bf16 v[16:19], v[192:195], v[228:231], v[16:19]
	v_mfma_f32_16x16x32_bf16 v[4:7], v[184:187], v[236:239], v[4:7]
	v_mfma_f32_16x16x32_bf16 v[0:3], v[192:195], v[236:239], v[0:3]
	s_setprio 0
	s_barrier
	s_add_i32 s83, 0, 0x18000
	s_add_i32 s84, 0, 0x1c000
	v_add_u32_e32 v140, s83, v181
	v_add_u32_e32 v192, s84, v181
	ds_read_b128 v[128:131], v140
	ds_read_b128 v[132:135], v140 offset:1024
	ds_read_b128 v[136:139], v140 offset:2048
	ds_read_b128 v[140:143], v140 offset:3072
	ds_read_b128 v[174:177], v192
	ds_read_b128 v[184:187], v192 offset:1024
	ds_read_b128 v[188:191], v192 offset:2048
	ds_read_b128 v[192:195], v192 offset:3072
	s_add_u32 s62, s62, 0x20000
	s_addc_u32 s63, s63, 0
	s_mov_b32 m0, s67
	v_lshl_add_u64 v[246:247], s[62:63], 0, v[148:149]
	ds_read_b128 v[196:199], v183 offset:32768
	ds_read_b128 v[210:213], v183 offset:33792
	ds_read_b128 v[214:217], v183 offset:34816
	ds_read_b128 v[218:221], v183 offset:35840
	ds_read_b128 v[224:227], v183 offset:36864
	ds_read_b128 v[228:231], v183 offset:37888
	ds_read_b128 v[232:235], v183 offset:38912
	ds_read_b128 v[236:239], v183 offset:39936
	global_load_lds_dwordx4 v[246:247], off
	v_lshl_add_u64 v[246:247], s[62:63], 0, v[146:147]
	s_mov_b32 m0, s68
	s_nop 0
	global_load_lds_dwordx4 v[246:247], off
	s_waitcnt vmcnt(8)
	s_waitcnt lgkmcnt(0)
	s_barrier
	s_setprio 1
	s_waitcnt lgkmcnt(0)
	v_mfma_f32_16x16x32_bf16 v[124:127], v[128:131], v[196:199], v[124:127]
	v_mfma_f32_16x16x32_bf16 v[120:123], v[136:139], v[196:199], v[120:123]
	v_mfma_f32_16x16x32_bf16 v[108:111], v[128:131], v[214:217], v[108:111]
	v_mfma_f32_16x16x32_bf16 v[104:107], v[136:139], v[214:217], v[104:107]
	v_mfma_f32_16x16x32_bf16 v[92:95], v[128:131], v[224:227], v[92:95]
	v_mfma_f32_16x16x32_bf16 v[88:91], v[136:139], v[224:227], v[88:91]
	v_mfma_f32_16x16x32_bf16 v[76:79], v[128:131], v[232:235], v[76:79]
	v_mfma_f32_16x16x32_bf16 v[72:75], v[136:139], v[232:235], v[72:75]
	v_mfma_f32_16x16x32_bf16 v[124:127], v[132:135], v[210:213], v[124:127]
	v_mfma_f32_16x16x32_bf16 v[120:123], v[140:143], v[210:213], v[120:123]
	v_mfma_f32_16x16x32_bf16 v[108:111], v[132:135], v[218:221], v[108:111]
	v_mfma_f32_16x16x32_bf16 v[104:107], v[140:143], v[218:221], v[104:107]
	v_mfma_f32_16x16x32_bf16 v[92:95], v[132:135], v[228:231], v[92:95]
	v_mfma_f32_16x16x32_bf16 v[88:91], v[140:143], v[228:231], v[88:91]
	v_mfma_f32_16x16x32_bf16 v[76:79], v[132:135], v[236:239], v[76:79]
	v_mfma_f32_16x16x32_bf16 v[72:75], v[140:143], v[236:239], v[72:75]
	v_mfma_f32_16x16x32_bf16 v[116:119], v[174:177], v[196:199], v[116:119]
	v_mfma_f32_16x16x32_bf16 v[112:115], v[188:191], v[196:199], v[112:115]
	v_mfma_f32_16x16x32_bf16 v[100:103], v[174:177], v[214:217], v[100:103]
	v_mfma_f32_16x16x32_bf16 v[96:99], v[188:191], v[214:217], v[96:99]
	v_mfma_f32_16x16x32_bf16 v[84:87], v[174:177], v[224:227], v[84:87]
	v_mfma_f32_16x16x32_bf16 v[80:83], v[188:191], v[224:227], v[80:83]
	v_mfma_f32_16x16x32_bf16 v[68:71], v[174:177], v[232:235], v[68:71]
	v_mfma_f32_16x16x32_bf16 v[64:67], v[188:191], v[232:235], v[64:67]
	v_mfma_f32_16x16x32_bf16 v[116:119], v[184:187], v[210:213], v[116:119]
	v_mfma_f32_16x16x32_bf16 v[112:115], v[192:195], v[210:213], v[112:115]
	v_mfma_f32_16x16x32_bf16 v[100:103], v[184:187], v[218:221], v[100:103]
	v_mfma_f32_16x16x32_bf16 v[96:99], v[192:195], v[218:221], v[96:99]
	v_mfma_f32_16x16x32_bf16 v[84:87], v[184:187], v[228:231], v[84:87]
	v_mfma_f32_16x16x32_bf16 v[80:83], v[192:195], v[228:231], v[80:83]
	v_mfma_f32_16x16x32_bf16 v[68:71], v[184:187], v[236:239], v[68:71]
	v_mfma_f32_16x16x32_bf16 v[64:67], v[192:195], v[236:239], v[64:67]
	s_setprio 0
	s_barrier
	s_add_i32 s62, s83, s8
	v_lshl_add_u64 v[178:179], v[178:179], 0, s[22:23]
	s_mov_b32 m0, s62
	ds_read_b128 v[196:199], v183 offset:49152
	ds_read_b128 v[210:213], v183 offset:50176
	ds_read_b128 v[214:217], v183 offset:51200
	ds_read_b128 v[218:221], v183 offset:52224
	ds_read_b128 v[224:227], v183 offset:53248
	ds_read_b128 v[228:231], v183 offset:54272
	ds_read_b128 v[232:235], v183 offset:55296
	ds_read_b128 v[236:239], v183 offset:56320
	global_load_lds_dwordx4 v[178:179], off
	s_add_i32 m0, s62, 0x2000
	s_add_u32 s44, s44, 0x20080
	v_lshl_add_u64 v[178:179], v[240:241], 0, s[22:23]
	s_addc_u32 s45, s45, 0
	s_add_i32 s62, s84, s8
	global_load_lds_dwordx4 v[178:179], off
	v_lshl_add_u64 v[178:179], s[44:45], 0, v[152:153]
	s_mov_b32 m0, s62
	s_nop 0
	global_load_lds_dwordx4 v[178:179], off
	v_lshl_add_u64 v[178:179], s[44:45], 0, v[144:145]
	s_add_i32 m0, s62, 0x2000
	s_nop 0
	global_load_lds_dwordx4 v[178:179], off
	v_lshl_add_u64 v[178:179], v[242:243], 0, s[22:23]
	s_mov_b32 m0, s69
	s_nop 0
	global_load_lds_dwordx4 v[178:179], off
	v_lshl_add_u64 v[178:179], v[244:245], 0, s[22:23]
	s_mov_b32 m0, s74
	s_nop 0
	global_load_lds_dwordx4 v[178:179], off
	s_waitcnt vmcnt(8)
	s_waitcnt lgkmcnt(0)
	s_barrier
	s_setprio 1
	s_waitcnt lgkmcnt(0)
	v_mfma_f32_16x16x32_bf16 v[60:63], v[128:131], v[196:199], v[60:63]
	v_mfma_f32_16x16x32_bf16 v[56:59], v[136:139], v[196:199], v[56:59]
	v_mfma_f32_16x16x32_bf16 v[44:47], v[128:131], v[214:217], v[44:47]
	v_mfma_f32_16x16x32_bf16 v[40:43], v[136:139], v[214:217], v[40:43]
	v_mfma_f32_16x16x32_bf16 v[28:31], v[128:131], v[224:227], v[28:31]
	v_mfma_f32_16x16x32_bf16 v[24:27], v[136:139], v[224:227], v[24:27]
	v_mfma_f32_16x16x32_bf16 v[12:15], v[128:131], v[232:235], v[12:15]
	v_mfma_f32_16x16x32_bf16 v[8:11], v[136:139], v[232:235], v[8:11]
	v_mfma_f32_16x16x32_bf16 v[60:63], v[132:135], v[210:213], v[60:63]
	v_mfma_f32_16x16x32_bf16 v[56:59], v[140:143], v[210:213], v[56:59]
	v_mfma_f32_16x16x32_bf16 v[44:47], v[132:135], v[218:221], v[44:47]
	v_mfma_f32_16x16x32_bf16 v[40:43], v[140:143], v[218:221], v[40:43]
	v_mfma_f32_16x16x32_bf16 v[28:31], v[132:135], v[228:231], v[28:31]
	v_mfma_f32_16x16x32_bf16 v[24:27], v[140:143], v[228:231], v[24:27]
	v_mfma_f32_16x16x32_bf16 v[12:15], v[132:135], v[236:239], v[12:15]
	v_mfma_f32_16x16x32_bf16 v[8:11], v[140:143], v[236:239], v[8:11]
	v_mfma_f32_16x16x32_bf16 v[52:55], v[174:177], v[196:199], v[52:55]
	v_mfma_f32_16x16x32_bf16 v[48:51], v[188:191], v[196:199], v[48:51]
	v_mfma_f32_16x16x32_bf16 v[36:39], v[174:177], v[214:217], v[36:39]
	v_mfma_f32_16x16x32_bf16 v[32:35], v[188:191], v[214:217], v[32:35]
	v_mfma_f32_16x16x32_bf16 v[20:23], v[174:177], v[224:227], v[20:23]
	v_mfma_f32_16x16x32_bf16 v[16:19], v[188:191], v[224:227], v[16:19]
	v_mfma_f32_16x16x32_bf16 v[4:7], v[174:177], v[232:235], v[4:7]
	v_mfma_f32_16x16x32_bf16 v[0:3], v[188:191], v[232:235], v[0:3]
	v_mfma_f32_16x16x32_bf16 v[52:55], v[184:187], v[210:213], v[52:55]
	v_mfma_f32_16x16x32_bf16 v[48:51], v[192:195], v[210:213], v[48:51]
	v_mfma_f32_16x16x32_bf16 v[36:39], v[184:187], v[218:221], v[36:39]
	v_mfma_f32_16x16x32_bf16 v[32:35], v[192:195], v[218:221], v[32:35]
	v_mfma_f32_16x16x32_bf16 v[20:23], v[184:187], v[228:231], v[20:23]
	v_mfma_f32_16x16x32_bf16 v[16:19], v[192:195], v[228:231], v[16:19]
	v_mfma_f32_16x16x32_bf16 v[4:7], v[184:187], v[236:239], v[4:7]
	v_mfma_f32_16x16x32_bf16 v[0:3], v[192:195], v[236:239], v[0:3]
	s_setprio 0
	s_barrier
	s_add_i32 s82, s82, 2
	s_add_u32 s80, s80, 0x100
	s_addc_u32 s81, s81, 0
	s_add_u32 s60, s60, 0x100
	s_addc_u32 s61, s61, 0
	s_cmp_gt_u32 s82, 5
	s_cbranch_scc0 .LBB0_725
	s_and_b64 vcc, exec, s[16:17]
	s_cbranch_vccz .LBB0_728
	s_barrier

.LBB0_821:
	s_ashr_i32 s21, s20, 31
	s_lshl_b64 s[48:49], s[20:21], 19
	s_add_u32 s48, s70, s48
	s_addc_u32 s49, s71, s49
	s_and_b64 s[50:51], s[46:47], exec
	s_cselect_b32 s21, s49, s61
	s_cselect_b32 s81, s48, s60
	s_ashr_i32 s19, s18, 31
	s_lshl_b64 s[50:51], s[18:19], 19
	v_readlane_b32 s19, v254, 54
	s_add_u32 s50, s19, s50
	v_readlane_b32 s19, v254, 55
	s_addc_u32 s51, s19, s51
	s_and_b64 s[66:67], s[46:47], exec
	s_cselect_b32 s19, s51, s63
	s_cselect_b32 s82, s50, s62
	s_add_u32 s83, s62, 0x100
	s_addc_u32 s84, s63, 0
	s_add_u32 s60, s60, 0x40080
	s_addc_u32 s61, s61, 0
	s_mov_b32 s85, -2
	s_add_u32 s62, s60, 0xfffc0080
	s_addc_u32 s63, s61, -1
	s_cmp_eq_u32 s85, 12
	s_cselect_b32 s67, s21, s63
	s_cselect_b32 s66, s81, s62
	s_cselect_b32 s63, s19, s84
	s_cselect_b32 s62, s82, s83
	v_lshl_add_u64 v[198:199], s[60:61], 0, v[180:181]
	s_add_i32 m0, s68, 0xc000
	global_load_lds_dwordx4 v[198:199], off
	v_lshl_add_u64 v[198:199], s[60:61], 0, v[178:179]
	s_add_i32 m0, s68, 0xe000
	s_nop 0
	global_load_lds_dwordx4 v[198:199], off
	s_waitcnt vmcnt(8)
	s_waitcnt lgkmcnt(0)
	s_barrier
	s_setprio 1
	s_waitcnt lgkmcnt(0)
	v_mfma_f32_16x16x32_bf16 v[148:151], v[112:115], v[190:193], 0
	v_mfma_f32_16x16x32_bf16 v[144:147], v[120:123], v[190:193], 0
	v_mfma_f32_16x16x32_bf16 v[108:111], v[112:115], v[214:217], 0
	v_mfma_f32_16x16x32_bf16 v[104:107], v[120:123], v[214:217], 0
	v_mfma_f32_16x16x32_bf16 v[92:95], v[112:115], v[224:227], 0
	v_mfma_f32_16x16x32_bf16 v[88:91], v[120:123], v[224:227], 0
	v_mfma_f32_16x16x32_bf16 v[76:79], v[112:115], v[232:235], 0
	v_mfma_f32_16x16x32_bf16 v[72:75], v[120:123], v[232:235], 0
	v_mfma_f32_16x16x32_bf16 v[148:151], v[116:119], v[194:197], v[148:151]
	v_mfma_f32_16x16x32_bf16 v[144:147], v[124:127], v[194:197], v[144:147]
	v_mfma_f32_16x16x32_bf16 v[108:111], v[116:119], v[218:221], v[108:111]
	v_mfma_f32_16x16x32_bf16 v[104:107], v[124:127], v[218:221], v[104:107]
	v_mfma_f32_16x16x32_bf16 v[92:95], v[116:119], v[228:231], v[92:95]
	v_mfma_f32_16x16x32_bf16 v[88:91], v[124:127], v[228:231], v[88:91]
	v_mfma_f32_16x16x32_bf16 v[76:79], v[116:119], v[236:239], v[76:79]
	v_mfma_f32_16x16x32_bf16 v[72:75], v[124:127], v[236:239], v[72:75]
	v_mfma_f32_16x16x32_bf16 v[136:139], v[132:135], v[190:193], 0
	v_mfma_f32_16x16x32_bf16 v[128:131], v[182:185], v[190:193], 0
	v_mfma_f32_16x16x32_bf16 v[100:103], v[132:135], v[214:217], 0
	v_mfma_f32_16x16x32_bf16 v[96:99], v[182:185], v[214:217], 0
	v_mfma_f32_16x16x32_bf16 v[84:87], v[132:135], v[224:227], 0
	v_mfma_f32_16x16x32_bf16 v[80:83], v[182:185], v[224:227], 0
	v_mfma_f32_16x16x32_bf16 v[68:71], v[132:135], v[232:235], 0
	v_mfma_f32_16x16x32_bf16 v[64:67], v[182:185], v[232:235], 0
	v_mfma_f32_16x16x32_bf16 v[136:139], v[140:143], v[194:197], v[136:139]
	v_mfma_f32_16x16x32_bf16 v[128:131], v[186:189], v[194:197], v[128:131]
	v_mfma_f32_16x16x32_bf16 v[100:103], v[140:143], v[218:221], v[100:103]
	v_mfma_f32_16x16x32_bf16 v[96:99], v[186:189], v[218:221], v[96:99]
	v_mfma_f32_16x16x32_bf16 v[84:87], v[140:143], v[228:231], v[84:87]
	v_mfma_f32_16x16x32_bf16 v[80:83], v[186:189], v[228:231], v[80:83]
	v_mfma_f32_16x16x32_bf16 v[68:71], v[140:143], v[236:239], v[68:71]
	v_mfma_f32_16x16x32_bf16 v[64:67], v[186:189], v[236:239], v[64:67]
	s_setprio 0
	s_barrier
	s_add_i32 s86, s86, s59
	v_lshl_add_u64 v[198:199], s[62:63], 0, v[152:153]
	s_mov_b32 m0, s86
	ds_read_b128 v[190:193], v212 offset:16384
	ds_read_b128 v[194:197], v212 offset:17408
	ds_read_b128 v[214:217], v212 offset:18432
	ds_read_b128 v[218:221], v212 offset:19456
	ds_read_b128 v[224:227], v212 offset:20480
	ds_read_b128 v[228:231], v212 offset:21504
	ds_read_b128 v[232:235], v212 offset:22528
	ds_read_b128 v[236:239], v212 offset:23552
	global_load_lds_dwordx4 v[198:199], off
	s_add_i32 m0, s86, 0x2000
	s_add_u32 s86, s62, 0x40000
	v_lshl_add_u64 v[240:241], s[62:63], 0, v[172:173]
	s_addc_u32 s87, s63, 0
	s_add_i32 s89, s89, s59
	global_load_lds_dwordx4 v[240:241], off
	v_lshl_add_u64 v[242:243], s[86:87], 0, v[152:153]
	s_mov_b32 m0, s89
	v_lshl_add_u64 v[244:245], s[66:67], 0, v[174:175]
	global_load_lds_dwordx4 v[242:243], off
	v_lshl_add_u64 v[242:243], s[86:87], 0, v[172:173]
	s_add_i32 m0, s89, 0x2000
	s_nop 0
	global_load_lds_dwordx4 v[242:243], off
	v_lshl_add_u64 v[242:243], s[66:67], 0, v[176:177]
	s_mov_b32 m0, s68
	s_nop 0
	global_load_lds_dwordx4 v[242:243], off
	s_mov_b32 m0, s69
	s_nop 0
	global_load_lds_dwordx4 v[244:245], off
	s_waitcnt vmcnt(8)
	s_waitcnt lgkmcnt(0)
	s_barrier
	s_setprio 1
	s_waitcnt lgkmcnt(0)
	v_mfma_f32_16x16x32_bf16 v[60:63], v[112:115], v[190:193], 0
	v_mfma_f32_16x16x32_bf16 v[56:59], v[120:123], v[190:193], 0
	v_mfma_f32_16x16x32_bf16 v[44:47], v[112:115], v[214:217], 0
	v_mfma_f32_16x16x32_bf16 v[40:43], v[120:123], v[214:217], 0
	v_mfma_f32_16x16x32_bf16 v[28:31], v[112:115], v[224:227], 0
	v_mfma_f32_16x16x32_bf16 v[24:27], v[120:123], v[224:227], 0
	v_mfma_f32_16x16x32_bf16 v[12:15], v[112:115], v[232:235], 0
	v_mfma_f32_16x16x32_bf16 v[8:11], v[120:123], v[232:235], 0
	v_mfma_f32_16x16x32_bf16 v[60:63], v[116:119], v[194:197], v[60:63]
	v_mfma_f32_16x16x32_bf16 v[56:59], v[124:127], v[194:197], v[56:59]
	v_mfma_f32_16x16x32_bf16 v[44:47], v[116:119], v[218:221], v[44:47]
	v_mfma_f32_16x16x32_bf16 v[40:43], v[124:127], v[218:221], v[40:43]
	v_mfma_f32_16x16x32_bf16 v[28:31], v[116:119], v[228:231], v[28:31]
	v_mfma_f32_16x16x32_bf16 v[24:27], v[124:127], v[228:231], v[24:27]
	v_mfma_f32_16x16x32_bf16 v[12:15], v[116:119], v[236:239], v[12:15]
	v_mfma_f32_16x16x32_bf16 v[8:11], v[124:127], v[236:239], v[8:11]
	v_mfma_f32_16x16x32_bf16 v[52:55], v[132:135], v[190:193], 0
	v_mfma_f32_16x16x32_bf16 v[48:51], v[182:185], v[190:193], 0
	v_mfma_f32_16x16x32_bf16 v[36:39], v[132:135], v[214:217], 0
	v_mfma_f32_16x16x32_bf16 v[32:35], v[182:185], v[214:217], 0
	v_mfma_f32_16x16x32_bf16 v[20:23], v[132:135], v[224:227], 0
	v_mfma_f32_16x16x32_bf16 v[16:19], v[182:185], v[224:227], 0
	v_mfma_f32_16x16x32_bf16 v[4:7], v[132:135], v[232:235], 0
	v_mfma_f32_16x16x32_bf16 v[0:3], v[182:185], v[232:235], 0
	v_mfma_f32_16x16x32_bf16 v[52:55], v[140:143], v[194:197], v[52:55]
	v_mfma_f32_16x16x32_bf16 v[48:51], v[186:189], v[194:197], v[48:51]
	v_mfma_f32_16x16x32_bf16 v[36:39], v[140:143], v[218:221], v[36:39]
	v_mfma_f32_16x16x32_bf16 v[32:35], v[186:189], v[218:221], v[32:35]
	v_mfma_f32_16x16x32_bf16 v[20:23], v[140:143], v[228:231], v[20:23]
	v_mfma_f32_16x16x32_bf16 v[16:19], v[186:189], v[228:231], v[16:19]
	v_mfma_f32_16x16x32_bf16 v[4:7], v[140:143], v[236:239], v[4:7]
	v_mfma_f32_16x16x32_bf16 v[0:3], v[186:189], v[236:239], v[0:3]
	s_setprio 0
	s_barrier
	s_add_i32 s86, 0, 0x18000
	s_add_i32 s87, 0, 0x1c000
	v_add_u32_e32 v124, s86, v210
	v_add_u32_e32 v186, s87, v210
	ds_read_b128 v[112:115], v124
	ds_read_b128 v[116:119], v124 offset:1024
	ds_read_b128 v[120:123], v124 offset:2048
	ds_read_b128 v[124:127], v124 offset:3072
	ds_read_b128 v[132:135], v186
	ds_read_b128 v[140:143], v186 offset:1024
	ds_read_b128 v[182:185], v186 offset:2048
	ds_read_b128 v[186:189], v186 offset:3072
	s_add_u32 s66, s66, 0x40000
	s_addc_u32 s67, s67, 0
	s_mov_b32 m0, s74
	v_lshl_add_u64 v[246:247], s[66:67], 0, v[176:177]
	ds_read_b128 v[190:193], v212 offset:32768
	ds_read_b128 v[194:197], v212 offset:33792
	ds_read_b128 v[214:217], v212 offset:34816
	ds_read_b128 v[218:221], v212 offset:35840
	ds_read_b128 v[224:227], v212 offset:36864
	ds_read_b128 v[228:231], v212 offset:37888
	ds_read_b128 v[232:235], v212 offset:38912
	ds_read_b128 v[236:239], v212 offset:39936
	global_load_lds_dwordx4 v[246:247], off
	v_lshl_add_u64 v[246:247], s[66:67], 0, v[174:175]
	s_mov_b32 m0, s75
	s_nop 0
	global_load_lds_dwordx4 v[246:247], off
	s_waitcnt vmcnt(8)
	s_waitcnt lgkmcnt(0)
	s_barrier
	s_setprio 1
	s_waitcnt lgkmcnt(0)
	v_mfma_f32_16x16x32_bf16 v[148:151], v[112:115], v[190:193], v[148:151]
	v_mfma_f32_16x16x32_bf16 v[144:147], v[120:123], v[190:193], v[144:147]
	v_mfma_f32_16x16x32_bf16 v[108:111], v[112:115], v[214:217], v[108:111]
	v_mfma_f32_16x16x32_bf16 v[104:107], v[120:123], v[214:217], v[104:107]
	v_mfma_f32_16x16x32_bf16 v[92:95], v[112:115], v[224:227], v[92:95]
	v_mfma_f32_16x16x32_bf16 v[88:91], v[120:123], v[224:227], v[88:91]
	v_mfma_f32_16x16x32_bf16 v[76:79], v[112:115], v[232:235], v[76:79]
	v_mfma_f32_16x16x32_bf16 v[72:75], v[120:123], v[232:235], v[72:75]
	v_mfma_f32_16x16x32_bf16 v[148:151], v[116:119], v[194:197], v[148:151]
	v_mfma_f32_16x16x32_bf16 v[144:147], v[124:127], v[194:197], v[144:147]
	v_mfma_f32_16x16x32_bf16 v[108:111], v[116:119], v[218:221], v[108:111]
	v_mfma_f32_16x16x32_bf16 v[104:107], v[124:127], v[218:221], v[104:107]
	v_mfma_f32_16x16x32_bf16 v[92:95], v[116:119], v[228:231], v[92:95]
	v_mfma_f32_16x16x32_bf16 v[88:91], v[124:127], v[228:231], v[88:91]
	v_mfma_f32_16x16x32_bf16 v[76:79], v[116:119], v[236:239], v[76:79]
	v_mfma_f32_16x16x32_bf16 v[72:75], v[124:127], v[236:239], v[72:75]
	v_mfma_f32_16x16x32_bf16 v[136:139], v[132:135], v[190:193], v[136:139]
	v_mfma_f32_16x16x32_bf16 v[128:131], v[182:185], v[190:193], v[128:131]
	v_mfma_f32_16x16x32_bf16 v[100:103], v[132:135], v[214:217], v[100:103]
	v_mfma_f32_16x16x32_bf16 v[96:99], v[182:185], v[214:217], v[96:99]
	v_mfma_f32_16x16x32_bf16 v[84:87], v[132:135], v[224:227], v[84:87]
	v_mfma_f32_16x16x32_bf16 v[80:83], v[182:185], v[224:227], v[80:83]
	v_mfma_f32_16x16x32_bf16 v[68:71], v[132:135], v[232:235], v[68:71]
	v_mfma_f32_16x16x32_bf16 v[64:67], v[182:185], v[232:235], v[64:67]
	v_mfma_f32_16x16x32_bf16 v[136:139], v[140:143], v[194:197], v[136:139]
	v_mfma_f32_16x16x32_bf16 v[128:131], v[186:189], v[194:197], v[128:131]
	v_mfma_f32_16x16x32_bf16 v[100:103], v[140:143], v[218:221], v[100:103]
	v_mfma_f32_16x16x32_bf16 v[96:99], v[186:189], v[218:221], v[96:99]
	v_mfma_f32_16x16x32_bf16 v[84:87], v[140:143], v[228:231], v[84:87]
	v_mfma_f32_16x16x32_bf16 v[80:83], v[186:189], v[228:231], v[80:83]
	v_mfma_f32_16x16x32_bf16 v[68:71], v[140:143], v[236:239], v[68:71]
	v_mfma_f32_16x16x32_bf16 v[64:67], v[186:189], v[236:239], v[64:67]
	s_setprio 0
	s_barrier
	s_add_i32 s66, s86, s59
	v_lshl_add_u64 v[198:199], v[198:199], 0, s[22:23]
	s_mov_b32 m0, s66
	ds_read_b128 v[190:193], v212 offset:49152
	ds_read_b128 v[194:197], v212 offset:50176
	ds_read_b128 v[214:217], v212 offset:51200
	ds_read_b128 v[218:221], v212 offset:52224
	ds_read_b128 v[224:227], v212 offset:53248
	ds_read_b128 v[228:231], v212 offset:54272
	ds_read_b128 v[232:235], v212 offset:55296
	ds_read_b128 v[236:239], v212 offset:56320
	global_load_lds_dwordx4 v[198:199], off
	s_add_i32 m0, s66, 0x2000
	s_add_u32 s62, s62, 0x40080
	v_lshl_add_u64 v[198:199], v[240:241], 0, s[22:23]
	s_addc_u32 s63, s63, 0
	s_add_i32 s66, s87, s59
	global_load_lds_dwordx4 v[198:199], off
	v_lshl_add_u64 v[198:199], s[62:63], 0, v[152:153]
	s_mov_b32 m0, s66
	s_nop 0
	global_load_lds_dwordx4 v[198:199], off
	v_lshl_add_u64 v[198:199], s[62:63], 0, v[172:173]
	s_add_i32 m0, s66, 0x2000
	s_nop 0
	global_load_lds_dwordx4 v[198:199], off
	v_lshl_add_u64 v[198:199], v[242:243], 0, s[22:23]
	s_mov_b32 m0, s77
	s_nop 0
	global_load_lds_dwordx4 v[198:199], off
	v_lshl_add_u64 v[198:199], v[244:245], 0, s[22:23]
	s_mov_b32 m0, s78
	s_nop 0
	global_load_lds_dwordx4 v[198:199], off
	s_waitcnt vmcnt(8)
	s_waitcnt lgkmcnt(0)
	s_barrier
	s_setprio 1
	s_waitcnt lgkmcnt(0)
	v_mfma_f32_16x16x32_bf16 v[60:63], v[112:115], v[190:193], v[60:63]
	v_mfma_f32_16x16x32_bf16 v[56:59], v[120:123], v[190:193], v[56:59]
	v_mfma_f32_16x16x32_bf16 v[44:47], v[112:115], v[214:217], v[44:47]
	v_mfma_f32_16x16x32_bf16 v[40:43], v[120:123], v[214:217], v[40:43]
	v_mfma_f32_16x16x32_bf16 v[28:31], v[112:115], v[224:227], v[28:31]
	v_mfma_f32_16x16x32_bf16 v[24:27], v[120:123], v[224:227], v[24:27]
	v_mfma_f32_16x16x32_bf16 v[12:15], v[112:115], v[232:235], v[12:15]
	v_mfma_f32_16x16x32_bf16 v[8:11], v[120:123], v[232:235], v[8:11]
	v_mfma_f32_16x16x32_bf16 v[60:63], v[116:119], v[194:197], v[60:63]
	v_mfma_f32_16x16x32_bf16 v[56:59], v[124:127], v[194:197], v[56:59]
	v_mfma_f32_16x16x32_bf16 v[44:47], v[116:119], v[218:221], v[44:47]
	v_mfma_f32_16x16x32_bf16 v[40:43], v[124:127], v[218:221], v[40:43]
	v_mfma_f32_16x16x32_bf16 v[28:31], v[116:119], v[228:231], v[28:31]
	v_mfma_f32_16x16x32_bf16 v[24:27], v[124:127], v[228:231], v[24:27]
	v_mfma_f32_16x16x32_bf16 v[12:15], v[116:119], v[236:239], v[12:15]
	v_mfma_f32_16x16x32_bf16 v[8:11], v[124:127], v[236:239], v[8:11]
	v_mfma_f32_16x16x32_bf16 v[52:55], v[132:135], v[190:193], v[52:55]
	v_mfma_f32_16x16x32_bf16 v[48:51], v[182:185], v[190:193], v[48:51]
	v_mfma_f32_16x16x32_bf16 v[36:39], v[132:135], v[214:217], v[36:39]
	v_mfma_f32_16x16x32_bf16 v[32:35], v[182:185], v[214:217], v[32:35]
	v_mfma_f32_16x16x32_bf16 v[20:23], v[132:135], v[224:227], v[20:23]
	v_mfma_f32_16x16x32_bf16 v[16:19], v[182:185], v[224:227], v[16:19]
	v_mfma_f32_16x16x32_bf16 v[4:7], v[132:135], v[232:235], v[4:7]
	v_mfma_f32_16x16x32_bf16 v[0:3], v[182:185], v[232:235], v[0:3]
	v_mfma_f32_16x16x32_bf16 v[52:55], v[140:143], v[194:197], v[52:55]
	v_mfma_f32_16x16x32_bf16 v[48:51], v[186:189], v[194:197], v[48:51]
	v_mfma_f32_16x16x32_bf16 v[36:39], v[140:143], v[218:221], v[36:39]
	v_mfma_f32_16x16x32_bf16 v[32:35], v[186:189], v[218:221], v[32:35]
	v_mfma_f32_16x16x32_bf16 v[20:23], v[140:143], v[228:231], v[20:23]
	v_mfma_f32_16x16x32_bf16 v[16:19], v[186:189], v[228:231], v[16:19]
	v_mfma_f32_16x16x32_bf16 v[4:7], v[140:143], v[236:239], v[4:7]
	v_mfma_f32_16x16x32_bf16 v[0:3], v[186:189], v[236:239], v[0:3]
	s_setprio 0
	s_barrier
	s_add_i32 s85, s85, 2
	s_add_u32 s83, s83, 0x100
	s_addc_u32 s84, s84, 0
	s_add_u32 s60, s60, 0x100
	s_addc_u32 s61, s61, 0
	s_cmp_gt_u32 s85, 13
	.p2align	6
.LBB0_822:
	s_add_u32 s62, s60, 0xfffc0080
	s_addc_u32 s63, s61, -1
	s_add_i32 s86, 0, 0x10000
	s_cmp_eq_u32 s85, 12
	s_cselect_b32 s67, s21, s63
	s_cselect_b32 s66, s81, s62
	s_cselect_b32 s63, s19, s84
	s_cselect_b32 s62, s82, s83
	s_add_i32 s89, 0, 0x14000
	v_add_u32_e32 v124, s86, v210
	v_add_u32_e32 v186, s89, v210
	ds_read_b128 v[112:115], v124
	ds_read_b128 v[116:119], v124 offset:1024
	ds_read_b128 v[120:123], v124 offset:2048
	ds_read_b128 v[124:127], v124 offset:3072
	ds_read_b128 v[132:135], v186
	ds_read_b128 v[140:143], v186 offset:1024
	ds_read_b128 v[182:185], v186 offset:2048
	ds_read_b128 v[186:189], v186 offset:3072
	v_lshl_add_u64 v[198:199], s[60:61], 0, v[180:181]
	s_add_i32 m0, s68, 0xc000
	ds_read_b128 v[190:193], v212
	ds_read_b128 v[194:197], v212 offset:1024
	ds_read_b128 v[214:217], v212 offset:2048
	ds_read_b128 v[218:221], v212 offset:3072
	ds_read_b128 v[224:227], v212 offset:4096
	ds_read_b128 v[228:231], v212 offset:5120
	ds_read_b128 v[232:235], v212 offset:6144
	ds_read_b128 v[236:239], v212 offset:7168
	global_load_lds_dwordx4 v[198:199], off
	v_lshl_add_u64 v[198:199], s[60:61], 0, v[178:179]
	s_add_i32 m0, s68, 0xe000
	s_nop 0
	global_load_lds_dwordx4 v[198:199], off
	s_waitcnt vmcnt(8)
	s_waitcnt lgkmcnt(0)
	s_barrier
	s_setprio 1
	s_waitcnt lgkmcnt(0)
	v_mfma_f32_16x16x32_bf16 v[148:151], v[112:115], v[190:193], v[148:151]
	v_mfma_f32_16x16x32_bf16 v[144:147], v[120:123], v[190:193], v[144:147]
	v_mfma_f32_16x16x32_bf16 v[108:111], v[112:115], v[214:217], v[108:111]
	v_mfma_f32_16x16x32_bf16 v[104:107], v[120:123], v[214:217], v[104:107]
	v_mfma_f32_16x16x32_bf16 v[92:95], v[112:115], v[224:227], v[92:95]
	v_mfma_f32_16x16x32_bf16 v[88:91], v[120:123], v[224:227], v[88:91]
	v_mfma_f32_16x16x32_bf16 v[76:79], v[112:115], v[232:235], v[76:79]
	v_mfma_f32_16x16x32_bf16 v[72:75], v[120:123], v[232:235], v[72:75]
	v_mfma_f32_16x16x32_bf16 v[148:151], v[116:119], v[194:197], v[148:151]
	v_mfma_f32_16x16x32_bf16 v[144:147], v[124:127], v[194:197], v[144:147]
	v_mfma_f32_16x16x32_bf16 v[108:111], v[116:119], v[218:221], v[108:111]
	v_mfma_f32_16x16x32_bf16 v[104:107], v[124:127], v[218:221], v[104:107]
	v_mfma_f32_16x16x32_bf16 v[92:95], v[116:119], v[228:231], v[92:95]
	v_mfma_f32_16x16x32_bf16 v[88:91], v[124:127], v[228:231], v[88:91]
	v_mfma_f32_16x16x32_bf16 v[76:79], v[116:119], v[236:239], v[76:79]
	v_mfma_f32_16x16x32_bf16 v[72:75], v[124:127], v[236:239], v[72:75]
	v_mfma_f32_16x16x32_bf16 v[136:139], v[132:135], v[190:193], v[136:139]
	v_mfma_f32_16x16x32_bf16 v[128:131], v[182:185], v[190:193], v[128:131]
	v_mfma_f32_16x16x32_bf16 v[100:103], v[132:135], v[214:217], v[100:103]
	v_mfma_f32_16x16x32_bf16 v[96:99], v[182:185], v[214:217], v[96:99]
	v_mfma_f32_16x16x32_bf16 v[84:87], v[132:135], v[224:227], v[84:87]
	v_mfma_f32_16x16x32_bf16 v[80:83], v[182:185], v[224:227], v[80:83]
	v_mfma_f32_16x16x32_bf16 v[68:71], v[132:135], v[232:235], v[68:71]
	v_mfma_f32_16x16x32_bf16 v[64:67], v[182:185], v[232:235], v[64:67]
	v_mfma_f32_16x16x32_bf16 v[136:139], v[140:143], v[194:197], v[136:139]
	v_mfma_f32_16x16x32_bf16 v[128:131], v[186:189], v[194:197], v[128:131]
	v_mfma_f32_16x16x32_bf16 v[100:103], v[140:143], v[218:221], v[100:103]
	v_mfma_f32_16x16x32_bf16 v[96:99], v[186:189], v[218:221], v[96:99]
	v_mfma_f32_16x16x32_bf16 v[84:87], v[140:143], v[228:231], v[84:87]
	v_mfma_f32_16x16x32_bf16 v[80:83], v[186:189], v[228:231], v[80:83]
	v_mfma_f32_16x16x32_bf16 v[68:71], v[140:143], v[236:239], v[68:71]
	v_mfma_f32_16x16x32_bf16 v[64:67], v[186:189], v[236:239], v[64:67]
	s_setprio 0
	s_barrier
	s_add_i32 s86, s86, s59
	v_lshl_add_u64 v[198:199], s[62:63], 0, v[152:153]
	s_mov_b32 m0, s86
	ds_read_b128 v[190:193], v212 offset:16384
	ds_read_b128 v[194:197], v212 offset:17408
	ds_read_b128 v[214:217], v212 offset:18432
	ds_read_b128 v[218:221], v212 offset:19456
	ds_read_b128 v[224:227], v212 offset:20480
	ds_read_b128 v[228:231], v212 offset:21504
	ds_read_b128 v[232:235], v212 offset:22528
	ds_read_b128 v[236:239], v212 offset:23552
	global_load_lds_dwordx4 v[198:199], off
	s_add_i32 m0, s86, 0x2000
	s_add_u32 s86, s62, 0x40000
	v_lshl_add_u64 v[240:241], s[62:63], 0, v[172:173]
	s_addc_u32 s87, s63, 0
	s_add_i32 s89, s89, s59
	global_load_lds_dwordx4 v[240:241], off
	v_lshl_add_u64 v[242:243], s[86:87], 0, v[152:153]
	s_mov_b32 m0, s89
	v_lshl_add_u64 v[244:245], s[66:67], 0, v[174:175]
	global_load_lds_dwordx4 v[242:243], off
	v_lshl_add_u64 v[242:243], s[86:87], 0, v[172:173]
	s_add_i32 m0, s89, 0x2000
	s_nop 0
	global_load_lds_dwordx4 v[242:243], off
	v_lshl_add_u64 v[242:243], s[66:67], 0, v[176:177]
	s_mov_b32 m0, s68
	s_nop 0
	global_load_lds_dwordx4 v[242:243], off
	s_mov_b32 m0, s69
	s_nop 0
	global_load_lds_dwordx4 v[244:245], off
	s_waitcnt vmcnt(8)
	s_waitcnt lgkmcnt(0)
	s_barrier
	s_setprio 1
	s_waitcnt lgkmcnt(0)
	v_mfma_f32_16x16x32_bf16 v[60:63], v[112:115], v[190:193], v[60:63]
	v_mfma_f32_16x16x32_bf16 v[56:59], v[120:123], v[190:193], v[56:59]
	v_mfma_f32_16x16x32_bf16 v[44:47], v[112:115], v[214:217], v[44:47]
	v_mfma_f32_16x16x32_bf16 v[40:43], v[120:123], v[214:217], v[40:43]
	v_mfma_f32_16x16x32_bf16 v[28:31], v[112:115], v[224:227], v[28:31]
	v_mfma_f32_16x16x32_bf16 v[24:27], v[120:123], v[224:227], v[24:27]
	v_mfma_f32_16x16x32_bf16 v[12:15], v[112:115], v[232:235], v[12:15]
	v_mfma_f32_16x16x32_bf16 v[8:11], v[120:123], v[232:235], v[8:11]
	v_mfma_f32_16x16x32_bf16 v[60:63], v[116:119], v[194:197], v[60:63]
	v_mfma_f32_16x16x32_bf16 v[56:59], v[124:127], v[194:197], v[56:59]
	v_mfma_f32_16x16x32_bf16 v[44:47], v[116:119], v[218:221], v[44:47]
	v_mfma_f32_16x16x32_bf16 v[40:43], v[124:127], v[218:221], v[40:43]
	v_mfma_f32_16x16x32_bf16 v[28:31], v[116:119], v[228:231], v[28:31]
	v_mfma_f32_16x16x32_bf16 v[24:27], v[124:127], v[228:231], v[24:27]
	v_mfma_f32_16x16x32_bf16 v[12:15], v[116:119], v[236:239], v[12:15]
	v_mfma_f32_16x16x32_bf16 v[8:11], v[124:127], v[236:239], v[8:11]
	v_mfma_f32_16x16x32_bf16 v[52:55], v[132:135], v[190:193], v[52:55]
	v_mfma_f32_16x16x32_bf16 v[48:51], v[182:185], v[190:193], v[48:51]
	v_mfma_f32_16x16x32_bf16 v[36:39], v[132:135], v[214:217], v[36:39]
	v_mfma_f32_16x16x32_bf16 v[32:35], v[182:185], v[214:217], v[32:35]
	v_mfma_f32_16x16x32_bf16 v[20:23], v[132:135], v[224:227], v[20:23]
	v_mfma_f32_16x16x32_bf16 v[16:19], v[182:185], v[224:227], v[16:19]
	v_mfma_f32_16x16x32_bf16 v[4:7], v[132:135], v[232:235], v[4:7]
	v_mfma_f32_16x16x32_bf16 v[0:3], v[182:185], v[232:235], v[0:3]
	v_mfma_f32_16x16x32_bf16 v[52:55], v[140:143], v[194:197], v[52:55]
	v_mfma_f32_16x16x32_bf16 v[48:51], v[186:189], v[194:197], v[48:51]
	v_mfma_f32_16x16x32_bf16 v[36:39], v[140:143], v[218:221], v[36:39]
	v_mfma_f32_16x16x32_bf16 v[32:35], v[186:189], v[218:221], v[32:35]
	v_mfma_f32_16x16x32_bf16 v[20:23], v[140:143], v[228:231], v[20:23]
	v_mfma_f32_16x16x32_bf16 v[16:19], v[186:189], v[228:231], v[16:19]
	v_mfma_f32_16x16x32_bf16 v[4:7], v[140:143], v[236:239], v[4:7]
	v_mfma_f32_16x16x32_bf16 v[0:3], v[186:189], v[236:239], v[0:3]
	s_setprio 0
	s_barrier
	s_add_i32 s86, 0, 0x18000
	s_add_i32 s87, 0, 0x1c000
	v_add_u32_e32 v124, s86, v210
	v_add_u32_e32 v186, s87, v210
	ds_read_b128 v[112:115], v124
	ds_read_b128 v[116:119], v124 offset:1024
	ds_read_b128 v[120:123], v124 offset:2048
	ds_read_b128 v[124:127], v124 offset:3072
	ds_read_b128 v[132:135], v186
	ds_read_b128 v[140:143], v186 offset:1024
	ds_read_b128 v[182:185], v186 offset:2048
	ds_read_b128 v[186:189], v186 offset:3072
	s_add_u32 s66, s66, 0x40000
	s_addc_u32 s67, s67, 0
	s_mov_b32 m0, s74
	v_lshl_add_u64 v[246:247], s[66:67], 0, v[176:177]
	ds_read_b128 v[190:193], v212 offset:32768
	ds_read_b128 v[194:197], v212 offset:33792
	ds_read_b128 v[214:217], v212 offset:34816
	ds_read_b128 v[218:221], v212 offset:35840
	ds_read_b128 v[224:227], v212 offset:36864
	ds_read_b128 v[228:231], v212 offset:37888
	ds_read_b128 v[232:235], v212 offset:38912
	ds_read_b128 v[236:239], v212 offset:39936
	global_load_lds_dwordx4 v[246:247], off
	v_lshl_add_u64 v[246:247], s[66:67], 0, v[174:175]
	s_mov_b32 m0, s75
	s_nop 0
	global_load_lds_dwordx4 v[246:247], off
	s_waitcnt vmcnt(8)
	s_waitcnt lgkmcnt(0)
	s_barrier
	s_setprio 1
	s_waitcnt lgkmcnt(0)
	v_mfma_f32_16x16x32_bf16 v[148:151], v[112:115], v[190:193], v[148:151]
	v_mfma_f32_16x16x32_bf16 v[144:147], v[120:123], v[190:193], v[144:147]
	v_mfma_f32_16x16x32_bf16 v[108:111], v[112:115], v[214:217], v[108:111]
	v_mfma_f32_16x16x32_bf16 v[104:107], v[120:123], v[214:217], v[104:107]
	v_mfma_f32_16x16x32_bf16 v[92:95], v[112:115], v[224:227], v[92:95]
	v_mfma_f32_16x16x32_bf16 v[88:91], v[120:123], v[224:227], v[88:91]
	v_mfma_f32_16x16x32_bf16 v[76:79], v[112:115], v[232:235], v[76:79]
	v_mfma_f32_16x16x32_bf16 v[72:75], v[120:123], v[232:235], v[72:75]
	v_mfma_f32_16x16x32_bf16 v[148:151], v[116:119], v[194:197], v[148:151]
	v_mfma_f32_16x16x32_bf16 v[144:147], v[124:127], v[194:197], v[144:147]
	v_mfma_f32_16x16x32_bf16 v[108:111], v[116:119], v[218:221], v[108:111]
	v_mfma_f32_16x16x32_bf16 v[104:107], v[124:127], v[218:221], v[104:107]
	v_mfma_f32_16x16x32_bf16 v[92:95], v[116:119], v[228:231], v[92:95]
	v_mfma_f32_16x16x32_bf16 v[88:91], v[124:127], v[228:231], v[88:91]
	v_mfma_f32_16x16x32_bf16 v[76:79], v[116:119], v[236:239], v[76:79]
	v_mfma_f32_16x16x32_bf16 v[72:75], v[124:127], v[236:239], v[72:75]
	v_mfma_f32_16x16x32_bf16 v[136:139], v[132:135], v[190:193], v[136:139]
	v_mfma_f32_16x16x32_bf16 v[128:131], v[182:185], v[190:193], v[128:131]
	v_mfma_f32_16x16x32_bf16 v[100:103], v[132:135], v[214:217], v[100:103]
	v_mfma_f32_16x16x32_bf16 v[96:99], v[182:185], v[214:217], v[96:99]
	v_mfma_f32_16x16x32_bf16 v[84:87], v[132:135], v[224:227], v[84:87]
	v_mfma_f32_16x16x32_bf16 v[80:83], v[182:185], v[224:227], v[80:83]
	v_mfma_f32_16x16x32_bf16 v[68:71], v[132:135], v[232:235], v[68:71]
	v_mfma_f32_16x16x32_bf16 v[64:67], v[182:185], v[232:235], v[64:67]
	v_mfma_f32_16x16x32_bf16 v[136:139], v[140:143], v[194:197], v[136:139]
	v_mfma_f32_16x16x32_bf16 v[128:131], v[186:189], v[194:197], v[128:131]
	v_mfma_f32_16x16x32_bf16 v[100:103], v[140:143], v[218:221], v[100:103]
	v_mfma_f32_16x16x32_bf16 v[96:99], v[186:189], v[218:221], v[96:99]
	v_mfma_f32_16x16x32_bf16 v[84:87], v[140:143], v[228:231], v[84:87]
	v_mfma_f32_16x16x32_bf16 v[80:83], v[186:189], v[228:231], v[80:83]
	v_mfma_f32_16x16x32_bf16 v[68:71], v[140:143], v[236:239], v[68:71]
	v_mfma_f32_16x16x32_bf16 v[64:67], v[186:189], v[236:239], v[64:67]
	s_setprio 0
	s_barrier
	s_add_i32 s66, s86, s59
	v_lshl_add_u64 v[198:199], v[198:199], 0, s[22:23]
	s_mov_b32 m0, s66
	ds_read_b128 v[190:193], v212 offset:49152
	ds_read_b128 v[194:197], v212 offset:50176
	ds_read_b128 v[214:217], v212 offset:51200
	ds_read_b128 v[218:221], v212 offset:52224
	ds_read_b128 v[224:227], v212 offset:53248
	ds_read_b128 v[228:231], v212 offset:54272
	ds_read_b128 v[232:235], v212 offset:55296
	ds_read_b128 v[236:239], v212 offset:56320
	global_load_lds_dwordx4 v[198:199], off
	s_add_i32 m0, s66, 0x2000
	s_add_u32 s62, s62, 0x40080
	v_lshl_add_u64 v[198:199], v[240:241], 0, s[22:23]
	s_addc_u32 s63, s63, 0
	s_add_i32 s66, s87, s59
	global_load_lds_dwordx4 v[198:199], off
	v_lshl_add_u64 v[198:199], s[62:63], 0, v[152:153]
	s_mov_b32 m0, s66
	s_nop 0
	global_load_lds_dwordx4 v[198:199], off
	v_lshl_add_u64 v[198:199], s[62:63], 0, v[172:173]
	s_add_i32 m0, s66, 0x2000
	s_nop 0
	global_load_lds_dwordx4 v[198:199], off
	v_lshl_add_u64 v[198:199], v[242:243], 0, s[22:23]
	s_mov_b32 m0, s77
	s_nop 0
	global_load_lds_dwordx4 v[198:199], off
	v_lshl_add_u64 v[198:199], v[244:245], 0, s[22:23]
	s_mov_b32 m0, s78
	s_nop 0
	global_load_lds_dwordx4 v[198:199], off
	s_waitcnt vmcnt(8)
	s_waitcnt lgkmcnt(0)
	s_barrier
	s_setprio 1
	s_waitcnt lgkmcnt(0)
	v_mfma_f32_16x16x32_bf16 v[60:63], v[112:115], v[190:193], v[60:63]
	v_mfma_f32_16x16x32_bf16 v[56:59], v[120:123], v[190:193], v[56:59]
	v_mfma_f32_16x16x32_bf16 v[44:47], v[112:115], v[214:217], v[44:47]
	v_mfma_f32_16x16x32_bf16 v[40:43], v[120:123], v[214:217], v[40:43]
	v_mfma_f32_16x16x32_bf16 v[28:31], v[112:115], v[224:227], v[28:31]
	v_mfma_f32_16x16x32_bf16 v[24:27], v[120:123], v[224:227], v[24:27]
	v_mfma_f32_16x16x32_bf16 v[12:15], v[112:115], v[232:235], v[12:15]
	v_mfma_f32_16x16x32_bf16 v[8:11], v[120:123], v[232:235], v[8:11]
	v_mfma_f32_16x16x32_bf16 v[60:63], v[116:119], v[194:197], v[60:63]
	v_mfma_f32_16x16x32_bf16 v[56:59], v[124:127], v[194:197], v[56:59]
	v_mfma_f32_16x16x32_bf16 v[44:47], v[116:119], v[218:221], v[44:47]
	v_mfma_f32_16x16x32_bf16 v[40:43], v[124:127], v[218:221], v[40:43]
	v_mfma_f32_16x16x32_bf16 v[28:31], v[116:119], v[228:231], v[28:31]
	v_mfma_f32_16x16x32_bf16 v[24:27], v[124:127], v[228:231], v[24:27]
	v_mfma_f32_16x16x32_bf16 v[12:15], v[116:119], v[236:239], v[12:15]
	v_mfma_f32_16x16x32_bf16 v[8:11], v[124:127], v[236:239], v[8:11]
	v_mfma_f32_16x16x32_bf16 v[52:55], v[132:135], v[190:193], v[52:55]
	v_mfma_f32_16x16x32_bf16 v[48:51], v[182:185], v[190:193], v[48:51]
	v_mfma_f32_16x16x32_bf16 v[36:39], v[132:135], v[214:217], v[36:39]
	v_mfma_f32_16x16x32_bf16 v[32:35], v[182:185], v[214:217], v[32:35]
	v_mfma_f32_16x16x32_bf16 v[20:23], v[132:135], v[224:227], v[20:23]
	v_mfma_f32_16x16x32_bf16 v[16:19], v[182:185], v[224:227], v[16:19]
	v_mfma_f32_16x16x32_bf16 v[4:7], v[132:135], v[232:235], v[4:7]
	v_mfma_f32_16x16x32_bf16 v[0:3], v[182:185], v[232:235], v[0:3]
	v_mfma_f32_16x16x32_bf16 v[52:55], v[140:143], v[194:197], v[52:55]
	v_mfma_f32_16x16x32_bf16 v[48:51], v[186:189], v[194:197], v[48:51]
	v_mfma_f32_16x16x32_bf16 v[36:39], v[140:143], v[218:221], v[36:39]
	v_mfma_f32_16x16x32_bf16 v[32:35], v[186:189], v[218:221], v[32:35]
	v_mfma_f32_16x16x32_bf16 v[20:23], v[140:143], v[228:231], v[20:23]
	v_mfma_f32_16x16x32_bf16 v[16:19], v[186:189], v[228:231], v[16:19]
	v_mfma_f32_16x16x32_bf16 v[4:7], v[140:143], v[236:239], v[4:7]
	v_mfma_f32_16x16x32_bf16 v[0:3], v[186:189], v[236:239], v[0:3]
	s_setprio 0
	s_barrier
	s_add_i32 s85, s85, 2
	s_add_u32 s83, s83, 0x100
	s_addc_u32 s84, s84, 0
	s_add_u32 s60, s60, 0x100
	s_addc_u32 s61, s61, 0
	s_cmp_gt_u32 s85, 13
	s_cbranch_scc0 .LBB0_822
	s_and_b64 vcc, exec, s[16:17]
	s_cbranch_vccz .LBB0_825
	s_barrier
